# GEMM loops: within each 16-MFMA block, the two k-steps of each accumulator issued back to back (same instructions, reordered); on top of the MLA loop edits
# baseline (speedup 1.0000x reference)
; #define PG8_STAGE(bufoff, gbase, voff) do { _Pragma("unroll") for (int _i = 0; _i < 2; ++_i) \
;         __builtin_amdgcn_global_load_lds((const unsigned*)((const char*)(gbase) + (voff)[_i]), (PG8_LAS unsigned*)(lds + (bufoff) + ldsw + _i * 8192), 16, 0, 0); } while (0)
; #define PG8_LDA(dst, b, h) do { _Pragma("unroll") for (int m = 0; m < 4; ++m) _Pragma("unroll") for (int k = 0; k < 2; ++k) dst[m][k] = *(const PG8_LAS bf16x8*)(lds + PG8_SA(b, h) + aoff + m * 2048 + k * 1024); } while (0)
; #define PG8_LDB(dst, b, h) do { _Pragma("unroll") for (int n = 0; n < 2; ++n) _Pragma("unroll") for (int k = 0; k < 2; ++k) dst[n][k] = *(const PG8_LAS bf16x8*)(lds + PG8_SB(b, h) + boff + n * 2048 + k * 1024); } while (0)
; #define PG8_MMA(ai, bj, At, Bt) do { __builtin_amdgcn_s_setprio(1); _Pragma("unroll") for (int m = 0; m < 4; ++m) _Pragma("unroll") for (int n = 0; n < 2; ++n) _Pragma("unroll") for (int k = 0; k < 2; ++k) \
;         acc[ai][bj][m][n] = __builtin_amdgcn_mfma_f32_16x16x32_bf16(Bt[n][k], At[m][k], acc[ai][bj][m][n], 0, 0, 0); __builtin_amdgcn_s_setprio(0); } while (0)
; #define PG8_WAIT_V(n) asm volatile("s_waitcnt vmcnt(" #n ")" ::: "memory")
; #define PG8_WAIT_L(n) asm volatile("s_waitcnt lgkmcnt(" #n ")" ::: "memory")
; #define PG8_BAR __builtin_amdgcn_s_barrier()
; template <class Epi, class Sched, bool ALIGN_EPI = false, bool SP2 = false>
; __device__ __forceinline__ void gemm_phase(PG8_LAS unsigned char* lds, const Gemm g, const Sched& S, const Epi& E, const int tid) {
;     ...
;             const char* a1 = cA + (size_t)(t + 1) * kstep;
;             const char* a2 = last ? nA : cA + (size_t)(t + 2) * kstep; const char* b2 = last ? nB : cB + (size_t)(t + 2) * kstep;
;             const char* a3 = a2 + kstep; const char* b3 = b2 + kstep;
;             if (last && has_next) S.a_ready(nxt);
;             if constexpr (SP2) {
;             PG8_LDB(B0, 0, 0); PG8_LDB(B1, 0, 1); PG8_SCHED; PG8_LDA(At, 0, 0); PG8_STAGE(PG8_SA(1, 1), a1 + hstep, voffA);
;             PG8_WAIT_V(8); PG8_WAIT_L(0); PG8_BAR; PG8_MMA(0, 0, At, B0); PG8_MMA(0, 1, At, B1); PG8_BAR; PG8_SCHED;
;             PG8_LDA(At, 0, 1); PG8_STAGE(PG8_SB(0, 0), b2, voffB); PG8_STAGE(PG8_SB(0, 1), b2 + hstep, voffB); PG8_STAGE(PG8_SA(0, 0), a2, voffA);
;             PG8_WAIT_V(8); PG8_WAIT_L(0); PG8_BAR; PG8_MMA(1, 0, At, B0); PG8_MMA(1, 1, At, B1); PG8_BAR; PG8_SCHED;
.LBB0_95:
	ds_read_b128 v[144:147], v152
	ds_read_b128 v[156:159], v152 offset:1024
	ds_read_b128 v[160:163], v152 offset:2048
	ds_read_b128 v[164:167], v152 offset:3072
	ds_read_b128 v[168:171], v153
	ds_read_b128 v[172:175], v153 offset:1024
	ds_read_b128 v[176:179], v153 offset:2048
	ds_read_b128 v[180:183], v153 offset:3072
	s_add_u32 s0, s34, 0xfff80080
	s_addc_u32 s1, s35, -1
	s_cmp_eq_u32 s56, 28
	s_cselect_b32 s3, s4, s1
	s_cselect_b32 s2, s5, s0
	s_cselect_b32 s1, s23, s55
	s_cselect_b32 s0, s25, s54
	v_lshl_add_u64 v[216:217], s[34:35], 0, v[136:137]
	s_add_i32 m0, s31, 0xc000
	ds_read_b128 v[184:187], v154
	ds_read_b128 v[188:191], v154 offset:1024
	ds_read_b128 v[192:195], v154 offset:2048
	ds_read_b128 v[196:199], v154 offset:3072
	ds_read_b128 v[200:203], v154 offset:4096
	ds_read_b128 v[204:207], v154 offset:5120
	ds_read_b128 v[208:211], v154 offset:6144
	ds_read_b128 v[212:215], v154 offset:7168
	global_load_lds_dwordx4 v[216:217], off
	v_lshl_add_u64 v[216:217], s[34:35], 0, v[138:139]
	s_add_i32 m0, s31, 0xe000
	s_nop 0
	global_load_lds_dwordx4 v[216:217], off
	s_waitcnt vmcnt(8)
	s_waitcnt lgkmcnt(0)
	s_barrier
	s_setprio 1
	s_waitcnt lgkmcnt(0)
	v_mfma_f32_16x16x32_bf16 v[124:127], v[144:147], v[184:187], v[124:127]
	v_mfma_f32_16x16x32_bf16 v[124:127], v[156:159], v[188:191], v[124:127]
	v_mfma_f32_16x16x32_bf16 v[120:123], v[160:163], v[184:187], v[120:123]
	v_mfma_f32_16x16x32_bf16 v[120:123], v[164:167], v[188:191], v[120:123]
	v_mfma_f32_16x16x32_bf16 v[116:119], v[144:147], v[192:195], v[116:119]
	v_mfma_f32_16x16x32_bf16 v[116:119], v[156:159], v[196:199], v[116:119]
	v_mfma_f32_16x16x32_bf16 v[108:111], v[160:163], v[192:195], v[108:111]
	v_mfma_f32_16x16x32_bf16 v[108:111], v[164:167], v[196:199], v[108:111]
	v_mfma_f32_16x16x32_bf16 v[100:103], v[144:147], v[200:203], v[100:103]
	v_mfma_f32_16x16x32_bf16 v[100:103], v[156:159], v[204:207], v[100:103]
	v_mfma_f32_16x16x32_bf16 v[92:95], v[160:163], v[200:203], v[92:95]
	v_mfma_f32_16x16x32_bf16 v[92:95], v[164:167], v[204:207], v[92:95]
	v_mfma_f32_16x16x32_bf16 v[84:87], v[144:147], v[208:211], v[84:87]
	v_mfma_f32_16x16x32_bf16 v[84:87], v[156:159], v[212:215], v[84:87]
	v_mfma_f32_16x16x32_bf16 v[76:79], v[160:163], v[208:211], v[76:79]
	v_mfma_f32_16x16x32_bf16 v[76:79], v[164:167], v[212:215], v[76:79]
	s_setprio 0
	s_setprio 1
	v_mfma_f32_16x16x32_bf16 v[112:115], v[168:171], v[184:187], v[112:115]
	v_mfma_f32_16x16x32_bf16 v[112:115], v[172:175], v[188:191], v[112:115]
	v_mfma_f32_16x16x32_bf16 v[104:107], v[176:179], v[184:187], v[104:107]
	v_mfma_f32_16x16x32_bf16 v[104:107], v[180:183], v[188:191], v[104:107]
	v_mfma_f32_16x16x32_bf16 v[96:99], v[168:171], v[192:195], v[96:99]
	v_mfma_f32_16x16x32_bf16 v[96:99], v[172:175], v[196:199], v[96:99]
	v_mfma_f32_16x16x32_bf16 v[88:91], v[176:179], v[192:195], v[88:91]
	v_mfma_f32_16x16x32_bf16 v[88:91], v[180:183], v[196:199], v[88:91]
	v_mfma_f32_16x16x32_bf16 v[80:83], v[168:171], v[200:203], v[80:83]
	v_mfma_f32_16x16x32_bf16 v[80:83], v[172:175], v[204:207], v[80:83]
	v_mfma_f32_16x16x32_bf16 v[72:75], v[176:179], v[200:203], v[72:75]
	v_mfma_f32_16x16x32_bf16 v[72:75], v[180:183], v[204:207], v[72:75]
	v_mfma_f32_16x16x32_bf16 v[68:71], v[168:171], v[208:211], v[68:71]
	v_mfma_f32_16x16x32_bf16 v[68:71], v[172:175], v[212:215], v[68:71]
	v_mfma_f32_16x16x32_bf16 v[64:67], v[176:179], v[208:211], v[64:67]
	v_mfma_f32_16x16x32_bf16 v[64:67], v[180:183], v[212:215], v[64:67]
	s_setprio 0
	s_barrier
	s_add_i32 s57, s50, s37
	v_lshl_add_u64 v[216:217], s[0:1], 0, v[130:131]
	s_mov_b32 m0, s57
	ds_read_b128 v[184:187], v154 offset:16384
	ds_read_b128 v[188:191], v154 offset:17408
	ds_read_b128 v[192:195], v154 offset:18432
	ds_read_b128 v[196:199], v154 offset:19456
	ds_read_b128 v[200:203], v154 offset:20480
	ds_read_b128 v[204:207], v154 offset:21504
	ds_read_b128 v[208:211], v154 offset:22528
	ds_read_b128 v[212:215], v154 offset:23552
	global_load_lds_dwordx4 v[216:217], off
	s_add_i32 m0, s57, 0x2000
	s_add_u32 s58, s0, 0x80000
	v_lshl_add_u64 v[218:219], s[0:1], 0, v[134:135]
	s_addc_u32 s59, s1, 0
	s_add_i32 s57, s51, s37
	global_load_lds_dwordx4 v[218:219], off
	v_lshl_add_u64 v[220:221], s[58:59], 0, v[130:131]
	s_mov_b32 m0, s57
	v_lshl_add_u64 v[222:223], s[2:3], 0, v[132:133]
	global_load_lds_dwordx4 v[220:221], off
	v_lshl_add_u64 v[220:221], s[58:59], 0, v[134:135]
	s_add_i32 m0, s57, 0x2000
	s_nop 0
	global_load_lds_dwordx4 v[220:221], off
	v_lshl_add_u64 v[220:221], s[2:3], 0, v[128:129]
	s_mov_b32 m0, s31
	s_nop 0
	global_load_lds_dwordx4 v[220:221], off
	s_mov_b32 m0, s38
	s_nop 0
	global_load_lds_dwordx4 v[222:223], off
	s_waitcnt vmcnt(8)
	s_waitcnt lgkmcnt(0)
	s_barrier
; #define PG8_STAGE(bufoff, gbase, voff) do { _Pragma("unroll") for (int _i = 0; _i < 2; ++_i) \
;         __builtin_amdgcn_global_load_lds((const unsigned*)((const char*)(gbase) + (voff)[_i]), (PG8_LAS unsigned*)(lds + (bufoff) + ldsw + _i * 8192), 16, 0, 0); } while (0)
; #define PG8_LDA(dst, b, h) do { _Pragma("unroll") for (int m = 0; m < 4; ++m) _Pragma("unroll") for (int k = 0; k < 2; ++k) dst[m][k] = *(const PG8_LAS bf16x8*)(lds + PG8_SA(b, h) + aoff + m * 2048 + k * 1024); } while (0)
; #define PG8_LDB(dst, b, h) do { _Pragma("unroll") for (int n = 0; n < 2; ++n) _Pragma("unroll") for (int k = 0; k < 2; ++k) dst[n][k] = *(const PG8_LAS bf16x8*)(lds + PG8_SB(b, h) + boff + n * 2048 + k * 1024); } while (0)
; #define PG8_MMA(ai, bj, At, Bt) do { __builtin_amdgcn_s_setprio(1); _Pragma("unroll") for (int m = 0; m < 4; ++m) _Pragma("unroll") for (int n = 0; n < 2; ++n) _Pragma("unroll") for (int k = 0; k < 2; ++k) \
;         acc[ai][bj][m][n] = __builtin_amdgcn_mfma_f32_16x16x32_bf16(Bt[n][k], At[m][k], acc[ai][bj][m][n], 0, 0, 0); __builtin_amdgcn_s_setprio(0); } while (0)
; #define PG8_WAIT_V(n) asm volatile("s_waitcnt vmcnt(" #n ")" ::: "memory")
; #define PG8_WAIT_L(n) asm volatile("s_waitcnt lgkmcnt(" #n ")" ::: "memory")
; #define PG8_BAR __builtin_amdgcn_s_barrier()
; #define PG8_SCHED __builtin_amdgcn_sched_barrier(0)
; template <class Epi, class Sched, bool ALIGN_EPI = false, bool SP2 = false>
; __device__ __forceinline__ void gemm_phase(PG8_LAS unsigned char* lds, const Gemm g, const Sched& S, const Epi& E, const int tid) {
;     ...
;             PG8_WAIT_V(8); PG8_WAIT_L(0); PG8_BAR; PG8_MMA(1, 0, At, B0); PG8_MMA(1, 1, At, B1); PG8_BAR; PG8_SCHED;
;             PG8_LDB(B0, 1, 0); PG8_LDB(B1, 1, 1); PG8_SCHED; PG8_LDA(At, 1, 0); PG8_STAGE(PG8_SA(0, 1), a2 + hstep, voffA);
;             PG8_WAIT_V(8); PG8_WAIT_L(0); PG8_BAR; PG8_MMA(0, 0, At, B0); PG8_MMA(0, 1, At, B1); PG8_BAR; PG8_SCHED;
	s_setprio 1
	s_waitcnt lgkmcnt(0)
	v_mfma_f32_16x16x32_bf16 v[60:63], v[144:147], v[184:187], v[60:63]
	v_mfma_f32_16x16x32_bf16 v[60:63], v[156:159], v[188:191], v[60:63]
	v_mfma_f32_16x16x32_bf16 v[56:59], v[160:163], v[184:187], v[56:59]
	v_mfma_f32_16x16x32_bf16 v[56:59], v[164:167], v[188:191], v[56:59]
	v_mfma_f32_16x16x32_bf16 v[52:55], v[144:147], v[192:195], v[52:55]
	v_mfma_f32_16x16x32_bf16 v[52:55], v[156:159], v[196:199], v[52:55]
	v_mfma_f32_16x16x32_bf16 v[44:47], v[160:163], v[192:195], v[44:47]
	v_mfma_f32_16x16x32_bf16 v[44:47], v[164:167], v[196:199], v[44:47]
	v_mfma_f32_16x16x32_bf16 v[36:39], v[144:147], v[200:203], v[36:39]
	v_mfma_f32_16x16x32_bf16 v[36:39], v[156:159], v[204:207], v[36:39]
	v_mfma_f32_16x16x32_bf16 v[28:31], v[160:163], v[200:203], v[28:31]
	v_mfma_f32_16x16x32_bf16 v[28:31], v[164:167], v[204:207], v[28:31]
	v_mfma_f32_16x16x32_bf16 v[20:23], v[144:147], v[208:211], v[20:23]
	v_mfma_f32_16x16x32_bf16 v[20:23], v[156:159], v[212:215], v[20:23]
	v_mfma_f32_16x16x32_bf16 v[12:15], v[160:163], v[208:211], v[12:15]
	v_mfma_f32_16x16x32_bf16 v[12:15], v[164:167], v[212:215], v[12:15]
	s_setprio 0
	s_setprio 1
	v_mfma_f32_16x16x32_bf16 v[48:51], v[168:171], v[184:187], v[48:51]
	v_mfma_f32_16x16x32_bf16 v[48:51], v[172:175], v[188:191], v[48:51]
	v_mfma_f32_16x16x32_bf16 v[40:43], v[176:179], v[184:187], v[40:43]
	v_mfma_f32_16x16x32_bf16 v[40:43], v[180:183], v[188:191], v[40:43]
	v_mfma_f32_16x16x32_bf16 v[32:35], v[168:171], v[192:195], v[32:35]
	v_mfma_f32_16x16x32_bf16 v[32:35], v[172:175], v[196:199], v[32:35]
	v_mfma_f32_16x16x32_bf16 v[24:27], v[176:179], v[192:195], v[24:27]
	v_mfma_f32_16x16x32_bf16 v[24:27], v[180:183], v[196:199], v[24:27]
	v_mfma_f32_16x16x32_bf16 v[16:19], v[168:171], v[200:203], v[16:19]
	v_mfma_f32_16x16x32_bf16 v[16:19], v[172:175], v[204:207], v[16:19]
	v_mfma_f32_16x16x32_bf16 v[8:11], v[176:179], v[200:203], v[8:11]
	v_mfma_f32_16x16x32_bf16 v[8:11], v[180:183], v[204:207], v[8:11]
	v_mfma_f32_16x16x32_bf16 v[4:7], v[168:171], v[208:211], v[4:7]
	v_mfma_f32_16x16x32_bf16 v[4:7], v[172:175], v[212:215], v[4:7]
	v_mfma_f32_16x16x32_bf16 v[0:3], v[176:179], v[208:211], v[0:3]
	v_mfma_f32_16x16x32_bf16 v[0:3], v[180:183], v[212:215], v[0:3]
	s_setprio 0
	s_barrier
	s_add_i32 s57, 0, 0x18000
	v_add_u32_e32 v155, s57, v150
	s_add_i32 s58, 0, 0x1c000
	ds_read_b128 v[144:147], v155
	ds_read_b128 v[156:159], v155 offset:1024
	ds_read_b128 v[160:163], v155 offset:2048
	ds_read_b128 v[164:167], v155 offset:3072
	v_add_u32_e32 v155, s58, v150
	ds_read_b128 v[168:171], v155
	ds_read_b128 v[172:175], v155 offset:1024
	ds_read_b128 v[176:179], v155 offset:2048
	ds_read_b128 v[180:183], v155 offset:3072
	s_add_u32 s2, s2, 0x80000
	s_addc_u32 s3, s3, 0
	s_mov_b32 m0, s39
	v_lshl_add_u64 v[224:225], s[2:3], 0, v[128:129]
	ds_read_b128 v[184:187], v154 offset:32768
	ds_read_b128 v[188:191], v154 offset:33792
	ds_read_b128 v[192:195], v154 offset:34816
	ds_read_b128 v[196:199], v154 offset:35840
	ds_read_b128 v[200:203], v154 offset:36864
	ds_read_b128 v[204:207], v154 offset:37888
	ds_read_b128 v[208:211], v154 offset:38912
	ds_read_b128 v[212:215], v154 offset:39936
	global_load_lds_dwordx4 v[224:225], off
	v_lshl_add_u64 v[224:225], s[2:3], 0, v[132:133]
	s_mov_b32 m0, s40
	s_nop 0
	global_load_lds_dwordx4 v[224:225], off
	s_waitcnt vmcnt(8)
	s_waitcnt lgkmcnt(0)
	s_barrier
	s_setprio 1
	s_waitcnt lgkmcnt(0)
	v_mfma_f32_16x16x32_bf16 v[124:127], v[144:147], v[184:187], v[124:127]
	v_mfma_f32_16x16x32_bf16 v[124:127], v[156:159], v[188:191], v[124:127]
	v_mfma_f32_16x16x32_bf16 v[120:123], v[160:163], v[184:187], v[120:123]
	v_mfma_f32_16x16x32_bf16 v[120:123], v[164:167], v[188:191], v[120:123]
	v_mfma_f32_16x16x32_bf16 v[116:119], v[144:147], v[192:195], v[116:119]
	v_mfma_f32_16x16x32_bf16 v[116:119], v[156:159], v[196:199], v[116:119]
	v_mfma_f32_16x16x32_bf16 v[108:111], v[160:163], v[192:195], v[108:111]
	v_mfma_f32_16x16x32_bf16 v[108:111], v[164:167], v[196:199], v[108:111]
	v_mfma_f32_16x16x32_bf16 v[100:103], v[144:147], v[200:203], v[100:103]
	v_mfma_f32_16x16x32_bf16 v[100:103], v[156:159], v[204:207], v[100:103]
	v_mfma_f32_16x16x32_bf16 v[92:95], v[160:163], v[200:203], v[92:95]
	v_mfma_f32_16x16x32_bf16 v[92:95], v[164:167], v[204:207], v[92:95]
	v_mfma_f32_16x16x32_bf16 v[84:87], v[144:147], v[208:211], v[84:87]
	v_mfma_f32_16x16x32_bf16 v[84:87], v[156:159], v[212:215], v[84:87]
	v_mfma_f32_16x16x32_bf16 v[76:79], v[160:163], v[208:211], v[76:79]
	v_mfma_f32_16x16x32_bf16 v[76:79], v[164:167], v[212:215], v[76:79]
	s_setprio 0
	s_setprio 1
	v_mfma_f32_16x16x32_bf16 v[112:115], v[168:171], v[184:187], v[112:115]
	v_mfma_f32_16x16x32_bf16 v[112:115], v[172:175], v[188:191], v[112:115]
	v_mfma_f32_16x16x32_bf16 v[104:107], v[176:179], v[184:187], v[104:107]
	v_mfma_f32_16x16x32_bf16 v[104:107], v[180:183], v[188:191], v[104:107]
	v_mfma_f32_16x16x32_bf16 v[96:99], v[168:171], v[192:195], v[96:99]
	v_mfma_f32_16x16x32_bf16 v[96:99], v[172:175], v[196:199], v[96:99]
	v_mfma_f32_16x16x32_bf16 v[88:91], v[176:179], v[192:195], v[88:91]
	v_mfma_f32_16x16x32_bf16 v[88:91], v[180:183], v[196:199], v[88:91]
	v_mfma_f32_16x16x32_bf16 v[80:83], v[168:171], v[200:203], v[80:83]
	v_mfma_f32_16x16x32_bf16 v[80:83], v[172:175], v[204:207], v[80:83]
	v_mfma_f32_16x16x32_bf16 v[72:75], v[176:179], v[200:203], v[72:75]
	v_mfma_f32_16x16x32_bf16 v[72:75], v[180:183], v[204:207], v[72:75]
	v_mfma_f32_16x16x32_bf16 v[68:71], v[168:171], v[208:211], v[68:71]
	v_mfma_f32_16x16x32_bf16 v[68:71], v[172:175], v[212:215], v[68:71]
	v_mfma_f32_16x16x32_bf16 v[64:67], v[176:179], v[208:211], v[64:67]
	v_mfma_f32_16x16x32_bf16 v[64:67], v[180:183], v[212:215], v[64:67]
	s_setprio 0
	s_barrier
; #define PG8_STAGE(bufoff, gbase, voff) do { _Pragma("unroll") for (int _i = 0; _i < 2; ++_i) \
;         __builtin_amdgcn_global_load_lds((const unsigned*)((const char*)(gbase) + (voff)[_i]), (PG8_LAS unsigned*)(lds + (bufoff) + ldsw + _i * 8192), 16, 0, 0); } while (0)
; #define PG8_LDA(dst, b, h) do { _Pragma("unroll") for (int m = 0; m < 4; ++m) _Pragma("unroll") for (int k = 0; k < 2; ++k) dst[m][k] = *(const PG8_LAS bf16x8*)(lds + PG8_SA(b, h) + aoff + m * 2048 + k * 1024); } while (0)
; #define PG8_BAR __builtin_amdgcn_s_barrier()
; template <class Epi, class Sched, bool ALIGN_EPI = false, bool SP2 = false>
; __device__ __forceinline__ void gemm_phase(PG8_LAS unsigned char* lds, const Gemm g, const Sched& S, const Epi& E, const int tid) {
;     ...
;             PG8_LDA(At, 1, 1); PG8_STAGE(PG8_SB(1, 0), b3, voffB); PG8_STAGE(PG8_SB(1, 1), b3 + hstep, voffB); PG8_STAGE(PG8_SA(1, 0), a3, voffA);
;             PG8_WAIT_V(8); PG8_WAIT_L(0); PG8_BAR; PG8_MMA(1, 0, At, B0); PG8_MMA(1, 1, At, B1); PG8_BAR; PG8_SCHED;
;             } else {
;             PG8_LDB(B0, 0, 0); PG8_SCHED; PG8_LDA(At, 0, 0); PG8_STAGE(PG8_SA(1, 1), a1 + hstep, voffA);
;             PG8_WAIT_L(8); PG8_BAR; PG8_WAIT_L(0); PG8_MMA(0, 0, At, B0); PG8_BAR; PG8_SCHED;
;             PG8_LDB(B1, 0, 1); PG8_STAGE(PG8_SB(0, 0), b2, voffB);
;             PG8_BAR; PG8_WAIT_L(0); PG8_MMA(0, 1, At, B1); PG8_BAR;
;             PG8_LDA(At, 0, 1); PG8_STAGE(PG8_SA(0, 0), a2, voffA);
;             PG8_BAR; PG8_WAIT_L(0); PG8_MMA(1, 0, At, B0); PG8_BAR; PG8_SCHED;
;             PG8_STAGE(PG8_SB(0, 1), b2 + hstep, voffB);
;             PG8_WAIT_V(6); PG8_BAR; PG8_MMA(1, 1, At, B1); PG8_BAR;
;             PG8_LDB(B0, 1, 0); PG8_SCHED; PG8_LDA(At, 1, 0); PG8_STAGE(PG8_SA(0, 1), a2 + hstep, voffA);
;             PG8_WAIT_L(8); PG8_BAR; PG8_WAIT_L(0); PG8_MMA(0, 0, At, B0); PG8_BAR; PG8_SCHED;
;             PG8_LDB(B1, 1, 1); PG8_STAGE(PG8_SB(1, 0), b3, voffB);
;             PG8_BAR; PG8_WAIT_L(0); PG8_MMA(0, 1, At, B1); PG8_BAR;
;             PG8_LDA(At, 1, 1); PG8_STAGE(PG8_SA(1, 0), a3, voffA);
;             PG8_BAR; PG8_WAIT_L(0); PG8_MMA(1, 0, At, B0); PG8_BAR; PG8_SCHED;
;             PG8_STAGE(PG8_SB(1, 1), b3 + hstep, voffB);
;             PG8_WAIT_V(6); PG8_BAR; PG8_MMA(1, 1, At, B1); PG8_BAR;
;             }
;         }
;         if constexpr (ALIGN_EPI) { if (wr == 0) PG8_BAR; }
	s_add_i32 s2, s57, s37
	v_lshl_add_u64 v[216:217], v[216:217], 0, s[10:11]
	s_mov_b32 m0, s2
	ds_read_b128 v[184:187], v154 offset:49152
	ds_read_b128 v[188:191], v154 offset:50176
	ds_read_b128 v[192:195], v154 offset:51200
	ds_read_b128 v[196:199], v154 offset:52224
	ds_read_b128 v[200:203], v154 offset:53248
	ds_read_b128 v[204:207], v154 offset:54272
	ds_read_b128 v[208:211], v154 offset:55296
	ds_read_b128 v[212:215], v154 offset:56320
	global_load_lds_dwordx4 v[216:217], off
	s_add_i32 m0, s2, 0x2000
	s_add_u32 s0, s0, 0x80080
	v_lshl_add_u64 v[216:217], v[218:219], 0, s[10:11]
	s_addc_u32 s1, s1, 0
	s_add_i32 s2, s58, s37
	global_load_lds_dwordx4 v[216:217], off
	v_lshl_add_u64 v[216:217], s[0:1], 0, v[130:131]
	s_mov_b32 m0, s2
	s_nop 0
	global_load_lds_dwordx4 v[216:217], off
	v_lshl_add_u64 v[216:217], s[0:1], 0, v[134:135]
	s_add_i32 m0, s2, 0x2000
	s_nop 0
	global_load_lds_dwordx4 v[216:217], off
	v_lshl_add_u64 v[216:217], v[220:221], 0, s[10:11]
	s_mov_b32 m0, s42
	s_nop 0
	global_load_lds_dwordx4 v[216:217], off
	v_lshl_add_u64 v[216:217], v[222:223], 0, s[10:11]
	s_mov_b32 m0, s44
	s_nop 0
	global_load_lds_dwordx4 v[216:217], off
	s_waitcnt vmcnt(8)
	s_waitcnt lgkmcnt(0)
	s_barrier
	s_setprio 1
	s_waitcnt lgkmcnt(0)
	v_mfma_f32_16x16x32_bf16 v[60:63], v[144:147], v[184:187], v[60:63]
	v_mfma_f32_16x16x32_bf16 v[60:63], v[156:159], v[188:191], v[60:63]
	v_mfma_f32_16x16x32_bf16 v[56:59], v[160:163], v[184:187], v[56:59]
	v_mfma_f32_16x16x32_bf16 v[56:59], v[164:167], v[188:191], v[56:59]
	v_mfma_f32_16x16x32_bf16 v[52:55], v[144:147], v[192:195], v[52:55]
	v_mfma_f32_16x16x32_bf16 v[52:55], v[156:159], v[196:199], v[52:55]
	v_mfma_f32_16x16x32_bf16 v[44:47], v[160:163], v[192:195], v[44:47]
	v_mfma_f32_16x16x32_bf16 v[44:47], v[164:167], v[196:199], v[44:47]
	v_mfma_f32_16x16x32_bf16 v[36:39], v[144:147], v[200:203], v[36:39]
	v_mfma_f32_16x16x32_bf16 v[36:39], v[156:159], v[204:207], v[36:39]
	v_mfma_f32_16x16x32_bf16 v[28:31], v[160:163], v[200:203], v[28:31]
	v_mfma_f32_16x16x32_bf16 v[28:31], v[164:167], v[204:207], v[28:31]
	v_mfma_f32_16x16x32_bf16 v[20:23], v[144:147], v[208:211], v[20:23]
	v_mfma_f32_16x16x32_bf16 v[20:23], v[156:159], v[212:215], v[20:23]
	v_mfma_f32_16x16x32_bf16 v[12:15], v[160:163], v[208:211], v[12:15]
	v_mfma_f32_16x16x32_bf16 v[12:15], v[164:167], v[212:215], v[12:15]
	s_setprio 0
	s_setprio 1
	v_mfma_f32_16x16x32_bf16 v[48:51], v[168:171], v[184:187], v[48:51]
	v_mfma_f32_16x16x32_bf16 v[48:51], v[172:175], v[188:191], v[48:51]
	v_mfma_f32_16x16x32_bf16 v[40:43], v[176:179], v[184:187], v[40:43]
	v_mfma_f32_16x16x32_bf16 v[40:43], v[180:183], v[188:191], v[40:43]
	v_mfma_f32_16x16x32_bf16 v[32:35], v[168:171], v[192:195], v[32:35]
	v_mfma_f32_16x16x32_bf16 v[32:35], v[172:175], v[196:199], v[32:35]
	v_mfma_f32_16x16x32_bf16 v[24:27], v[176:179], v[192:195], v[24:27]
	v_mfma_f32_16x16x32_bf16 v[24:27], v[180:183], v[196:199], v[24:27]
	v_mfma_f32_16x16x32_bf16 v[16:19], v[168:171], v[200:203], v[16:19]
	v_mfma_f32_16x16x32_bf16 v[16:19], v[172:175], v[204:207], v[16:19]
	v_mfma_f32_16x16x32_bf16 v[8:11], v[176:179], v[200:203], v[8:11]
	v_mfma_f32_16x16x32_bf16 v[8:11], v[180:183], v[204:207], v[8:11]
	v_mfma_f32_16x16x32_bf16 v[4:7], v[168:171], v[208:211], v[4:7]
	v_mfma_f32_16x16x32_bf16 v[4:7], v[172:175], v[212:215], v[4:7]
	v_mfma_f32_16x16x32_bf16 v[0:3], v[176:179], v[208:211], v[0:3]
	v_mfma_f32_16x16x32_bf16 v[0:3], v[180:183], v[212:215], v[0:3]
	s_setprio 0
	s_barrier
	s_add_i32 s56, s56, 2
	s_add_u32 s34, s34, 0x100
	s_addc_u32 s35, s35, 0
	s_add_u32 s54, s54, 0x100
	s_addc_u32 s55, s55, 0
	s_cmp_gt_u32 s56, 29
	s_cbranch_scc0 .LBB0_95
	s_and_b64 vcc, exec, s[20:21]
	s_cbranch_vccz .LBB0_98
	s_barrier

; #define PG8_STAGE(bufoff, gbase, voff) do { _Pragma("unroll") for (int _i = 0; _i < 2; ++_i) \
;         __builtin_amdgcn_global_load_lds((const unsigned*)((const char*)(gbase) + (voff)[_i]), (PG8_LAS unsigned*)(lds + (bufoff) + ldsw + _i * 8192), 16, 0, 0); } while (0)
; #define PG8_LDA(dst, b, h) do { _Pragma("unroll") for (int m = 0; m < 4; ++m) _Pragma("unroll") for (int k = 0; k < 2; ++k) dst[m][k] = *(const PG8_LAS bf16x8*)(lds + PG8_SA(b, h) + aoff + m * 2048 + k * 1024); } while (0)
; #define PG8_LDB(dst, b, h) do { _Pragma("unroll") for (int n = 0; n < 2; ++n) _Pragma("unroll") for (int k = 0; k < 2; ++k) dst[n][k] = *(const PG8_LAS bf16x8*)(lds + PG8_SB(b, h) + boff + n * 2048 + k * 1024); } while (0)
; #define PG8_MMA(ai, bj, At, Bt) do { __builtin_amdgcn_s_setprio(1); _Pragma("unroll") for (int m = 0; m < 4; ++m) _Pragma("unroll") for (int n = 0; n < 2; ++n) _Pragma("unroll") for (int k = 0; k < 2; ++k) \
;         acc[ai][bj][m][n] = __builtin_amdgcn_mfma_f32_16x16x32_bf16(Bt[n][k], At[m][k], acc[ai][bj][m][n], 0, 0, 0); __builtin_amdgcn_s_setprio(0); } while (0)
; #define PG8_WAIT_V(n) asm volatile("s_waitcnt vmcnt(" #n ")" ::: "memory")
; #define PG8_WAIT_L(n) asm volatile("s_waitcnt lgkmcnt(" #n ")" ::: "memory")
; #define PG8_BAR __builtin_amdgcn_s_barrier()
; template <class Epi, class Sched, bool ALIGN_EPI = false, bool SP2 = false>
; __device__ __forceinline__ void gemm_phase(PG8_LAS unsigned char* lds, const Gemm g, const Sched& S, const Epi& E, const int tid) {
;     ...
;             const char* a1 = cA + (size_t)(t + 1) * kstep;
;             const char* a2 = last ? nA : cA + (size_t)(t + 2) * kstep; const char* b2 = last ? nB : cB + (size_t)(t + 2) * kstep;
;             const char* a3 = a2 + kstep; const char* b3 = b2 + kstep;
;             if (last && has_next) S.a_ready(nxt);
;             if constexpr (SP2) {
;             PG8_LDB(B0, 0, 0); PG8_LDB(B1, 0, 1); PG8_SCHED; PG8_LDA(At, 0, 0); PG8_STAGE(PG8_SA(1, 1), a1 + hstep, voffA);
;             PG8_WAIT_V(8); PG8_WAIT_L(0); PG8_BAR; PG8_MMA(0, 0, At, B0); PG8_MMA(0, 1, At, B1); PG8_BAR; PG8_SCHED;
;             PG8_LDA(At, 0, 1); PG8_STAGE(PG8_SB(0, 0), b2, voffB); PG8_STAGE(PG8_SB(0, 1), b2 + hstep, voffB); PG8_STAGE(PG8_SA(0, 0), a2, voffA);
;             PG8_WAIT_V(8); PG8_WAIT_L(0); PG8_BAR; PG8_MMA(1, 0, At, B0); PG8_MMA(1, 1, At, B1); PG8_BAR; PG8_SCHED;
.LBB0_119:
	ds_read_b128 v[144:147], v152
	ds_read_b128 v[156:159], v152 offset:1024
	ds_read_b128 v[160:163], v152 offset:2048
	ds_read_b128 v[164:167], v152 offset:3072
	ds_read_b128 v[168:171], v153
	ds_read_b128 v[172:175], v153 offset:1024
	ds_read_b128 v[176:179], v153 offset:2048
	ds_read_b128 v[180:183], v153 offset:3072
	s_add_u32 s0, s30, 0xfff80080
	s_addc_u32 s1, s31, -1
	s_cmp_eq_u32 s55, 28
	s_cselect_b32 s3, s4, s1
	s_cselect_b32 s2, s5, s0
	s_cselect_b32 s1, s21, s54
	s_cselect_b32 s0, s23, s53
	v_lshl_add_u64 v[216:217], s[30:31], 0, v[136:137]
	s_add_i32 m0, s29, 0xc000
	ds_read_b128 v[184:187], v154
	ds_read_b128 v[188:191], v154 offset:1024
	ds_read_b128 v[192:195], v154 offset:2048
	ds_read_b128 v[196:199], v154 offset:3072
	ds_read_b128 v[200:203], v154 offset:4096
	ds_read_b128 v[204:207], v154 offset:5120
	ds_read_b128 v[208:211], v154 offset:6144
	ds_read_b128 v[212:215], v154 offset:7168
	global_load_lds_dwordx4 v[216:217], off
	v_lshl_add_u64 v[216:217], s[30:31], 0, v[138:139]
	s_add_i32 m0, s29, 0xe000
	s_nop 0
	global_load_lds_dwordx4 v[216:217], off
	s_waitcnt vmcnt(8)
	s_waitcnt lgkmcnt(0)
	s_barrier
	s_setprio 1
	s_waitcnt lgkmcnt(0)
	v_mfma_f32_16x16x32_bf16 v[124:127], v[144:147], v[184:187], v[124:127]
	v_mfma_f32_16x16x32_bf16 v[124:127], v[156:159], v[188:191], v[124:127]
	v_mfma_f32_16x16x32_bf16 v[120:123], v[160:163], v[184:187], v[120:123]
	v_mfma_f32_16x16x32_bf16 v[120:123], v[164:167], v[188:191], v[120:123]
	v_mfma_f32_16x16x32_bf16 v[116:119], v[144:147], v[192:195], v[116:119]
	v_mfma_f32_16x16x32_bf16 v[116:119], v[156:159], v[196:199], v[116:119]
	v_mfma_f32_16x16x32_bf16 v[108:111], v[160:163], v[192:195], v[108:111]
	v_mfma_f32_16x16x32_bf16 v[108:111], v[164:167], v[196:199], v[108:111]
	v_mfma_f32_16x16x32_bf16 v[100:103], v[144:147], v[200:203], v[100:103]
	v_mfma_f32_16x16x32_bf16 v[100:103], v[156:159], v[204:207], v[100:103]
	v_mfma_f32_16x16x32_bf16 v[92:95], v[160:163], v[200:203], v[92:95]
	v_mfma_f32_16x16x32_bf16 v[92:95], v[164:167], v[204:207], v[92:95]
	v_mfma_f32_16x16x32_bf16 v[84:87], v[144:147], v[208:211], v[84:87]
	v_mfma_f32_16x16x32_bf16 v[84:87], v[156:159], v[212:215], v[84:87]
	v_mfma_f32_16x16x32_bf16 v[76:79], v[160:163], v[208:211], v[76:79]
	v_mfma_f32_16x16x32_bf16 v[76:79], v[164:167], v[212:215], v[76:79]
	s_setprio 0
	s_setprio 1
	v_mfma_f32_16x16x32_bf16 v[112:115], v[168:171], v[184:187], v[112:115]
	v_mfma_f32_16x16x32_bf16 v[112:115], v[172:175], v[188:191], v[112:115]
	v_mfma_f32_16x16x32_bf16 v[104:107], v[176:179], v[184:187], v[104:107]
	v_mfma_f32_16x16x32_bf16 v[104:107], v[180:183], v[188:191], v[104:107]
	v_mfma_f32_16x16x32_bf16 v[96:99], v[168:171], v[192:195], v[96:99]
	v_mfma_f32_16x16x32_bf16 v[96:99], v[172:175], v[196:199], v[96:99]
	v_mfma_f32_16x16x32_bf16 v[88:91], v[176:179], v[192:195], v[88:91]
	v_mfma_f32_16x16x32_bf16 v[88:91], v[180:183], v[196:199], v[88:91]
	v_mfma_f32_16x16x32_bf16 v[80:83], v[168:171], v[200:203], v[80:83]
	v_mfma_f32_16x16x32_bf16 v[80:83], v[172:175], v[204:207], v[80:83]
	v_mfma_f32_16x16x32_bf16 v[72:75], v[176:179], v[200:203], v[72:75]
	v_mfma_f32_16x16x32_bf16 v[72:75], v[180:183], v[204:207], v[72:75]
	v_mfma_f32_16x16x32_bf16 v[68:71], v[168:171], v[208:211], v[68:71]
	v_mfma_f32_16x16x32_bf16 v[68:71], v[172:175], v[212:215], v[68:71]
	v_mfma_f32_16x16x32_bf16 v[64:67], v[176:179], v[208:211], v[64:67]
	v_mfma_f32_16x16x32_bf16 v[64:67], v[180:183], v[212:215], v[64:67]
	s_setprio 0
	s_barrier
	s_add_i32 s56, s48, s35
	v_lshl_add_u64 v[216:217], s[0:1], 0, v[130:131]
	s_mov_b32 m0, s56
	ds_read_b128 v[184:187], v154 offset:16384
	ds_read_b128 v[188:191], v154 offset:17408
	ds_read_b128 v[192:195], v154 offset:18432
	ds_read_b128 v[196:199], v154 offset:19456
	ds_read_b128 v[200:203], v154 offset:20480
	ds_read_b128 v[204:207], v154 offset:21504
	ds_read_b128 v[208:211], v154 offset:22528
	ds_read_b128 v[212:215], v154 offset:23552
	global_load_lds_dwordx4 v[216:217], off
	s_add_i32 m0, s56, 0x2000
	s_add_u32 s56, s0, 0x80000
	v_lshl_add_u64 v[218:219], s[0:1], 0, v[134:135]
	s_addc_u32 s57, s1, 0
	s_add_i32 s58, s50, s35
	global_load_lds_dwordx4 v[218:219], off
	v_lshl_add_u64 v[220:221], s[56:57], 0, v[130:131]
	s_mov_b32 m0, s58
	v_lshl_add_u64 v[222:223], s[2:3], 0, v[132:133]
	global_load_lds_dwordx4 v[220:221], off
	v_lshl_add_u64 v[220:221], s[56:57], 0, v[134:135]
	s_add_i32 m0, s58, 0x2000
	s_nop 0
	global_load_lds_dwordx4 v[220:221], off
	v_lshl_add_u64 v[220:221], s[2:3], 0, v[128:129]
	s_mov_b32 m0, s29
	s_nop 0
	global_load_lds_dwordx4 v[220:221], off
	s_mov_b32 m0, s36
	s_nop 0
	global_load_lds_dwordx4 v[222:223], off
	s_waitcnt vmcnt(8)
	s_waitcnt lgkmcnt(0)
	s_barrier
; #define PG8_STAGE(bufoff, gbase, voff) do { _Pragma("unroll") for (int _i = 0; _i < 2; ++_i) \
;         __builtin_amdgcn_global_load_lds((const unsigned*)((const char*)(gbase) + (voff)[_i]), (PG8_LAS unsigned*)(lds + (bufoff) + ldsw + _i * 8192), 16, 0, 0); } while (0)
; #define PG8_LDA(dst, b, h) do { _Pragma("unroll") for (int m = 0; m < 4; ++m) _Pragma("unroll") for (int k = 0; k < 2; ++k) dst[m][k] = *(const PG8_LAS bf16x8*)(lds + PG8_SA(b, h) + aoff + m * 2048 + k * 1024); } while (0)
; #define PG8_LDB(dst, b, h) do { _Pragma("unroll") for (int n = 0; n < 2; ++n) _Pragma("unroll") for (int k = 0; k < 2; ++k) dst[n][k] = *(const PG8_LAS bf16x8*)(lds + PG8_SB(b, h) + boff + n * 2048 + k * 1024); } while (0)
; #define PG8_MMA(ai, bj, At, Bt) do { __builtin_amdgcn_s_setprio(1); _Pragma("unroll") for (int m = 0; m < 4; ++m) _Pragma("unroll") for (int n = 0; n < 2; ++n) _Pragma("unroll") for (int k = 0; k < 2; ++k) \
;         acc[ai][bj][m][n] = __builtin_amdgcn_mfma_f32_16x16x32_bf16(Bt[n][k], At[m][k], acc[ai][bj][m][n], 0, 0, 0); __builtin_amdgcn_s_setprio(0); } while (0)
; #define PG8_WAIT_V(n) asm volatile("s_waitcnt vmcnt(" #n ")" ::: "memory")
; #define PG8_WAIT_L(n) asm volatile("s_waitcnt lgkmcnt(" #n ")" ::: "memory")
; #define PG8_BAR __builtin_amdgcn_s_barrier()
; #define PG8_SCHED __builtin_amdgcn_sched_barrier(0)
; template <class Epi, class Sched, bool ALIGN_EPI = false, bool SP2 = false>
; __device__ __forceinline__ void gemm_phase(PG8_LAS unsigned char* lds, const Gemm g, const Sched& S, const Epi& E, const int tid) {
;     ...
;             PG8_WAIT_V(8); PG8_WAIT_L(0); PG8_BAR; PG8_MMA(1, 0, At, B0); PG8_MMA(1, 1, At, B1); PG8_BAR; PG8_SCHED;
;             PG8_LDB(B0, 1, 0); PG8_LDB(B1, 1, 1); PG8_SCHED; PG8_LDA(At, 1, 0); PG8_STAGE(PG8_SA(0, 1), a2 + hstep, voffA);
;             PG8_WAIT_V(8); PG8_WAIT_L(0); PG8_BAR; PG8_MMA(0, 0, At, B0); PG8_MMA(0, 1, At, B1); PG8_BAR; PG8_SCHED;
	s_setprio 1
	s_waitcnt lgkmcnt(0)
	v_mfma_f32_16x16x32_bf16 v[60:63], v[144:147], v[184:187], v[60:63]
	v_mfma_f32_16x16x32_bf16 v[60:63], v[156:159], v[188:191], v[60:63]
	v_mfma_f32_16x16x32_bf16 v[56:59], v[160:163], v[184:187], v[56:59]
	v_mfma_f32_16x16x32_bf16 v[56:59], v[164:167], v[188:191], v[56:59]
	v_mfma_f32_16x16x32_bf16 v[52:55], v[144:147], v[192:195], v[52:55]
	v_mfma_f32_16x16x32_bf16 v[52:55], v[156:159], v[196:199], v[52:55]
	v_mfma_f32_16x16x32_bf16 v[44:47], v[160:163], v[192:195], v[44:47]
	v_mfma_f32_16x16x32_bf16 v[44:47], v[164:167], v[196:199], v[44:47]
	v_mfma_f32_16x16x32_bf16 v[36:39], v[144:147], v[200:203], v[36:39]
	v_mfma_f32_16x16x32_bf16 v[36:39], v[156:159], v[204:207], v[36:39]
	v_mfma_f32_16x16x32_bf16 v[28:31], v[160:163], v[200:203], v[28:31]
	v_mfma_f32_16x16x32_bf16 v[28:31], v[164:167], v[204:207], v[28:31]
	v_mfma_f32_16x16x32_bf16 v[20:23], v[144:147], v[208:211], v[20:23]
	v_mfma_f32_16x16x32_bf16 v[20:23], v[156:159], v[212:215], v[20:23]
	v_mfma_f32_16x16x32_bf16 v[12:15], v[160:163], v[208:211], v[12:15]
	v_mfma_f32_16x16x32_bf16 v[12:15], v[164:167], v[212:215], v[12:15]
	s_setprio 0
	s_setprio 1
	v_mfma_f32_16x16x32_bf16 v[48:51], v[168:171], v[184:187], v[48:51]
	v_mfma_f32_16x16x32_bf16 v[48:51], v[172:175], v[188:191], v[48:51]
	v_mfma_f32_16x16x32_bf16 v[40:43], v[176:179], v[184:187], v[40:43]
	v_mfma_f32_16x16x32_bf16 v[40:43], v[180:183], v[188:191], v[40:43]
	v_mfma_f32_16x16x32_bf16 v[32:35], v[168:171], v[192:195], v[32:35]
	v_mfma_f32_16x16x32_bf16 v[32:35], v[172:175], v[196:199], v[32:35]
	v_mfma_f32_16x16x32_bf16 v[24:27], v[176:179], v[192:195], v[24:27]
	v_mfma_f32_16x16x32_bf16 v[24:27], v[180:183], v[196:199], v[24:27]
	v_mfma_f32_16x16x32_bf16 v[16:19], v[168:171], v[200:203], v[16:19]
	v_mfma_f32_16x16x32_bf16 v[16:19], v[172:175], v[204:207], v[16:19]
	v_mfma_f32_16x16x32_bf16 v[8:11], v[176:179], v[200:203], v[8:11]
	v_mfma_f32_16x16x32_bf16 v[8:11], v[180:183], v[204:207], v[8:11]
	v_mfma_f32_16x16x32_bf16 v[4:7], v[168:171], v[208:211], v[4:7]
	v_mfma_f32_16x16x32_bf16 v[4:7], v[172:175], v[212:215], v[4:7]
	v_mfma_f32_16x16x32_bf16 v[0:3], v[176:179], v[208:211], v[0:3]
	v_mfma_f32_16x16x32_bf16 v[0:3], v[180:183], v[212:215], v[0:3]
	s_setprio 0
	s_barrier
	s_add_i32 s56, 0, 0x18000
	v_add_u32_e32 v155, s56, v150
	s_add_i32 s57, 0, 0x1c000
	ds_read_b128 v[144:147], v155
	ds_read_b128 v[156:159], v155 offset:1024
	ds_read_b128 v[160:163], v155 offset:2048
	ds_read_b128 v[164:167], v155 offset:3072
	v_add_u32_e32 v155, s57, v150
	ds_read_b128 v[168:171], v155
	ds_read_b128 v[172:175], v155 offset:1024
	ds_read_b128 v[176:179], v155 offset:2048
	ds_read_b128 v[180:183], v155 offset:3072
	s_add_u32 s2, s2, 0x80000
	s_addc_u32 s3, s3, 0
	s_mov_b32 m0, s37
	v_lshl_add_u64 v[224:225], s[2:3], 0, v[128:129]
	ds_read_b128 v[184:187], v154 offset:32768
	ds_read_b128 v[188:191], v154 offset:33792
	ds_read_b128 v[192:195], v154 offset:34816
	ds_read_b128 v[196:199], v154 offset:35840
	ds_read_b128 v[200:203], v154 offset:36864
	ds_read_b128 v[204:207], v154 offset:37888
	ds_read_b128 v[208:211], v154 offset:38912
	ds_read_b128 v[212:215], v154 offset:39936
	global_load_lds_dwordx4 v[224:225], off
	v_lshl_add_u64 v[224:225], s[2:3], 0, v[132:133]
	s_mov_b32 m0, s38
	s_nop 0
	global_load_lds_dwordx4 v[224:225], off
	s_waitcnt vmcnt(8)
	s_waitcnt lgkmcnt(0)
	s_barrier
	s_setprio 1
	s_waitcnt lgkmcnt(0)
	v_mfma_f32_16x16x32_bf16 v[124:127], v[144:147], v[184:187], v[124:127]
	v_mfma_f32_16x16x32_bf16 v[124:127], v[156:159], v[188:191], v[124:127]
	v_mfma_f32_16x16x32_bf16 v[120:123], v[160:163], v[184:187], v[120:123]
	v_mfma_f32_16x16x32_bf16 v[120:123], v[164:167], v[188:191], v[120:123]
	v_mfma_f32_16x16x32_bf16 v[116:119], v[144:147], v[192:195], v[116:119]
	v_mfma_f32_16x16x32_bf16 v[116:119], v[156:159], v[196:199], v[116:119]
	v_mfma_f32_16x16x32_bf16 v[108:111], v[160:163], v[192:195], v[108:111]
	v_mfma_f32_16x16x32_bf16 v[108:111], v[164:167], v[196:199], v[108:111]
	v_mfma_f32_16x16x32_bf16 v[100:103], v[144:147], v[200:203], v[100:103]
	v_mfma_f32_16x16x32_bf16 v[100:103], v[156:159], v[204:207], v[100:103]
	v_mfma_f32_16x16x32_bf16 v[92:95], v[160:163], v[200:203], v[92:95]
	v_mfma_f32_16x16x32_bf16 v[92:95], v[164:167], v[204:207], v[92:95]
	v_mfma_f32_16x16x32_bf16 v[84:87], v[144:147], v[208:211], v[84:87]
	v_mfma_f32_16x16x32_bf16 v[84:87], v[156:159], v[212:215], v[84:87]
	v_mfma_f32_16x16x32_bf16 v[76:79], v[160:163], v[208:211], v[76:79]
	v_mfma_f32_16x16x32_bf16 v[76:79], v[164:167], v[212:215], v[76:79]
	s_setprio 0
	s_setprio 1
	v_mfma_f32_16x16x32_bf16 v[112:115], v[168:171], v[184:187], v[112:115]
	v_mfma_f32_16x16x32_bf16 v[112:115], v[172:175], v[188:191], v[112:115]
	v_mfma_f32_16x16x32_bf16 v[104:107], v[176:179], v[184:187], v[104:107]
	v_mfma_f32_16x16x32_bf16 v[104:107], v[180:183], v[188:191], v[104:107]
	v_mfma_f32_16x16x32_bf16 v[96:99], v[168:171], v[192:195], v[96:99]
	v_mfma_f32_16x16x32_bf16 v[96:99], v[172:175], v[196:199], v[96:99]
	v_mfma_f32_16x16x32_bf16 v[88:91], v[176:179], v[192:195], v[88:91]
	v_mfma_f32_16x16x32_bf16 v[88:91], v[180:183], v[196:199], v[88:91]
	v_mfma_f32_16x16x32_bf16 v[80:83], v[168:171], v[200:203], v[80:83]
	v_mfma_f32_16x16x32_bf16 v[80:83], v[172:175], v[204:207], v[80:83]
	v_mfma_f32_16x16x32_bf16 v[72:75], v[176:179], v[200:203], v[72:75]
	v_mfma_f32_16x16x32_bf16 v[72:75], v[180:183], v[204:207], v[72:75]
	v_mfma_f32_16x16x32_bf16 v[68:71], v[168:171], v[208:211], v[68:71]
	v_mfma_f32_16x16x32_bf16 v[68:71], v[172:175], v[212:215], v[68:71]
	v_mfma_f32_16x16x32_bf16 v[64:67], v[176:179], v[208:211], v[64:67]
	v_mfma_f32_16x16x32_bf16 v[64:67], v[180:183], v[212:215], v[64:67]
	s_setprio 0
	s_barrier
; #define PG8_STAGE(bufoff, gbase, voff) do { _Pragma("unroll") for (int _i = 0; _i < 2; ++_i) \
;         __builtin_amdgcn_global_load_lds((const unsigned*)((const char*)(gbase) + (voff)[_i]), (PG8_LAS unsigned*)(lds + (bufoff) + ldsw + _i * 8192), 16, 0, 0); } while (0)
; #define PG8_LDA(dst, b, h) do { _Pragma("unroll") for (int m = 0; m < 4; ++m) _Pragma("unroll") for (int k = 0; k < 2; ++k) dst[m][k] = *(const PG8_LAS bf16x8*)(lds + PG8_SA(b, h) + aoff + m * 2048 + k * 1024); } while (0)
; #define PG8_BAR __builtin_amdgcn_s_barrier()
; template <class Epi, class Sched, bool ALIGN_EPI = false, bool SP2 = false>
; __device__ __forceinline__ void gemm_phase(PG8_LAS unsigned char* lds, const Gemm g, const Sched& S, const Epi& E, const int tid) {
;     ...
;             PG8_LDA(At, 1, 1); PG8_STAGE(PG8_SB(1, 0), b3, voffB); PG8_STAGE(PG8_SB(1, 1), b3 + hstep, voffB); PG8_STAGE(PG8_SA(1, 0), a3, voffA);
;             PG8_WAIT_V(8); PG8_WAIT_L(0); PG8_BAR; PG8_MMA(1, 0, At, B0); PG8_MMA(1, 1, At, B1); PG8_BAR; PG8_SCHED;
;             } else {
;             PG8_LDB(B0, 0, 0); PG8_SCHED; PG8_LDA(At, 0, 0); PG8_STAGE(PG8_SA(1, 1), a1 + hstep, voffA);
;             PG8_WAIT_L(8); PG8_BAR; PG8_WAIT_L(0); PG8_MMA(0, 0, At, B0); PG8_BAR; PG8_SCHED;
;             PG8_LDB(B1, 0, 1); PG8_STAGE(PG8_SB(0, 0), b2, voffB);
;             PG8_BAR; PG8_WAIT_L(0); PG8_MMA(0, 1, At, B1); PG8_BAR;
;             PG8_LDA(At, 0, 1); PG8_STAGE(PG8_SA(0, 0), a2, voffA);
;             PG8_BAR; PG8_WAIT_L(0); PG8_MMA(1, 0, At, B0); PG8_BAR; PG8_SCHED;
;             PG8_STAGE(PG8_SB(0, 1), b2 + hstep, voffB);
;             PG8_WAIT_V(6); PG8_BAR; PG8_MMA(1, 1, At, B1); PG8_BAR;
;             PG8_LDB(B0, 1, 0); PG8_SCHED; PG8_LDA(At, 1, 0); PG8_STAGE(PG8_SA(0, 1), a2 + hstep, voffA);
;             PG8_WAIT_L(8); PG8_BAR; PG8_WAIT_L(0); PG8_MMA(0, 0, At, B0); PG8_BAR; PG8_SCHED;
;             PG8_LDB(B1, 1, 1); PG8_STAGE(PG8_SB(1, 0), b3, voffB);
;             PG8_BAR; PG8_WAIT_L(0); PG8_MMA(0, 1, At, B1); PG8_BAR;
;             PG8_LDA(At, 1, 1); PG8_STAGE(PG8_SA(1, 0), a3, voffA);
;             PG8_BAR; PG8_WAIT_L(0); PG8_MMA(1, 0, At, B0); PG8_BAR; PG8_SCHED;
;             PG8_STAGE(PG8_SB(1, 1), b3 + hstep, voffB);
;             PG8_WAIT_V(6); PG8_BAR; PG8_MMA(1, 1, At, B1); PG8_BAR;
;             }
;         }
;         if constexpr (ALIGN_EPI) { if (wr == 0) PG8_BAR; }
	s_add_i32 s2, s56, s35
	v_lshl_add_u64 v[216:217], v[216:217], 0, s[10:11]
	s_mov_b32 m0, s2
	ds_read_b128 v[184:187], v154 offset:49152
	ds_read_b128 v[188:191], v154 offset:50176
	ds_read_b128 v[192:195], v154 offset:51200
	ds_read_b128 v[196:199], v154 offset:52224
	ds_read_b128 v[200:203], v154 offset:53248
	ds_read_b128 v[204:207], v154 offset:54272
	ds_read_b128 v[208:211], v154 offset:55296
	ds_read_b128 v[212:215], v154 offset:56320
	global_load_lds_dwordx4 v[216:217], off
	s_add_i32 m0, s2, 0x2000
	s_add_u32 s0, s0, 0x80080
	v_lshl_add_u64 v[216:217], v[218:219], 0, s[10:11]
	s_addc_u32 s1, s1, 0
	s_add_i32 s2, s57, s35
	global_load_lds_dwordx4 v[216:217], off
	v_lshl_add_u64 v[216:217], s[0:1], 0, v[130:131]
	s_mov_b32 m0, s2
	s_nop 0
	global_load_lds_dwordx4 v[216:217], off
	v_lshl_add_u64 v[216:217], s[0:1], 0, v[134:135]
	s_add_i32 m0, s2, 0x2000
	s_nop 0
	global_load_lds_dwordx4 v[216:217], off
	v_lshl_add_u64 v[216:217], v[220:221], 0, s[10:11]
	s_mov_b32 m0, s41
	s_nop 0
	global_load_lds_dwordx4 v[216:217], off
	v_lshl_add_u64 v[216:217], v[222:223], 0, s[10:11]
	s_mov_b32 m0, s42
	s_nop 0
	global_load_lds_dwordx4 v[216:217], off
	s_waitcnt vmcnt(8)
	s_waitcnt lgkmcnt(0)
	s_barrier
	s_setprio 1
	s_waitcnt lgkmcnt(0)
	v_mfma_f32_16x16x32_bf16 v[60:63], v[144:147], v[184:187], v[60:63]
	v_mfma_f32_16x16x32_bf16 v[60:63], v[156:159], v[188:191], v[60:63]
	v_mfma_f32_16x16x32_bf16 v[56:59], v[160:163], v[184:187], v[56:59]
	v_mfma_f32_16x16x32_bf16 v[56:59], v[164:167], v[188:191], v[56:59]
	v_mfma_f32_16x16x32_bf16 v[52:55], v[144:147], v[192:195], v[52:55]
	v_mfma_f32_16x16x32_bf16 v[52:55], v[156:159], v[196:199], v[52:55]
	v_mfma_f32_16x16x32_bf16 v[44:47], v[160:163], v[192:195], v[44:47]
	v_mfma_f32_16x16x32_bf16 v[44:47], v[164:167], v[196:199], v[44:47]
	v_mfma_f32_16x16x32_bf16 v[36:39], v[144:147], v[200:203], v[36:39]
	v_mfma_f32_16x16x32_bf16 v[36:39], v[156:159], v[204:207], v[36:39]
	v_mfma_f32_16x16x32_bf16 v[28:31], v[160:163], v[200:203], v[28:31]
	v_mfma_f32_16x16x32_bf16 v[28:31], v[164:167], v[204:207], v[28:31]
	v_mfma_f32_16x16x32_bf16 v[20:23], v[144:147], v[208:211], v[20:23]
	v_mfma_f32_16x16x32_bf16 v[20:23], v[156:159], v[212:215], v[20:23]
	v_mfma_f32_16x16x32_bf16 v[12:15], v[160:163], v[208:211], v[12:15]
	v_mfma_f32_16x16x32_bf16 v[12:15], v[164:167], v[212:215], v[12:15]
	s_setprio 0
	s_setprio 1
	v_mfma_f32_16x16x32_bf16 v[48:51], v[168:171], v[184:187], v[48:51]
	v_mfma_f32_16x16x32_bf16 v[48:51], v[172:175], v[188:191], v[48:51]
	v_mfma_f32_16x16x32_bf16 v[40:43], v[176:179], v[184:187], v[40:43]
	v_mfma_f32_16x16x32_bf16 v[40:43], v[180:183], v[188:191], v[40:43]
	v_mfma_f32_16x16x32_bf16 v[32:35], v[168:171], v[192:195], v[32:35]
	v_mfma_f32_16x16x32_bf16 v[32:35], v[172:175], v[196:199], v[32:35]
	v_mfma_f32_16x16x32_bf16 v[24:27], v[176:179], v[192:195], v[24:27]
	v_mfma_f32_16x16x32_bf16 v[24:27], v[180:183], v[196:199], v[24:27]
	v_mfma_f32_16x16x32_bf16 v[16:19], v[168:171], v[200:203], v[16:19]
	v_mfma_f32_16x16x32_bf16 v[16:19], v[172:175], v[204:207], v[16:19]
	v_mfma_f32_16x16x32_bf16 v[8:11], v[176:179], v[200:203], v[8:11]
	v_mfma_f32_16x16x32_bf16 v[8:11], v[180:183], v[204:207], v[8:11]
	v_mfma_f32_16x16x32_bf16 v[4:7], v[168:171], v[208:211], v[4:7]
	v_mfma_f32_16x16x32_bf16 v[4:7], v[172:175], v[212:215], v[4:7]
	v_mfma_f32_16x16x32_bf16 v[0:3], v[176:179], v[208:211], v[0:3]
	v_mfma_f32_16x16x32_bf16 v[0:3], v[180:183], v[212:215], v[0:3]
	s_setprio 0
	s_barrier
	s_add_i32 s55, s55, 2
	s_add_u32 s30, s30, 0x100
	s_addc_u32 s31, s31, 0
	s_add_u32 s53, s53, 0x100
	s_addc_u32 s54, s54, 0
	s_cmp_gt_u32 s55, 29
	s_cbranch_scc0 .LBB0_119
	s_and_b64 vcc, exec, s[18:19]
	s_cbranch_vccz .LBB0_122
	s_barrier

; #define PG8_STAGE(bufoff, gbase, voff) do { _Pragma("unroll") for (int _i = 0; _i < 2; ++_i) \
;         __builtin_amdgcn_global_load_lds((const unsigned*)((const char*)(gbase) + (voff)[_i]), (PG8_LAS unsigned*)(lds + (bufoff) + ldsw + _i * 8192), 16, 0, 0); } while (0)
; #define PG8_LDA(dst, b, h) do { _Pragma("unroll") for (int m = 0; m < 4; ++m) _Pragma("unroll") for (int k = 0; k < 2; ++k) dst[m][k] = *(const PG8_LAS bf16x8*)(lds + PG8_SA(b, h) + aoff + m * 2048 + k * 1024); } while (0)
; #define PG8_LDB(dst, b, h) do { _Pragma("unroll") for (int n = 0; n < 2; ++n) _Pragma("unroll") for (int k = 0; k < 2; ++k) dst[n][k] = *(const PG8_LAS bf16x8*)(lds + PG8_SB(b, h) + boff + n * 2048 + k * 1024); } while (0)
; #define PG8_MMA(ai, bj, At, Bt) do { __builtin_amdgcn_s_setprio(1); _Pragma("unroll") for (int m = 0; m < 4; ++m) _Pragma("unroll") for (int n = 0; n < 2; ++n) _Pragma("unroll") for (int k = 0; k < 2; ++k) \
;         acc[ai][bj][m][n] = __builtin_amdgcn_mfma_f32_16x16x32_bf16(Bt[n][k], At[m][k], acc[ai][bj][m][n], 0, 0, 0); __builtin_amdgcn_s_setprio(0); } while (0)
; #define PG8_WAIT_V(n) asm volatile("s_waitcnt vmcnt(" #n ")" ::: "memory")
; #define PG8_WAIT_L(n) asm volatile("s_waitcnt lgkmcnt(" #n ")" ::: "memory")
; #define PG8_BAR __builtin_amdgcn_s_barrier()
; template <class Epi, class Sched, bool ALIGN_EPI = false, bool SP2 = false>
; __device__ __forceinline__ void gemm_phase(PG8_LAS unsigned char* lds, const Gemm g, const Sched& S, const Epi& E, const int tid) {
;     ...
;             const char* a1 = cA + (size_t)(t + 1) * kstep;
;             const char* a2 = last ? nA : cA + (size_t)(t + 2) * kstep; const char* b2 = last ? nB : cB + (size_t)(t + 2) * kstep;
;             const char* a3 = a2 + kstep; const char* b3 = b2 + kstep;
;             if (last && has_next) S.a_ready(nxt);
;             if constexpr (SP2) {
;             PG8_LDB(B0, 0, 0); PG8_LDB(B1, 0, 1); PG8_SCHED; PG8_LDA(At, 0, 0); PG8_STAGE(PG8_SA(1, 1), a1 + hstep, voffA);
;             PG8_WAIT_V(8); PG8_WAIT_L(0); PG8_BAR; PG8_MMA(0, 0, At, B0); PG8_MMA(0, 1, At, B1); PG8_BAR; PG8_SCHED;
;             PG8_LDA(At, 0, 1); PG8_STAGE(PG8_SB(0, 0), b2, voffB); PG8_STAGE(PG8_SB(0, 1), b2 + hstep, voffB); PG8_STAGE(PG8_SA(0, 0), a2, voffA);
;             PG8_WAIT_V(8); PG8_WAIT_L(0); PG8_BAR; PG8_MMA(1, 0, At, B0); PG8_MMA(1, 1, At, B1); PG8_BAR; PG8_SCHED;
.LBB0_252:
	ds_read_b128 v[144:147], v152
	ds_read_b128 v[156:159], v152 offset:1024
	ds_read_b128 v[160:163], v152 offset:2048
	ds_read_b128 v[164:167], v152 offset:3072
	ds_read_b128 v[168:171], v153
	ds_read_b128 v[172:175], v153 offset:1024
	ds_read_b128 v[176:179], v153 offset:2048
	ds_read_b128 v[180:183], v153 offset:3072
	s_add_u32 s0, s28, 0xfffe0080
	s_addc_u32 s1, s29, -1
	s_cmp_eq_u32 s55, 4
	s_cselect_b32 s3, s4, s1
	s_cselect_b32 s2, s5, s0
	s_cselect_b32 s1, s19, s54
	s_cselect_b32 s0, s21, s53
	v_lshl_add_u64 v[216:217], s[28:29], 0, v[136:137]
	s_add_i32 m0, s27, 0xc000
	ds_read_b128 v[184:187], v154
	ds_read_b128 v[188:191], v154 offset:1024
	ds_read_b128 v[192:195], v154 offset:2048
	ds_read_b128 v[196:199], v154 offset:3072
	ds_read_b128 v[200:203], v154 offset:4096
	ds_read_b128 v[204:207], v154 offset:5120
	ds_read_b128 v[208:211], v154 offset:6144
	ds_read_b128 v[212:215], v154 offset:7168
	global_load_lds_dwordx4 v[216:217], off
	v_lshl_add_u64 v[216:217], s[28:29], 0, v[138:139]
	s_add_i32 m0, s27, 0xe000
	s_nop 0
	global_load_lds_dwordx4 v[216:217], off
	s_waitcnt vmcnt(8)
	s_waitcnt lgkmcnt(0)
	s_barrier
	s_setprio 1
	s_waitcnt lgkmcnt(0)
	v_mfma_f32_16x16x32_bf16 v[124:127], v[144:147], v[184:187], v[124:127]
	v_mfma_f32_16x16x32_bf16 v[124:127], v[156:159], v[188:191], v[124:127]
	v_mfma_f32_16x16x32_bf16 v[120:123], v[160:163], v[184:187], v[120:123]
	v_mfma_f32_16x16x32_bf16 v[120:123], v[164:167], v[188:191], v[120:123]
	v_mfma_f32_16x16x32_bf16 v[116:119], v[144:147], v[192:195], v[116:119]
	v_mfma_f32_16x16x32_bf16 v[116:119], v[156:159], v[196:199], v[116:119]
	v_mfma_f32_16x16x32_bf16 v[108:111], v[160:163], v[192:195], v[108:111]
	v_mfma_f32_16x16x32_bf16 v[108:111], v[164:167], v[196:199], v[108:111]
	v_mfma_f32_16x16x32_bf16 v[100:103], v[144:147], v[200:203], v[100:103]
	v_mfma_f32_16x16x32_bf16 v[100:103], v[156:159], v[204:207], v[100:103]
	v_mfma_f32_16x16x32_bf16 v[92:95], v[160:163], v[200:203], v[92:95]
	v_mfma_f32_16x16x32_bf16 v[92:95], v[164:167], v[204:207], v[92:95]
	v_mfma_f32_16x16x32_bf16 v[84:87], v[144:147], v[208:211], v[84:87]
	v_mfma_f32_16x16x32_bf16 v[84:87], v[156:159], v[212:215], v[84:87]
	v_mfma_f32_16x16x32_bf16 v[76:79], v[160:163], v[208:211], v[76:79]
	v_mfma_f32_16x16x32_bf16 v[76:79], v[164:167], v[212:215], v[76:79]
	s_setprio 0
	s_setprio 1
	v_mfma_f32_16x16x32_bf16 v[112:115], v[168:171], v[184:187], v[112:115]
	v_mfma_f32_16x16x32_bf16 v[112:115], v[172:175], v[188:191], v[112:115]
	v_mfma_f32_16x16x32_bf16 v[104:107], v[176:179], v[184:187], v[104:107]
	v_mfma_f32_16x16x32_bf16 v[104:107], v[180:183], v[188:191], v[104:107]
	v_mfma_f32_16x16x32_bf16 v[96:99], v[168:171], v[192:195], v[96:99]
	v_mfma_f32_16x16x32_bf16 v[96:99], v[172:175], v[196:199], v[96:99]
	v_mfma_f32_16x16x32_bf16 v[88:91], v[176:179], v[192:195], v[88:91]
	v_mfma_f32_16x16x32_bf16 v[88:91], v[180:183], v[196:199], v[88:91]
	v_mfma_f32_16x16x32_bf16 v[80:83], v[168:171], v[200:203], v[80:83]
	v_mfma_f32_16x16x32_bf16 v[80:83], v[172:175], v[204:207], v[80:83]
	v_mfma_f32_16x16x32_bf16 v[72:75], v[176:179], v[200:203], v[72:75]
	v_mfma_f32_16x16x32_bf16 v[72:75], v[180:183], v[204:207], v[72:75]
	v_mfma_f32_16x16x32_bf16 v[68:71], v[168:171], v[208:211], v[68:71]
	v_mfma_f32_16x16x32_bf16 v[68:71], v[172:175], v[212:215], v[68:71]
	v_mfma_f32_16x16x32_bf16 v[64:67], v[176:179], v[208:211], v[64:67]
	v_mfma_f32_16x16x32_bf16 v[64:67], v[180:183], v[212:215], v[64:67]
	s_setprio 0
	s_barrier
	s_add_i32 s56, s48, s31
	v_lshl_add_u64 v[216:217], s[0:1], 0, v[130:131]
	s_mov_b32 m0, s56
	ds_read_b128 v[184:187], v154 offset:16384
	ds_read_b128 v[188:191], v154 offset:17408
	ds_read_b128 v[192:195], v154 offset:18432
	ds_read_b128 v[196:199], v154 offset:19456
	ds_read_b128 v[200:203], v154 offset:20480
	ds_read_b128 v[204:207], v154 offset:21504
	ds_read_b128 v[208:211], v154 offset:22528
	ds_read_b128 v[212:215], v154 offset:23552
	global_load_lds_dwordx4 v[216:217], off
	s_add_i32 m0, s56, 0x2000
	s_add_u32 s56, s0, 0x20000
	v_lshl_add_u64 v[218:219], s[0:1], 0, v[134:135]
	s_addc_u32 s57, s1, 0
	s_add_i32 s58, s50, s31
	global_load_lds_dwordx4 v[218:219], off
	v_lshl_add_u64 v[220:221], s[56:57], 0, v[130:131]
	s_mov_b32 m0, s58
	v_lshl_add_u64 v[222:223], s[2:3], 0, v[132:133]
	global_load_lds_dwordx4 v[220:221], off
	v_lshl_add_u64 v[220:221], s[56:57], 0, v[134:135]
	s_add_i32 m0, s58, 0x2000
	s_nop 0
	global_load_lds_dwordx4 v[220:221], off
	v_lshl_add_u64 v[220:221], s[2:3], 0, v[128:129]
	s_mov_b32 m0, s27
	s_nop 0
	global_load_lds_dwordx4 v[220:221], off
	s_mov_b32 m0, s36
	s_nop 0
	global_load_lds_dwordx4 v[222:223], off
	s_waitcnt vmcnt(8)
	s_waitcnt lgkmcnt(0)
	s_barrier
; #define PG8_STAGE(bufoff, gbase, voff) do { _Pragma("unroll") for (int _i = 0; _i < 2; ++_i) \
;         __builtin_amdgcn_global_load_lds((const unsigned*)((const char*)(gbase) + (voff)[_i]), (PG8_LAS unsigned*)(lds + (bufoff) + ldsw + _i * 8192), 16, 0, 0); } while (0)
; #define PG8_LDA(dst, b, h) do { _Pragma("unroll") for (int m = 0; m < 4; ++m) _Pragma("unroll") for (int k = 0; k < 2; ++k) dst[m][k] = *(const PG8_LAS bf16x8*)(lds + PG8_SA(b, h) + aoff + m * 2048 + k * 1024); } while (0)
; #define PG8_LDB(dst, b, h) do { _Pragma("unroll") for (int n = 0; n < 2; ++n) _Pragma("unroll") for (int k = 0; k < 2; ++k) dst[n][k] = *(const PG8_LAS bf16x8*)(lds + PG8_SB(b, h) + boff + n * 2048 + k * 1024); } while (0)
; #define PG8_MMA(ai, bj, At, Bt) do { __builtin_amdgcn_s_setprio(1); _Pragma("unroll") for (int m = 0; m < 4; ++m) _Pragma("unroll") for (int n = 0; n < 2; ++n) _Pragma("unroll") for (int k = 0; k < 2; ++k) \
;         acc[ai][bj][m][n] = __builtin_amdgcn_mfma_f32_16x16x32_bf16(Bt[n][k], At[m][k], acc[ai][bj][m][n], 0, 0, 0); __builtin_amdgcn_s_setprio(0); } while (0)
; #define PG8_WAIT_V(n) asm volatile("s_waitcnt vmcnt(" #n ")" ::: "memory")
; #define PG8_WAIT_L(n) asm volatile("s_waitcnt lgkmcnt(" #n ")" ::: "memory")
; #define PG8_BAR __builtin_amdgcn_s_barrier()
; #define PG8_SCHED __builtin_amdgcn_sched_barrier(0)
; template <class Epi, class Sched, bool ALIGN_EPI = false, bool SP2 = false>
; __device__ __forceinline__ void gemm_phase(PG8_LAS unsigned char* lds, const Gemm g, const Sched& S, const Epi& E, const int tid) {
;     ...
;             PG8_WAIT_V(8); PG8_WAIT_L(0); PG8_BAR; PG8_MMA(1, 0, At, B0); PG8_MMA(1, 1, At, B1); PG8_BAR; PG8_SCHED;
;             PG8_LDB(B0, 1, 0); PG8_LDB(B1, 1, 1); PG8_SCHED; PG8_LDA(At, 1, 0); PG8_STAGE(PG8_SA(0, 1), a2 + hstep, voffA);
;             PG8_WAIT_V(8); PG8_WAIT_L(0); PG8_BAR; PG8_MMA(0, 0, At, B0); PG8_MMA(0, 1, At, B1); PG8_BAR; PG8_SCHED;
	s_setprio 1
	s_waitcnt lgkmcnt(0)
	v_mfma_f32_16x16x32_bf16 v[60:63], v[144:147], v[184:187], v[60:63]
	v_mfma_f32_16x16x32_bf16 v[60:63], v[156:159], v[188:191], v[60:63]
	v_mfma_f32_16x16x32_bf16 v[56:59], v[160:163], v[184:187], v[56:59]
	v_mfma_f32_16x16x32_bf16 v[56:59], v[164:167], v[188:191], v[56:59]
	v_mfma_f32_16x16x32_bf16 v[52:55], v[144:147], v[192:195], v[52:55]
	v_mfma_f32_16x16x32_bf16 v[52:55], v[156:159], v[196:199], v[52:55]
	v_mfma_f32_16x16x32_bf16 v[44:47], v[160:163], v[192:195], v[44:47]
	v_mfma_f32_16x16x32_bf16 v[44:47], v[164:167], v[196:199], v[44:47]
	v_mfma_f32_16x16x32_bf16 v[36:39], v[144:147], v[200:203], v[36:39]
	v_mfma_f32_16x16x32_bf16 v[36:39], v[156:159], v[204:207], v[36:39]
	v_mfma_f32_16x16x32_bf16 v[28:31], v[160:163], v[200:203], v[28:31]
	v_mfma_f32_16x16x32_bf16 v[28:31], v[164:167], v[204:207], v[28:31]
	v_mfma_f32_16x16x32_bf16 v[20:23], v[144:147], v[208:211], v[20:23]
	v_mfma_f32_16x16x32_bf16 v[20:23], v[156:159], v[212:215], v[20:23]
	v_mfma_f32_16x16x32_bf16 v[12:15], v[160:163], v[208:211], v[12:15]
	v_mfma_f32_16x16x32_bf16 v[12:15], v[164:167], v[212:215], v[12:15]
	s_setprio 0
	s_setprio 1
	v_mfma_f32_16x16x32_bf16 v[48:51], v[168:171], v[184:187], v[48:51]
	v_mfma_f32_16x16x32_bf16 v[48:51], v[172:175], v[188:191], v[48:51]
	v_mfma_f32_16x16x32_bf16 v[40:43], v[176:179], v[184:187], v[40:43]
	v_mfma_f32_16x16x32_bf16 v[40:43], v[180:183], v[188:191], v[40:43]
	v_mfma_f32_16x16x32_bf16 v[32:35], v[168:171], v[192:195], v[32:35]
	v_mfma_f32_16x16x32_bf16 v[32:35], v[172:175], v[196:199], v[32:35]
	v_mfma_f32_16x16x32_bf16 v[24:27], v[176:179], v[192:195], v[24:27]
	v_mfma_f32_16x16x32_bf16 v[24:27], v[180:183], v[196:199], v[24:27]
	v_mfma_f32_16x16x32_bf16 v[16:19], v[168:171], v[200:203], v[16:19]
	v_mfma_f32_16x16x32_bf16 v[16:19], v[172:175], v[204:207], v[16:19]
	v_mfma_f32_16x16x32_bf16 v[8:11], v[176:179], v[200:203], v[8:11]
	v_mfma_f32_16x16x32_bf16 v[8:11], v[180:183], v[204:207], v[8:11]
	v_mfma_f32_16x16x32_bf16 v[4:7], v[168:171], v[208:211], v[4:7]
	v_mfma_f32_16x16x32_bf16 v[4:7], v[172:175], v[212:215], v[4:7]
	v_mfma_f32_16x16x32_bf16 v[0:3], v[176:179], v[208:211], v[0:3]
	v_mfma_f32_16x16x32_bf16 v[0:3], v[180:183], v[212:215], v[0:3]
	s_setprio 0
	s_barrier
	s_add_i32 s56, 0, 0x18000
	v_add_u32_e32 v155, s56, v150
	s_add_i32 s57, 0, 0x1c000
	ds_read_b128 v[144:147], v155
	ds_read_b128 v[156:159], v155 offset:1024
	ds_read_b128 v[160:163], v155 offset:2048
	ds_read_b128 v[164:167], v155 offset:3072
	v_add_u32_e32 v155, s57, v150
	ds_read_b128 v[168:171], v155
	ds_read_b128 v[172:175], v155 offset:1024
	ds_read_b128 v[176:179], v155 offset:2048
	ds_read_b128 v[180:183], v155 offset:3072
	s_add_u32 s2, s2, 0x20000
	s_addc_u32 s3, s3, 0
	s_mov_b32 m0, s37
	v_lshl_add_u64 v[224:225], s[2:3], 0, v[128:129]
	ds_read_b128 v[184:187], v154 offset:32768
	ds_read_b128 v[188:191], v154 offset:33792
	ds_read_b128 v[192:195], v154 offset:34816
	ds_read_b128 v[196:199], v154 offset:35840
	ds_read_b128 v[200:203], v154 offset:36864
	ds_read_b128 v[204:207], v154 offset:37888
	ds_read_b128 v[208:211], v154 offset:38912
	ds_read_b128 v[212:215], v154 offset:39936
	global_load_lds_dwordx4 v[224:225], off
	v_lshl_add_u64 v[224:225], s[2:3], 0, v[132:133]
	s_mov_b32 m0, s38
	s_nop 0
	global_load_lds_dwordx4 v[224:225], off
	s_waitcnt vmcnt(8)
	s_waitcnt lgkmcnt(0)
	s_barrier
	s_setprio 1
	s_waitcnt lgkmcnt(0)
	v_mfma_f32_16x16x32_bf16 v[124:127], v[144:147], v[184:187], v[124:127]
	v_mfma_f32_16x16x32_bf16 v[124:127], v[156:159], v[188:191], v[124:127]
	v_mfma_f32_16x16x32_bf16 v[120:123], v[160:163], v[184:187], v[120:123]
	v_mfma_f32_16x16x32_bf16 v[120:123], v[164:167], v[188:191], v[120:123]
	v_mfma_f32_16x16x32_bf16 v[116:119], v[144:147], v[192:195], v[116:119]
	v_mfma_f32_16x16x32_bf16 v[116:119], v[156:159], v[196:199], v[116:119]
	v_mfma_f32_16x16x32_bf16 v[108:111], v[160:163], v[192:195], v[108:111]
	v_mfma_f32_16x16x32_bf16 v[108:111], v[164:167], v[196:199], v[108:111]
	v_mfma_f32_16x16x32_bf16 v[100:103], v[144:147], v[200:203], v[100:103]
	v_mfma_f32_16x16x32_bf16 v[100:103], v[156:159], v[204:207], v[100:103]
	v_mfma_f32_16x16x32_bf16 v[92:95], v[160:163], v[200:203], v[92:95]
	v_mfma_f32_16x16x32_bf16 v[92:95], v[164:167], v[204:207], v[92:95]
	v_mfma_f32_16x16x32_bf16 v[84:87], v[144:147], v[208:211], v[84:87]
	v_mfma_f32_16x16x32_bf16 v[84:87], v[156:159], v[212:215], v[84:87]
	v_mfma_f32_16x16x32_bf16 v[76:79], v[160:163], v[208:211], v[76:79]
	v_mfma_f32_16x16x32_bf16 v[76:79], v[164:167], v[212:215], v[76:79]
	s_setprio 0
	s_setprio 1
	v_mfma_f32_16x16x32_bf16 v[112:115], v[168:171], v[184:187], v[112:115]
	v_mfma_f32_16x16x32_bf16 v[112:115], v[172:175], v[188:191], v[112:115]
	v_mfma_f32_16x16x32_bf16 v[104:107], v[176:179], v[184:187], v[104:107]
	v_mfma_f32_16x16x32_bf16 v[104:107], v[180:183], v[188:191], v[104:107]
	v_mfma_f32_16x16x32_bf16 v[96:99], v[168:171], v[192:195], v[96:99]
	v_mfma_f32_16x16x32_bf16 v[96:99], v[172:175], v[196:199], v[96:99]
	v_mfma_f32_16x16x32_bf16 v[88:91], v[176:179], v[192:195], v[88:91]
	v_mfma_f32_16x16x32_bf16 v[88:91], v[180:183], v[196:199], v[88:91]
	v_mfma_f32_16x16x32_bf16 v[80:83], v[168:171], v[200:203], v[80:83]
	v_mfma_f32_16x16x32_bf16 v[80:83], v[172:175], v[204:207], v[80:83]
	v_mfma_f32_16x16x32_bf16 v[72:75], v[176:179], v[200:203], v[72:75]
	v_mfma_f32_16x16x32_bf16 v[72:75], v[180:183], v[204:207], v[72:75]
	v_mfma_f32_16x16x32_bf16 v[68:71], v[168:171], v[208:211], v[68:71]
	v_mfma_f32_16x16x32_bf16 v[68:71], v[172:175], v[212:215], v[68:71]
	v_mfma_f32_16x16x32_bf16 v[64:67], v[176:179], v[208:211], v[64:67]
	v_mfma_f32_16x16x32_bf16 v[64:67], v[180:183], v[212:215], v[64:67]
	s_setprio 0
	s_barrier
; #define PG8_STAGE(bufoff, gbase, voff) do { _Pragma("unroll") for (int _i = 0; _i < 2; ++_i) \
;         __builtin_amdgcn_global_load_lds((const unsigned*)((const char*)(gbase) + (voff)[_i]), (PG8_LAS unsigned*)(lds + (bufoff) + ldsw + _i * 8192), 16, 0, 0); } while (0)
; #define PG8_LDA(dst, b, h) do { _Pragma("unroll") for (int m = 0; m < 4; ++m) _Pragma("unroll") for (int k = 0; k < 2; ++k) dst[m][k] = *(const PG8_LAS bf16x8*)(lds + PG8_SA(b, h) + aoff + m * 2048 + k * 1024); } while (0)
; #define PG8_BAR __builtin_amdgcn_s_barrier()
; template <class Epi, class Sched, bool ALIGN_EPI = false, bool SP2 = false>
; __device__ __forceinline__ void gemm_phase(PG8_LAS unsigned char* lds, const Gemm g, const Sched& S, const Epi& E, const int tid) {
;     ...
;             PG8_LDA(At, 1, 1); PG8_STAGE(PG8_SB(1, 0), b3, voffB); PG8_STAGE(PG8_SB(1, 1), b3 + hstep, voffB); PG8_STAGE(PG8_SA(1, 0), a3, voffA);
;             PG8_WAIT_V(8); PG8_WAIT_L(0); PG8_BAR; PG8_MMA(1, 0, At, B0); PG8_MMA(1, 1, At, B1); PG8_BAR; PG8_SCHED;
;             } else {
;             PG8_LDB(B0, 0, 0); PG8_SCHED; PG8_LDA(At, 0, 0); PG8_STAGE(PG8_SA(1, 1), a1 + hstep, voffA);
;             PG8_WAIT_L(8); PG8_BAR; PG8_WAIT_L(0); PG8_MMA(0, 0, At, B0); PG8_BAR; PG8_SCHED;
;             PG8_LDB(B1, 0, 1); PG8_STAGE(PG8_SB(0, 0), b2, voffB);
;             PG8_BAR; PG8_WAIT_L(0); PG8_MMA(0, 1, At, B1); PG8_BAR;
;             PG8_LDA(At, 0, 1); PG8_STAGE(PG8_SA(0, 0), a2, voffA);
;             PG8_BAR; PG8_WAIT_L(0); PG8_MMA(1, 0, At, B0); PG8_BAR; PG8_SCHED;
;             PG8_STAGE(PG8_SB(0, 1), b2 + hstep, voffB);
;             PG8_WAIT_V(6); PG8_BAR; PG8_MMA(1, 1, At, B1); PG8_BAR;
;             PG8_LDB(B0, 1, 0); PG8_SCHED; PG8_LDA(At, 1, 0); PG8_STAGE(PG8_SA(0, 1), a2 + hstep, voffA);
;             PG8_WAIT_L(8); PG8_BAR; PG8_WAIT_L(0); PG8_MMA(0, 0, At, B0); PG8_BAR; PG8_SCHED;
;             PG8_LDB(B1, 1, 1); PG8_STAGE(PG8_SB(1, 0), b3, voffB);
;             PG8_BAR; PG8_WAIT_L(0); PG8_MMA(0, 1, At, B1); PG8_BAR;
;             PG8_LDA(At, 1, 1); PG8_STAGE(PG8_SA(1, 0), a3, voffA);
;             PG8_BAR; PG8_WAIT_L(0); PG8_MMA(1, 0, At, B0); PG8_BAR; PG8_SCHED;
;             PG8_STAGE(PG8_SB(1, 1), b3 + hstep, voffB);
;             PG8_WAIT_V(6); PG8_BAR; PG8_MMA(1, 1, At, B1); PG8_BAR;
;             }
;         }
;         if constexpr (ALIGN_EPI) { if (wr == 0) PG8_BAR; }
	s_add_i32 s2, s56, s31
	v_lshl_add_u64 v[216:217], v[216:217], 0, s[10:11]
	s_mov_b32 m0, s2
	ds_read_b128 v[184:187], v154 offset:49152
	ds_read_b128 v[188:191], v154 offset:50176
	ds_read_b128 v[192:195], v154 offset:51200
	ds_read_b128 v[196:199], v154 offset:52224
	ds_read_b128 v[200:203], v154 offset:53248
	ds_read_b128 v[204:207], v154 offset:54272
	ds_read_b128 v[208:211], v154 offset:55296
	ds_read_b128 v[212:215], v154 offset:56320
	global_load_lds_dwordx4 v[216:217], off
	s_add_i32 m0, s2, 0x2000
	s_add_u32 s0, s0, 0x20080
	v_lshl_add_u64 v[216:217], v[218:219], 0, s[10:11]
	s_addc_u32 s1, s1, 0
	s_add_i32 s2, s57, s31
	global_load_lds_dwordx4 v[216:217], off
	v_lshl_add_u64 v[216:217], s[0:1], 0, v[130:131]
	s_mov_b32 m0, s2
	s_nop 0
	global_load_lds_dwordx4 v[216:217], off
	v_lshl_add_u64 v[216:217], s[0:1], 0, v[134:135]
	s_add_i32 m0, s2, 0x2000
	s_nop 0
	global_load_lds_dwordx4 v[216:217], off
	v_lshl_add_u64 v[216:217], v[220:221], 0, s[10:11]
	s_mov_b32 m0, s41
	s_nop 0
	global_load_lds_dwordx4 v[216:217], off
	v_lshl_add_u64 v[216:217], v[222:223], 0, s[10:11]
	s_mov_b32 m0, s42
	s_nop 0
	global_load_lds_dwordx4 v[216:217], off
	s_waitcnt vmcnt(8)
	s_waitcnt lgkmcnt(0)
	s_barrier
	s_setprio 1
	s_waitcnt lgkmcnt(0)
	v_mfma_f32_16x16x32_bf16 v[60:63], v[144:147], v[184:187], v[60:63]
	v_mfma_f32_16x16x32_bf16 v[60:63], v[156:159], v[188:191], v[60:63]
	v_mfma_f32_16x16x32_bf16 v[56:59], v[160:163], v[184:187], v[56:59]
	v_mfma_f32_16x16x32_bf16 v[56:59], v[164:167], v[188:191], v[56:59]
	v_mfma_f32_16x16x32_bf16 v[52:55], v[144:147], v[192:195], v[52:55]
	v_mfma_f32_16x16x32_bf16 v[52:55], v[156:159], v[196:199], v[52:55]
	v_mfma_f32_16x16x32_bf16 v[44:47], v[160:163], v[192:195], v[44:47]
	v_mfma_f32_16x16x32_bf16 v[44:47], v[164:167], v[196:199], v[44:47]
	v_mfma_f32_16x16x32_bf16 v[36:39], v[144:147], v[200:203], v[36:39]
	v_mfma_f32_16x16x32_bf16 v[36:39], v[156:159], v[204:207], v[36:39]
	v_mfma_f32_16x16x32_bf16 v[28:31], v[160:163], v[200:203], v[28:31]
	v_mfma_f32_16x16x32_bf16 v[28:31], v[164:167], v[204:207], v[28:31]
	v_mfma_f32_16x16x32_bf16 v[20:23], v[144:147], v[208:211], v[20:23]
	v_mfma_f32_16x16x32_bf16 v[20:23], v[156:159], v[212:215], v[20:23]
	v_mfma_f32_16x16x32_bf16 v[12:15], v[160:163], v[208:211], v[12:15]
	v_mfma_f32_16x16x32_bf16 v[12:15], v[164:167], v[212:215], v[12:15]
	s_setprio 0
	s_setprio 1
	v_mfma_f32_16x16x32_bf16 v[48:51], v[168:171], v[184:187], v[48:51]
	v_mfma_f32_16x16x32_bf16 v[48:51], v[172:175], v[188:191], v[48:51]
	v_mfma_f32_16x16x32_bf16 v[40:43], v[176:179], v[184:187], v[40:43]
	v_mfma_f32_16x16x32_bf16 v[40:43], v[180:183], v[188:191], v[40:43]
	v_mfma_f32_16x16x32_bf16 v[32:35], v[168:171], v[192:195], v[32:35]
	v_mfma_f32_16x16x32_bf16 v[32:35], v[172:175], v[196:199], v[32:35]
	v_mfma_f32_16x16x32_bf16 v[24:27], v[176:179], v[192:195], v[24:27]
	v_mfma_f32_16x16x32_bf16 v[24:27], v[180:183], v[196:199], v[24:27]
	v_mfma_f32_16x16x32_bf16 v[16:19], v[168:171], v[200:203], v[16:19]
	v_mfma_f32_16x16x32_bf16 v[16:19], v[172:175], v[204:207], v[16:19]
	v_mfma_f32_16x16x32_bf16 v[8:11], v[176:179], v[200:203], v[8:11]
	v_mfma_f32_16x16x32_bf16 v[8:11], v[180:183], v[204:207], v[8:11]
	v_mfma_f32_16x16x32_bf16 v[4:7], v[168:171], v[208:211], v[4:7]
	v_mfma_f32_16x16x32_bf16 v[4:7], v[172:175], v[212:215], v[4:7]
	v_mfma_f32_16x16x32_bf16 v[0:3], v[176:179], v[208:211], v[0:3]
	v_mfma_f32_16x16x32_bf16 v[0:3], v[180:183], v[212:215], v[0:3]
	s_setprio 0
	s_barrier
	s_add_i32 s55, s55, 2
	s_add_u32 s28, s28, 0x100
	s_addc_u32 s29, s29, 0
	s_add_u32 s53, s53, 0x100
	s_addc_u32 s54, s54, 0
	s_cmp_gt_u32 s55, 5
	s_cbranch_scc0 .LBB0_252
	s_and_b64 vcc, exec, s[16:17]
	s_cbranch_vccz .LBB0_255
	s_barrier

; #define PG8_STAGE(bufoff, gbase, voff) do { _Pragma("unroll") for (int _i = 0; _i < 2; ++_i) \
;         __builtin_amdgcn_global_load_lds((const unsigned*)((const char*)(gbase) + (voff)[_i]), (PG8_LAS unsigned*)(lds + (bufoff) + ldsw + _i * 8192), 16, 0, 0); } while (0)
; #define PG8_LDA(dst, b, h) do { _Pragma("unroll") for (int m = 0; m < 4; ++m) _Pragma("unroll") for (int k = 0; k < 2; ++k) dst[m][k] = *(const PG8_LAS bf16x8*)(lds + PG8_SA(b, h) + aoff + m * 2048 + k * 1024); } while (0)
; #define PG8_LDB(dst, b, h) do { _Pragma("unroll") for (int n = 0; n < 2; ++n) _Pragma("unroll") for (int k = 0; k < 2; ++k) dst[n][k] = *(const PG8_LAS bf16x8*)(lds + PG8_SB(b, h) + boff + n * 2048 + k * 1024); } while (0)
; #define PG8_WAIT_V(n) asm volatile("s_waitcnt vmcnt(" #n ")" ::: "memory")
; #define PG8_WAIT_L(n) asm volatile("s_waitcnt lgkmcnt(" #n ")" ::: "memory")
; #define PG8_BAR __builtin_amdgcn_s_barrier()
; #define PG8_SCHED __builtin_amdgcn_sched_barrier(0)
; template <class Epi, class Sched, bool ALIGN_EPI = false, bool SP2 = false>
; __device__ __forceinline__ void gemm_phase(PG8_LAS unsigned char* lds, const Gemm g, const Sched& S, const Epi& E, const int tid) {
;     ...
;         const bool has_next = S.next(ui + 1, nxt);
;         const char* nA = has_next ? (const char*)g.A + (size_t)nxt.pm * tstep : cA; const char* nB = has_next ? (const char*)g.Bt + (size_t)nxt.pn * tstep : cB;
;         for (int t = 0; t < nt; t += 2) {
;             const bool last = (t == nt - 2);
;             const char* a1 = cA + (size_t)(t + 1) * kstep;
;             const char* a2 = last ? nA : cA + (size_t)(t + 2) * kstep; const char* b2 = last ? nB : cB + (size_t)(t + 2) * kstep;
;             const char* a3 = a2 + kstep; const char* b3 = b2 + kstep;
;             if (last && has_next) S.a_ready(nxt);
;             if constexpr (SP2) {
;             PG8_LDB(B0, 0, 0); PG8_LDB(B1, 0, 1); PG8_SCHED; PG8_LDA(At, 0, 0); PG8_STAGE(PG8_SA(1, 1), a1 + hstep, voffA);
;             PG8_WAIT_V(8); PG8_WAIT_L(0); PG8_BAR; PG8_MMA(0, 0, At, B0); PG8_MMA(0, 1, At, B1); PG8_BAR; PG8_SCHED;
;             PG8_LDA(At, 0, 1); PG8_STAGE(PG8_SB(0, 0), b2, voffB); PG8_STAGE(PG8_SB(0, 1), b2 + hstep, voffB); PG8_STAGE(PG8_SA(0, 0), a2, voffA);
;             PG8_WAIT_V(8); PG8_WAIT_L(0); PG8_BAR; PG8_MMA(1, 0, At, B0); PG8_MMA(1, 1, At, B1); PG8_BAR; PG8_SCHED;
.LBB0_268:
	s_add_u32 s36, s28, s0
	s_addc_u32 s37, s29, 0
	s_add_u32 s1, s36, 0x100
	s_addc_u32 s4, s37, 0
	s_and_b64 s[2:3], s[34:35], exec
	s_cselect_b32 s3, s19, s4
	s_cselect_b32 s2, s61, s1
	s_add_u32 s0, s26, s0
	s_addc_u32 s1, s27, 0
	s_add_u32 s4, s0, 0x100
	s_addc_u32 s5, s1, 0
	s_and_b64 s[0:1], s[34:35], exec
	s_cselect_b32 s5, s17, s5
	s_cselect_b32 s4, s62, s4
	s_add_u32 s38, s36, 0x10080
	ds_read_b128 v[150:153], v145
	ds_read_b128 v[154:157], v145 offset:1024
	ds_read_b128 v[158:161], v145 offset:2048
	ds_read_b128 v[162:165], v145 offset:3072
	ds_read_b128 v[166:169], v146
	ds_read_b128 v[170:173], v146 offset:1024
	ds_read_b128 v[174:177], v146 offset:2048
	ds_read_b128 v[178:181], v146 offset:3072
	s_addc_u32 s39, s37, 0
	s_add_i32 s76, s58, s41
	s_add_i32 m0, s25, 0xc000
	s_add_i32 s77, s25, 0xe000
	s_add_i32 s69, s76, 0x2000
	s_add_u32 s36, s4, 0x10000
	s_addc_u32 s37, s5, 0
	s_add_i32 s75, s59, s41
	s_add_i32 s74, s75, 0x2000
	s_add_i32 s68, 0, 0x18000
	s_add_i32 s67, 0, 0x1c000
	s_add_u32 s0, s2, 0x10000
	s_addc_u32 s1, s3, 0
	s_add_i32 s66, s68, s41
	s_add_i32 s64, s66, 0x2000
	s_add_u32 s34, s4, 0x10080
	s_addc_u32 s35, s5, 0
	s_add_i32 s65, s67, s41
	s_add_i32 s63, s65, 0x2000
	v_lshl_add_u64 v[140:141], s[38:39], 0, v[134:135]
	ds_read_b128 v[182:185], v147
	ds_read_b128 v[186:189], v147 offset:1024
	ds_read_b128 v[190:193], v147 offset:2048
	ds_read_b128 v[194:197], v147 offset:3072
	ds_read_b128 v[198:201], v147 offset:4096
	ds_read_b128 v[202:205], v147 offset:5120
	ds_read_b128 v[206:209], v147 offset:6144
	ds_read_b128 v[210:213], v147 offset:7168
	global_load_lds_dwordx4 v[140:141], off
	v_lshl_add_u64 v[140:141], s[38:39], 0, v[130:131]
	s_mov_b32 m0, s77
	s_nop 0
	global_load_lds_dwordx4 v[140:141], off
	s_waitcnt vmcnt(8)
	s_waitcnt lgkmcnt(0)
	s_barrier
	s_setprio 1
	s_waitcnt lgkmcnt(0)
	v_mfma_f32_16x16x32_bf16 v[124:127], v[150:153], v[182:185], v[124:127]
	v_mfma_f32_16x16x32_bf16 v[124:127], v[154:157], v[186:189], v[124:127]
	v_mfma_f32_16x16x32_bf16 v[120:123], v[158:161], v[182:185], v[120:123]
	v_mfma_f32_16x16x32_bf16 v[120:123], v[162:165], v[186:189], v[120:123]
	v_mfma_f32_16x16x32_bf16 v[116:119], v[150:153], v[190:193], v[116:119]
	v_mfma_f32_16x16x32_bf16 v[116:119], v[154:157], v[194:197], v[116:119]
	v_mfma_f32_16x16x32_bf16 v[108:111], v[158:161], v[190:193], v[108:111]
	v_mfma_f32_16x16x32_bf16 v[108:111], v[162:165], v[194:197], v[108:111]
	v_mfma_f32_16x16x32_bf16 v[100:103], v[150:153], v[198:201], v[100:103]
	v_mfma_f32_16x16x32_bf16 v[100:103], v[154:157], v[202:205], v[100:103]
	v_mfma_f32_16x16x32_bf16 v[92:95], v[158:161], v[198:201], v[92:95]
	v_mfma_f32_16x16x32_bf16 v[92:95], v[162:165], v[202:205], v[92:95]
	v_mfma_f32_16x16x32_bf16 v[80:83], v[150:153], v[206:209], v[80:83]
	v_mfma_f32_16x16x32_bf16 v[80:83], v[154:157], v[210:213], v[80:83]
	v_mfma_f32_16x16x32_bf16 v[72:75], v[158:161], v[206:209], v[72:75]
	v_mfma_f32_16x16x32_bf16 v[72:75], v[162:165], v[210:213], v[72:75]
	s_setprio 0
	s_setprio 1
	v_mfma_f32_16x16x32_bf16 v[112:115], v[166:169], v[182:185], v[112:115]
	v_mfma_f32_16x16x32_bf16 v[112:115], v[170:173], v[186:189], v[112:115]
	v_mfma_f32_16x16x32_bf16 v[104:107], v[174:177], v[182:185], v[104:107]
	v_mfma_f32_16x16x32_bf16 v[104:107], v[178:181], v[186:189], v[104:107]
	v_mfma_f32_16x16x32_bf16 v[96:99], v[166:169], v[190:193], v[96:99]
	v_mfma_f32_16x16x32_bf16 v[96:99], v[170:173], v[194:197], v[96:99]
	v_mfma_f32_16x16x32_bf16 v[88:91], v[174:177], v[190:193], v[88:91]
	v_mfma_f32_16x16x32_bf16 v[88:91], v[178:181], v[194:197], v[88:91]
	v_mfma_f32_16x16x32_bf16 v[84:87], v[166:169], v[198:201], v[84:87]
	v_mfma_f32_16x16x32_bf16 v[84:87], v[170:173], v[202:205], v[84:87]
	v_mfma_f32_16x16x32_bf16 v[76:79], v[174:177], v[198:201], v[76:79]
	v_mfma_f32_16x16x32_bf16 v[76:79], v[178:181], v[202:205], v[76:79]
	v_mfma_f32_16x16x32_bf16 v[68:71], v[166:169], v[206:209], v[68:71]
	v_mfma_f32_16x16x32_bf16 v[68:71], v[170:173], v[210:213], v[68:71]
	v_mfma_f32_16x16x32_bf16 v[64:67], v[174:177], v[206:209], v[64:67]
	v_mfma_f32_16x16x32_bf16 v[64:67], v[178:181], v[210:213], v[64:67]
	s_setprio 0
	s_barrier
	s_mov_b32 m0, s76
	v_lshl_add_u64 v[140:141], s[4:5], 0, v[132:133]
	ds_read_b128 v[182:185], v147 offset:16384
	ds_read_b128 v[186:189], v147 offset:17408
	ds_read_b128 v[190:193], v147 offset:18432
	ds_read_b128 v[194:197], v147 offset:19456
	ds_read_b128 v[198:201], v147 offset:20480
	ds_read_b128 v[202:205], v147 offset:21504
	ds_read_b128 v[206:209], v147 offset:22528
	ds_read_b128 v[210:213], v147 offset:23552
	global_load_lds_dwordx4 v[140:141], off
	v_lshl_add_u64 v[214:215], s[4:5], 0, v[128:129]
	s_mov_b32 m0, s69
	v_lshl_add_u64 v[216:217], s[36:37], 0, v[132:133]
	global_load_lds_dwordx4 v[214:215], off
	s_mov_b32 m0, s75
	v_lshl_add_u64 v[218:219], s[2:3], 0, v[130:131]
	global_load_lds_dwordx4 v[216:217], off
	v_lshl_add_u64 v[216:217], s[36:37], 0, v[128:129]
	s_mov_b32 m0, s74
	s_nop 0
	global_load_lds_dwordx4 v[216:217], off
	v_lshl_add_u64 v[216:217], s[2:3], 0, v[134:135]
	s_mov_b32 m0, s25
	s_nop 0
	global_load_lds_dwordx4 v[216:217], off
	s_mov_b32 m0, s50
	s_nop 0
	global_load_lds_dwordx4 v[218:219], off
	s_waitcnt vmcnt(8)
	s_waitcnt lgkmcnt(0)
	s_barrier
; #define PG8_STAGE(bufoff, gbase, voff) do { _Pragma("unroll") for (int _i = 0; _i < 2; ++_i) \
;         __builtin_amdgcn_global_load_lds((const unsigned*)((const char*)(gbase) + (voff)[_i]), (PG8_LAS unsigned*)(lds + (bufoff) + ldsw + _i * 8192), 16, 0, 0); } while (0)
; #define PG8_LDA(dst, b, h) do { _Pragma("unroll") for (int m = 0; m < 4; ++m) _Pragma("unroll") for (int k = 0; k < 2; ++k) dst[m][k] = *(const PG8_LAS bf16x8*)(lds + PG8_SA(b, h) + aoff + m * 2048 + k * 1024); } while (0)
; #define PG8_LDB(dst, b, h) do { _Pragma("unroll") for (int n = 0; n < 2; ++n) _Pragma("unroll") for (int k = 0; k < 2; ++k) dst[n][k] = *(const PG8_LAS bf16x8*)(lds + PG8_SB(b, h) + boff + n * 2048 + k * 1024); } while (0)
; #define PG8_MMA(ai, bj, At, Bt) do { __builtin_amdgcn_s_setprio(1); _Pragma("unroll") for (int m = 0; m < 4; ++m) _Pragma("unroll") for (int n = 0; n < 2; ++n) _Pragma("unroll") for (int k = 0; k < 2; ++k) \
;         acc[ai][bj][m][n] = __builtin_amdgcn_mfma_f32_16x16x32_bf16(Bt[n][k], At[m][k], acc[ai][bj][m][n], 0, 0, 0); __builtin_amdgcn_s_setprio(0); } while (0)
; #define PG8_WAIT_V(n) asm volatile("s_waitcnt vmcnt(" #n ")" ::: "memory")
; #define PG8_WAIT_L(n) asm volatile("s_waitcnt lgkmcnt(" #n ")" ::: "memory")
; #define PG8_BAR __builtin_amdgcn_s_barrier()
; #define PG8_SCHED __builtin_amdgcn_sched_barrier(0)
; template <class Epi, class Sched, bool ALIGN_EPI = false, bool SP2 = false>
; __device__ __forceinline__ void gemm_phase(PG8_LAS unsigned char* lds, const Gemm g, const Sched& S, const Epi& E, const int tid) {
;     ...
;             PG8_WAIT_V(8); PG8_WAIT_L(0); PG8_BAR; PG8_MMA(1, 0, At, B0); PG8_MMA(1, 1, At, B1); PG8_BAR; PG8_SCHED;
;             PG8_LDB(B0, 1, 0); PG8_LDB(B1, 1, 1); PG8_SCHED; PG8_LDA(At, 1, 0); PG8_STAGE(PG8_SA(0, 1), a2 + hstep, voffA);
;             PG8_WAIT_V(8); PG8_WAIT_L(0); PG8_BAR; PG8_MMA(0, 0, At, B0); PG8_MMA(0, 1, At, B1); PG8_BAR; PG8_SCHED;
	s_setprio 1
	s_waitcnt lgkmcnt(0)
	v_mfma_f32_16x16x32_bf16 v[60:63], v[150:153], v[182:185], v[60:63]
	v_mfma_f32_16x16x32_bf16 v[60:63], v[154:157], v[186:189], v[60:63]
	v_mfma_f32_16x16x32_bf16 v[56:59], v[158:161], v[182:185], v[56:59]
	v_mfma_f32_16x16x32_bf16 v[56:59], v[162:165], v[186:189], v[56:59]
	v_mfma_f32_16x16x32_bf16 v[52:55], v[150:153], v[190:193], v[52:55]
	v_mfma_f32_16x16x32_bf16 v[52:55], v[154:157], v[194:197], v[52:55]
	v_mfma_f32_16x16x32_bf16 v[44:47], v[158:161], v[190:193], v[44:47]
	v_mfma_f32_16x16x32_bf16 v[44:47], v[162:165], v[194:197], v[44:47]
	v_mfma_f32_16x16x32_bf16 v[36:39], v[150:153], v[198:201], v[36:39]
	v_mfma_f32_16x16x32_bf16 v[36:39], v[154:157], v[202:205], v[36:39]
	v_mfma_f32_16x16x32_bf16 v[28:31], v[158:161], v[198:201], v[28:31]
	v_mfma_f32_16x16x32_bf16 v[28:31], v[162:165], v[202:205], v[28:31]
	v_mfma_f32_16x16x32_bf16 v[20:23], v[150:153], v[206:209], v[20:23]
	v_mfma_f32_16x16x32_bf16 v[20:23], v[154:157], v[210:213], v[20:23]
	v_mfma_f32_16x16x32_bf16 v[12:15], v[158:161], v[206:209], v[12:15]
	v_mfma_f32_16x16x32_bf16 v[12:15], v[162:165], v[210:213], v[12:15]
	s_setprio 0
	s_setprio 1
	v_mfma_f32_16x16x32_bf16 v[48:51], v[166:169], v[182:185], v[48:51]
	v_mfma_f32_16x16x32_bf16 v[48:51], v[170:173], v[186:189], v[48:51]
	v_mfma_f32_16x16x32_bf16 v[40:43], v[174:177], v[182:185], v[40:43]
	v_mfma_f32_16x16x32_bf16 v[40:43], v[178:181], v[186:189], v[40:43]
	v_mfma_f32_16x16x32_bf16 v[32:35], v[166:169], v[190:193], v[32:35]
	v_mfma_f32_16x16x32_bf16 v[32:35], v[170:173], v[194:197], v[32:35]
	v_mfma_f32_16x16x32_bf16 v[24:27], v[174:177], v[190:193], v[24:27]
	v_mfma_f32_16x16x32_bf16 v[24:27], v[178:181], v[194:197], v[24:27]
	v_mfma_f32_16x16x32_bf16 v[16:19], v[166:169], v[198:201], v[16:19]
	v_mfma_f32_16x16x32_bf16 v[16:19], v[170:173], v[202:205], v[16:19]
	v_mfma_f32_16x16x32_bf16 v[8:11], v[174:177], v[198:201], v[8:11]
	v_mfma_f32_16x16x32_bf16 v[8:11], v[178:181], v[202:205], v[8:11]
	v_mfma_f32_16x16x32_bf16 v[4:7], v[166:169], v[206:209], v[4:7]
	v_mfma_f32_16x16x32_bf16 v[4:7], v[170:173], v[210:213], v[4:7]
	v_mfma_f32_16x16x32_bf16 v[0:3], v[174:177], v[206:209], v[0:3]
	v_mfma_f32_16x16x32_bf16 v[0:3], v[178:181], v[210:213], v[0:3]
	s_setprio 0
	s_barrier
	v_add_u32_e32 v149, s68, v143
	ds_read_b128 v[150:153], v149
	ds_read_b128 v[154:157], v149 offset:1024
	ds_read_b128 v[158:161], v149 offset:2048
	ds_read_b128 v[162:165], v149 offset:3072
	v_add_u32_e32 v149, s67, v143
	ds_read_b128 v[166:169], v149
	ds_read_b128 v[170:173], v149 offset:1024
	ds_read_b128 v[174:177], v149 offset:2048
	ds_read_b128 v[178:181], v149 offset:3072
	s_mov_b32 m0, s51
	v_lshl_add_u64 v[220:221], s[0:1], 0, v[134:135]
	ds_read_b128 v[182:185], v147 offset:32768
	ds_read_b128 v[186:189], v147 offset:33792
	ds_read_b128 v[190:193], v147 offset:34816
	ds_read_b128 v[194:197], v147 offset:35840
	ds_read_b128 v[198:201], v147 offset:36864
	ds_read_b128 v[202:205], v147 offset:37888
	ds_read_b128 v[206:209], v147 offset:38912
	ds_read_b128 v[210:213], v147 offset:39936
	global_load_lds_dwordx4 v[220:221], off
	v_lshl_add_u64 v[220:221], s[0:1], 0, v[130:131]
	s_mov_b32 m0, s52
	s_nop 0
	global_load_lds_dwordx4 v[220:221], off
	s_waitcnt vmcnt(8)
	s_waitcnt lgkmcnt(0)
	s_barrier
	s_setprio 1
	s_waitcnt lgkmcnt(0)
	v_mfma_f32_16x16x32_bf16 v[124:127], v[150:153], v[182:185], v[124:127]
	v_mfma_f32_16x16x32_bf16 v[124:127], v[154:157], v[186:189], v[124:127]
	v_mfma_f32_16x16x32_bf16 v[120:123], v[158:161], v[182:185], v[120:123]
	v_mfma_f32_16x16x32_bf16 v[120:123], v[162:165], v[186:189], v[120:123]
	v_mfma_f32_16x16x32_bf16 v[116:119], v[150:153], v[190:193], v[116:119]
	v_mfma_f32_16x16x32_bf16 v[116:119], v[154:157], v[194:197], v[116:119]
	v_mfma_f32_16x16x32_bf16 v[108:111], v[158:161], v[190:193], v[108:111]
	v_mfma_f32_16x16x32_bf16 v[108:111], v[162:165], v[194:197], v[108:111]
	v_mfma_f32_16x16x32_bf16 v[100:103], v[150:153], v[198:201], v[100:103]
	v_mfma_f32_16x16x32_bf16 v[100:103], v[154:157], v[202:205], v[100:103]
	v_mfma_f32_16x16x32_bf16 v[92:95], v[158:161], v[198:201], v[92:95]
	v_mfma_f32_16x16x32_bf16 v[92:95], v[162:165], v[202:205], v[92:95]
	v_mfma_f32_16x16x32_bf16 v[80:83], v[150:153], v[206:209], v[80:83]
	v_mfma_f32_16x16x32_bf16 v[80:83], v[154:157], v[210:213], v[80:83]
	v_mfma_f32_16x16x32_bf16 v[72:75], v[158:161], v[206:209], v[72:75]
	v_mfma_f32_16x16x32_bf16 v[72:75], v[162:165], v[210:213], v[72:75]
	s_setprio 0
	s_setprio 1
	v_mfma_f32_16x16x32_bf16 v[112:115], v[166:169], v[182:185], v[112:115]
	v_mfma_f32_16x16x32_bf16 v[112:115], v[170:173], v[186:189], v[112:115]
	v_mfma_f32_16x16x32_bf16 v[104:107], v[174:177], v[182:185], v[104:107]
	v_mfma_f32_16x16x32_bf16 v[104:107], v[178:181], v[186:189], v[104:107]
	v_mfma_f32_16x16x32_bf16 v[96:99], v[166:169], v[190:193], v[96:99]
	v_mfma_f32_16x16x32_bf16 v[96:99], v[170:173], v[194:197], v[96:99]
	v_mfma_f32_16x16x32_bf16 v[88:91], v[174:177], v[190:193], v[88:91]
	v_mfma_f32_16x16x32_bf16 v[88:91], v[178:181], v[194:197], v[88:91]
	v_mfma_f32_16x16x32_bf16 v[84:87], v[166:169], v[198:201], v[84:87]
	v_mfma_f32_16x16x32_bf16 v[84:87], v[170:173], v[202:205], v[84:87]
	v_mfma_f32_16x16x32_bf16 v[76:79], v[174:177], v[198:201], v[76:79]
	v_mfma_f32_16x16x32_bf16 v[76:79], v[178:181], v[202:205], v[76:79]
	v_mfma_f32_16x16x32_bf16 v[68:71], v[166:169], v[206:209], v[68:71]
	v_mfma_f32_16x16x32_bf16 v[68:71], v[170:173], v[210:213], v[68:71]
	v_mfma_f32_16x16x32_bf16 v[64:67], v[174:177], v[206:209], v[64:67]
	v_mfma_f32_16x16x32_bf16 v[64:67], v[178:181], v[210:213], v[64:67]
	s_setprio 0
	s_barrier
; #define PG8_STAGE(bufoff, gbase, voff) do { _Pragma("unroll") for (int _i = 0; _i < 2; ++_i) \
;         __builtin_amdgcn_global_load_lds((const unsigned*)((const char*)(gbase) + (voff)[_i]), (PG8_LAS unsigned*)(lds + (bufoff) + ldsw + _i * 8192), 16, 0, 0); } while (0)
; #define PG8_LDA(dst, b, h) do { _Pragma("unroll") for (int m = 0; m < 4; ++m) _Pragma("unroll") for (int k = 0; k < 2; ++k) dst[m][k] = *(const PG8_LAS bf16x8*)(lds + PG8_SA(b, h) + aoff + m * 2048 + k * 1024); } while (0)
; #define PG8_BAR __builtin_amdgcn_s_barrier()
; template <class Epi, class Sched, bool ALIGN_EPI = false, bool SP2 = false>
; __device__ __forceinline__ void gemm_phase(PG8_LAS unsigned char* lds, const Gemm g, const Sched& S, const Epi& E, const int tid) {
;     ...
;             PG8_LDA(At, 1, 1); PG8_STAGE(PG8_SB(1, 0), b3, voffB); PG8_STAGE(PG8_SB(1, 1), b3 + hstep, voffB); PG8_STAGE(PG8_SA(1, 0), a3, voffA);
;             PG8_WAIT_V(8); PG8_WAIT_L(0); PG8_BAR; PG8_MMA(1, 0, At, B0); PG8_MMA(1, 1, At, B1); PG8_BAR; PG8_SCHED;
;             } else {
;             PG8_LDB(B0, 0, 0); PG8_SCHED; PG8_LDA(At, 0, 0); PG8_STAGE(PG8_SA(1, 1), a1 + hstep, voffA);
;             PG8_WAIT_L(8); PG8_BAR; PG8_WAIT_L(0); PG8_MMA(0, 0, At, B0); PG8_BAR; PG8_SCHED;
;             PG8_LDB(B1, 0, 1); PG8_STAGE(PG8_SB(0, 0), b2, voffB);
;             PG8_BAR; PG8_WAIT_L(0); PG8_MMA(0, 1, At, B1); PG8_BAR;
;             PG8_LDA(At, 0, 1); PG8_STAGE(PG8_SA(0, 0), a2, voffA);
;             PG8_BAR; PG8_WAIT_L(0); PG8_MMA(1, 0, At, B0); PG8_BAR; PG8_SCHED;
;             PG8_STAGE(PG8_SB(0, 1), b2 + hstep, voffB);
;             PG8_WAIT_V(6); PG8_BAR; PG8_MMA(1, 1, At, B1); PG8_BAR;
;             PG8_LDB(B0, 1, 0); PG8_SCHED; PG8_LDA(At, 1, 0); PG8_STAGE(PG8_SA(0, 1), a2 + hstep, voffA);
;             PG8_WAIT_L(8); PG8_BAR; PG8_WAIT_L(0); PG8_MMA(0, 0, At, B0); PG8_BAR; PG8_SCHED;
;             PG8_LDB(B1, 1, 1); PG8_STAGE(PG8_SB(1, 0), b3, voffB);
;             PG8_BAR; PG8_WAIT_L(0); PG8_MMA(0, 1, At, B1); PG8_BAR;
;             PG8_LDA(At, 1, 1); PG8_STAGE(PG8_SA(1, 0), a3, voffA);
;             PG8_BAR; PG8_WAIT_L(0); PG8_MMA(1, 0, At, B0); PG8_BAR; PG8_SCHED;
;             PG8_STAGE(PG8_SB(1, 1), b3 + hstep, voffB);
;             PG8_WAIT_V(6); PG8_BAR; PG8_MMA(1, 1, At, B1); PG8_BAR;
;             }
;         }
;         if constexpr (ALIGN_EPI) { if (wr == 0) PG8_BAR; }
	s_mov_b32 m0, s66
	v_lshl_add_u64 v[140:141], v[140:141], 0, s[10:11]
	ds_read_b128 v[182:185], v147 offset:49152
	ds_read_b128 v[186:189], v147 offset:50176
	ds_read_b128 v[190:193], v147 offset:51200
	ds_read_b128 v[194:197], v147 offset:52224
	ds_read_b128 v[198:201], v147 offset:53248
	ds_read_b128 v[202:205], v147 offset:54272
	ds_read_b128 v[206:209], v147 offset:55296
	ds_read_b128 v[210:213], v147 offset:56320
	global_load_lds_dwordx4 v[140:141], off
	v_lshl_add_u64 v[140:141], v[214:215], 0, s[10:11]
	s_mov_b32 m0, s64
	s_nop 0
	global_load_lds_dwordx4 v[140:141], off
	v_lshl_add_u64 v[140:141], s[34:35], 0, v[132:133]
	s_mov_b32 m0, s65
	s_nop 0
	global_load_lds_dwordx4 v[140:141], off
	v_lshl_add_u64 v[140:141], s[34:35], 0, v[128:129]
	s_mov_b32 m0, s63
	s_nop 0
	global_load_lds_dwordx4 v[140:141], off
	v_lshl_add_u64 v[140:141], v[216:217], 0, s[10:11]
	s_mov_b32 m0, s54
	s_nop 0
	global_load_lds_dwordx4 v[140:141], off
	v_lshl_add_u64 v[140:141], v[218:219], 0, s[10:11]
	s_mov_b32 m0, s55
	s_nop 0
	global_load_lds_dwordx4 v[140:141], off
	s_waitcnt vmcnt(8)
	s_waitcnt lgkmcnt(0)
	s_barrier
	s_setprio 1
	s_waitcnt lgkmcnt(0)
	v_mfma_f32_16x16x32_bf16 v[60:63], v[150:153], v[182:185], v[60:63]
	v_mfma_f32_16x16x32_bf16 v[60:63], v[154:157], v[186:189], v[60:63]
	v_mfma_f32_16x16x32_bf16 v[56:59], v[158:161], v[182:185], v[56:59]
	v_mfma_f32_16x16x32_bf16 v[56:59], v[162:165], v[186:189], v[56:59]
	v_mfma_f32_16x16x32_bf16 v[52:55], v[150:153], v[190:193], v[52:55]
	v_mfma_f32_16x16x32_bf16 v[52:55], v[154:157], v[194:197], v[52:55]
	v_mfma_f32_16x16x32_bf16 v[44:47], v[158:161], v[190:193], v[44:47]
	v_mfma_f32_16x16x32_bf16 v[44:47], v[162:165], v[194:197], v[44:47]
	v_mfma_f32_16x16x32_bf16 v[36:39], v[150:153], v[198:201], v[36:39]
	v_mfma_f32_16x16x32_bf16 v[36:39], v[154:157], v[202:205], v[36:39]
	v_mfma_f32_16x16x32_bf16 v[28:31], v[158:161], v[198:201], v[28:31]
	v_mfma_f32_16x16x32_bf16 v[28:31], v[162:165], v[202:205], v[28:31]
	v_mfma_f32_16x16x32_bf16 v[20:23], v[150:153], v[206:209], v[20:23]
	v_mfma_f32_16x16x32_bf16 v[20:23], v[154:157], v[210:213], v[20:23]
	v_mfma_f32_16x16x32_bf16 v[12:15], v[158:161], v[206:209], v[12:15]
	v_mfma_f32_16x16x32_bf16 v[12:15], v[162:165], v[210:213], v[12:15]
	s_setprio 0
	s_setprio 1
	v_mfma_f32_16x16x32_bf16 v[48:51], v[166:169], v[182:185], v[48:51]
	v_mfma_f32_16x16x32_bf16 v[48:51], v[170:173], v[186:189], v[48:51]
	v_mfma_f32_16x16x32_bf16 v[40:43], v[174:177], v[182:185], v[40:43]
	v_mfma_f32_16x16x32_bf16 v[40:43], v[178:181], v[186:189], v[40:43]
	v_mfma_f32_16x16x32_bf16 v[32:35], v[166:169], v[190:193], v[32:35]
	v_mfma_f32_16x16x32_bf16 v[32:35], v[170:173], v[194:197], v[32:35]
	v_mfma_f32_16x16x32_bf16 v[24:27], v[174:177], v[190:193], v[24:27]
	v_mfma_f32_16x16x32_bf16 v[24:27], v[178:181], v[194:197], v[24:27]
	v_mfma_f32_16x16x32_bf16 v[16:19], v[166:169], v[198:201], v[16:19]
	v_mfma_f32_16x16x32_bf16 v[16:19], v[170:173], v[202:205], v[16:19]
	v_mfma_f32_16x16x32_bf16 v[8:11], v[174:177], v[198:201], v[8:11]
	v_mfma_f32_16x16x32_bf16 v[8:11], v[178:181], v[202:205], v[8:11]
	v_mfma_f32_16x16x32_bf16 v[4:7], v[166:169], v[206:209], v[4:7]
	v_mfma_f32_16x16x32_bf16 v[4:7], v[170:173], v[210:213], v[4:7]
	v_mfma_f32_16x16x32_bf16 v[0:3], v[174:177], v[206:209], v[0:3]
	v_mfma_f32_16x16x32_bf16 v[0:3], v[178:181], v[210:213], v[0:3]
	s_setprio 0
	s_barrier
	s_movk_i32 s0, 0x100
	s_andn2_b64 vcc, exec, s[30:31]
	s_mov_b64 s[34:35], -1
	s_mov_b64 s[30:31], 0
	s_cbranch_vccz .LBB0_268
	s_and_b64 vcc, exec, s[14:15]
	s_cbranch_vccz .LBB0_271
	s_barrier

; #define PG8_STAGE(bufoff, gbase, voff) do { _Pragma("unroll") for (int _i = 0; _i < 2; ++_i) \
;         __builtin_amdgcn_global_load_lds((const unsigned*)((const char*)(gbase) + (voff)[_i]), (PG8_LAS unsigned*)(lds + (bufoff) + ldsw + _i * 8192), 16, 0, 0); } while (0)
; #define PG8_LDA(dst, b, h) do { _Pragma("unroll") for (int m = 0; m < 4; ++m) _Pragma("unroll") for (int k = 0; k < 2; ++k) dst[m][k] = *(const PG8_LAS bf16x8*)(lds + PG8_SA(b, h) + aoff + m * 2048 + k * 1024); } while (0)
; #define PG8_LDB(dst, b, h) do { _Pragma("unroll") for (int n = 0; n < 2; ++n) _Pragma("unroll") for (int k = 0; k < 2; ++k) dst[n][k] = *(const PG8_LAS bf16x8*)(lds + PG8_SB(b, h) + boff + n * 2048 + k * 1024); } while (0)
; #define PG8_MMA(ai, bj, At, Bt) do { __builtin_amdgcn_s_setprio(1); _Pragma("unroll") for (int m = 0; m < 4; ++m) _Pragma("unroll") for (int n = 0; n < 2; ++n) _Pragma("unroll") for (int k = 0; k < 2; ++k) \
;         acc[ai][bj][m][n] = __builtin_amdgcn_mfma_f32_16x16x32_bf16(Bt[n][k], At[m][k], acc[ai][bj][m][n], 0, 0, 0); __builtin_amdgcn_s_setprio(0); } while (0)
; #define PG8_WAIT_V(n) asm volatile("s_waitcnt vmcnt(" #n ")" ::: "memory")
; #define PG8_WAIT_L(n) asm volatile("s_waitcnt lgkmcnt(" #n ")" ::: "memory")
; #define PG8_BAR __builtin_amdgcn_s_barrier()
; template <class Epi, class Sched, bool ALIGN_EPI = false, bool SP2 = false>
; __device__ __forceinline__ void gemm_phase(PG8_LAS unsigned char* lds, const Gemm g, const Sched& S, const Epi& E, const int tid) {
;     ...
;             const char* a1 = cA + (size_t)(t + 1) * kstep;
;             const char* a2 = last ? nA : cA + (size_t)(t + 2) * kstep; const char* b2 = last ? nB : cB + (size_t)(t + 2) * kstep;
;             const char* a3 = a2 + kstep; const char* b3 = b2 + kstep;
;             if (last && has_next) S.a_ready(nxt);
;             if constexpr (SP2) {
;             PG8_LDB(B0, 0, 0); PG8_LDB(B1, 0, 1); PG8_SCHED; PG8_LDA(At, 0, 0); PG8_STAGE(PG8_SA(1, 1), a1 + hstep, voffA);
;             PG8_WAIT_V(8); PG8_WAIT_L(0); PG8_BAR; PG8_MMA(0, 0, At, B0); PG8_MMA(0, 1, At, B1); PG8_BAR; PG8_SCHED;
;             PG8_LDA(At, 0, 1); PG8_STAGE(PG8_SB(0, 0), b2, voffB); PG8_STAGE(PG8_SB(0, 1), b2 + hstep, voffB); PG8_STAGE(PG8_SA(0, 0), a2, voffA);
;             PG8_WAIT_V(8); PG8_WAIT_L(0); PG8_BAR; PG8_MMA(1, 0, At, B0); PG8_MMA(1, 1, At, B1); PG8_BAR; PG8_SCHED;
.LBB0_616:
	ds_read_b128 v[144:147], v151
	ds_read_b128 v[154:157], v151 offset:1024
	ds_read_b128 v[158:161], v151 offset:2048
	ds_read_b128 v[162:165], v151 offset:3072
	ds_read_b128 v[166:169], v152
	ds_read_b128 v[170:173], v152 offset:1024
	ds_read_b128 v[174:177], v152 offset:2048
	ds_read_b128 v[178:181], v152 offset:3072
	s_add_u32 s0, s38, 0xfff80080
	s_addc_u32 s1, s39, -1
	s_cmp_eq_u32 s60, 28
	s_cselect_b32 s3, s4, s1
	s_cselect_b32 s2, s5, s0
	s_cselect_b32 s1, s27, s59
	s_cselect_b32 s0, s29, s37
	v_lshl_add_u64 v[216:217], s[38:39], 0, v[136:137]
	s_add_i32 m0, s42, 0xc000
	ds_read_b128 v[182:185], v153
	ds_read_b128 v[186:189], v153 offset:1024
	ds_read_b128 v[190:193], v153 offset:2048
	ds_read_b128 v[194:197], v153 offset:3072
	ds_read_b128 v[200:203], v153 offset:4096
	ds_read_b128 v[204:207], v153 offset:5120
	ds_read_b128 v[208:211], v153 offset:6144
	ds_read_b128 v[212:215], v153 offset:7168
	global_load_lds_dwordx4 v[216:217], off
	v_lshl_add_u64 v[216:217], s[38:39], 0, v[138:139]
	s_add_i32 m0, s42, 0xe000
	s_nop 0
	global_load_lds_dwordx4 v[216:217], off
	s_waitcnt vmcnt(8)
	s_waitcnt lgkmcnt(0)
	s_barrier
	s_setprio 1
	s_waitcnt lgkmcnt(0)
	v_mfma_f32_16x16x32_bf16 v[124:127], v[144:147], v[182:185], v[124:127]
	v_mfma_f32_16x16x32_bf16 v[124:127], v[154:157], v[186:189], v[124:127]
	v_mfma_f32_16x16x32_bf16 v[120:123], v[158:161], v[182:185], v[120:123]
	v_mfma_f32_16x16x32_bf16 v[120:123], v[162:165], v[186:189], v[120:123]
	v_mfma_f32_16x16x32_bf16 v[108:111], v[144:147], v[190:193], v[108:111]
	v_mfma_f32_16x16x32_bf16 v[108:111], v[154:157], v[194:197], v[108:111]
	v_mfma_f32_16x16x32_bf16 v[104:107], v[158:161], v[190:193], v[104:107]
	v_mfma_f32_16x16x32_bf16 v[104:107], v[162:165], v[194:197], v[104:107]
	v_mfma_f32_16x16x32_bf16 v[92:95], v[144:147], v[200:203], v[92:95]
	v_mfma_f32_16x16x32_bf16 v[92:95], v[154:157], v[204:207], v[92:95]
	v_mfma_f32_16x16x32_bf16 v[88:91], v[158:161], v[200:203], v[88:91]
	v_mfma_f32_16x16x32_bf16 v[88:91], v[162:165], v[204:207], v[88:91]
	v_mfma_f32_16x16x32_bf16 v[76:79], v[144:147], v[208:211], v[76:79]
	v_mfma_f32_16x16x32_bf16 v[76:79], v[154:157], v[212:215], v[76:79]
	v_mfma_f32_16x16x32_bf16 v[72:75], v[158:161], v[208:211], v[72:75]
	v_mfma_f32_16x16x32_bf16 v[72:75], v[162:165], v[212:215], v[72:75]
	s_setprio 0
	s_setprio 1
	v_mfma_f32_16x16x32_bf16 v[116:119], v[166:169], v[182:185], v[116:119]
	v_mfma_f32_16x16x32_bf16 v[116:119], v[170:173], v[186:189], v[116:119]
	v_mfma_f32_16x16x32_bf16 v[112:115], v[174:177], v[182:185], v[112:115]
	v_mfma_f32_16x16x32_bf16 v[112:115], v[178:181], v[186:189], v[112:115]
	v_mfma_f32_16x16x32_bf16 v[100:103], v[166:169], v[190:193], v[100:103]
	v_mfma_f32_16x16x32_bf16 v[100:103], v[170:173], v[194:197], v[100:103]
	v_mfma_f32_16x16x32_bf16 v[96:99], v[174:177], v[190:193], v[96:99]
	v_mfma_f32_16x16x32_bf16 v[96:99], v[178:181], v[194:197], v[96:99]
	v_mfma_f32_16x16x32_bf16 v[84:87], v[166:169], v[200:203], v[84:87]
	v_mfma_f32_16x16x32_bf16 v[84:87], v[170:173], v[204:207], v[84:87]
	v_mfma_f32_16x16x32_bf16 v[80:83], v[174:177], v[200:203], v[80:83]
	v_mfma_f32_16x16x32_bf16 v[80:83], v[178:181], v[204:207], v[80:83]
	v_mfma_f32_16x16x32_bf16 v[68:71], v[166:169], v[208:211], v[68:71]
	v_mfma_f32_16x16x32_bf16 v[68:71], v[170:173], v[212:215], v[68:71]
	v_mfma_f32_16x16x32_bf16 v[64:67], v[174:177], v[208:211], v[64:67]
	v_mfma_f32_16x16x32_bf16 v[64:67], v[178:181], v[212:215], v[64:67]
	s_setprio 0
	s_barrier
	s_add_i32 s61, s56, s41
	v_lshl_add_u64 v[216:217], s[0:1], 0, v[130:131]
	s_mov_b32 m0, s61
	ds_read_b128 v[182:185], v153 offset:16384
	ds_read_b128 v[186:189], v153 offset:17408
	ds_read_b128 v[190:193], v153 offset:18432
	ds_read_b128 v[194:197], v153 offset:19456
	ds_read_b128 v[200:203], v153 offset:20480
	ds_read_b128 v[204:207], v153 offset:21504
	ds_read_b128 v[208:211], v153 offset:22528
	ds_read_b128 v[212:215], v153 offset:23552
	global_load_lds_dwordx4 v[216:217], off
	s_add_i32 m0, s61, 0x2000
	s_add_u32 s62, s0, 0x80000
	v_lshl_add_u64 v[218:219], s[0:1], 0, v[134:135]
	s_addc_u32 s63, s1, 0
	s_add_i32 s61, s57, s41
	global_load_lds_dwordx4 v[218:219], off
	v_lshl_add_u64 v[220:221], s[62:63], 0, v[130:131]
	s_mov_b32 m0, s61
	v_lshl_add_u64 v[222:223], s[2:3], 0, v[132:133]
	global_load_lds_dwordx4 v[220:221], off
	v_lshl_add_u64 v[220:221], s[62:63], 0, v[134:135]
	s_add_i32 m0, s61, 0x2000
	s_nop 0
	global_load_lds_dwordx4 v[220:221], off
	v_lshl_add_u64 v[220:221], s[2:3], 0, v[128:129]
	s_mov_b32 m0, s42
	s_nop 0
	global_load_lds_dwordx4 v[220:221], off
	s_mov_b32 m0, s44
	s_nop 0
	global_load_lds_dwordx4 v[222:223], off
	s_waitcnt vmcnt(8)
	s_waitcnt lgkmcnt(0)
	s_barrier
; #define PG8_STAGE(bufoff, gbase, voff) do { _Pragma("unroll") for (int _i = 0; _i < 2; ++_i) \
;         __builtin_amdgcn_global_load_lds((const unsigned*)((const char*)(gbase) + (voff)[_i]), (PG8_LAS unsigned*)(lds + (bufoff) + ldsw + _i * 8192), 16, 0, 0); } while (0)
; #define PG8_LDA(dst, b, h) do { _Pragma("unroll") for (int m = 0; m < 4; ++m) _Pragma("unroll") for (int k = 0; k < 2; ++k) dst[m][k] = *(const PG8_LAS bf16x8*)(lds + PG8_SA(b, h) + aoff + m * 2048 + k * 1024); } while (0)
; #define PG8_LDB(dst, b, h) do { _Pragma("unroll") for (int n = 0; n < 2; ++n) _Pragma("unroll") for (int k = 0; k < 2; ++k) dst[n][k] = *(const PG8_LAS bf16x8*)(lds + PG8_SB(b, h) + boff + n * 2048 + k * 1024); } while (0)
; #define PG8_MMA(ai, bj, At, Bt) do { __builtin_amdgcn_s_setprio(1); _Pragma("unroll") for (int m = 0; m < 4; ++m) _Pragma("unroll") for (int n = 0; n < 2; ++n) _Pragma("unroll") for (int k = 0; k < 2; ++k) \
;         acc[ai][bj][m][n] = __builtin_amdgcn_mfma_f32_16x16x32_bf16(Bt[n][k], At[m][k], acc[ai][bj][m][n], 0, 0, 0); __builtin_amdgcn_s_setprio(0); } while (0)
; #define PG8_WAIT_V(n) asm volatile("s_waitcnt vmcnt(" #n ")" ::: "memory")
; #define PG8_WAIT_L(n) asm volatile("s_waitcnt lgkmcnt(" #n ")" ::: "memory")
; #define PG8_BAR __builtin_amdgcn_s_barrier()
; #define PG8_SCHED __builtin_amdgcn_sched_barrier(0)
; template <class Epi, class Sched, bool ALIGN_EPI = false, bool SP2 = false>
; __device__ __forceinline__ void gemm_phase(PG8_LAS unsigned char* lds, const Gemm g, const Sched& S, const Epi& E, const int tid) {
;     ...
;             PG8_WAIT_V(8); PG8_WAIT_L(0); PG8_BAR; PG8_MMA(1, 0, At, B0); PG8_MMA(1, 1, At, B1); PG8_BAR; PG8_SCHED;
;             PG8_LDB(B0, 1, 0); PG8_LDB(B1, 1, 1); PG8_SCHED; PG8_LDA(At, 1, 0); PG8_STAGE(PG8_SA(0, 1), a2 + hstep, voffA);
;             PG8_WAIT_V(8); PG8_WAIT_L(0); PG8_BAR; PG8_MMA(0, 0, At, B0); PG8_MMA(0, 1, At, B1); PG8_BAR; PG8_SCHED;
	s_setprio 1
	s_waitcnt lgkmcnt(0)
	v_mfma_f32_16x16x32_bf16 v[60:63], v[144:147], v[182:185], v[60:63]
	v_mfma_f32_16x16x32_bf16 v[60:63], v[154:157], v[186:189], v[60:63]
	v_mfma_f32_16x16x32_bf16 v[56:59], v[158:161], v[182:185], v[56:59]
	v_mfma_f32_16x16x32_bf16 v[56:59], v[162:165], v[186:189], v[56:59]
	v_mfma_f32_16x16x32_bf16 v[44:47], v[144:147], v[190:193], v[44:47]
	v_mfma_f32_16x16x32_bf16 v[44:47], v[154:157], v[194:197], v[44:47]
	v_mfma_f32_16x16x32_bf16 v[40:43], v[158:161], v[190:193], v[40:43]
	v_mfma_f32_16x16x32_bf16 v[40:43], v[162:165], v[194:197], v[40:43]
	v_mfma_f32_16x16x32_bf16 v[28:31], v[144:147], v[200:203], v[28:31]
	v_mfma_f32_16x16x32_bf16 v[28:31], v[154:157], v[204:207], v[28:31]
	v_mfma_f32_16x16x32_bf16 v[24:27], v[158:161], v[200:203], v[24:27]
	v_mfma_f32_16x16x32_bf16 v[24:27], v[162:165], v[204:207], v[24:27]
	v_mfma_f32_16x16x32_bf16 v[12:15], v[144:147], v[208:211], v[12:15]
	v_mfma_f32_16x16x32_bf16 v[12:15], v[154:157], v[212:215], v[12:15]
	v_mfma_f32_16x16x32_bf16 v[8:11], v[158:161], v[208:211], v[8:11]
	v_mfma_f32_16x16x32_bf16 v[8:11], v[162:165], v[212:215], v[8:11]
	s_setprio 0
	s_setprio 1
	v_mfma_f32_16x16x32_bf16 v[52:55], v[166:169], v[182:185], v[52:55]
	v_mfma_f32_16x16x32_bf16 v[52:55], v[170:173], v[186:189], v[52:55]
	v_mfma_f32_16x16x32_bf16 v[48:51], v[174:177], v[182:185], v[48:51]
	v_mfma_f32_16x16x32_bf16 v[48:51], v[178:181], v[186:189], v[48:51]
	v_mfma_f32_16x16x32_bf16 v[36:39], v[166:169], v[190:193], v[36:39]
	v_mfma_f32_16x16x32_bf16 v[36:39], v[170:173], v[194:197], v[36:39]
	v_mfma_f32_16x16x32_bf16 v[32:35], v[174:177], v[190:193], v[32:35]
	v_mfma_f32_16x16x32_bf16 v[32:35], v[178:181], v[194:197], v[32:35]
	v_mfma_f32_16x16x32_bf16 v[20:23], v[166:169], v[200:203], v[20:23]
	v_mfma_f32_16x16x32_bf16 v[20:23], v[170:173], v[204:207], v[20:23]
	v_mfma_f32_16x16x32_bf16 v[16:19], v[174:177], v[200:203], v[16:19]
	v_mfma_f32_16x16x32_bf16 v[16:19], v[178:181], v[204:207], v[16:19]
	v_mfma_f32_16x16x32_bf16 v[4:7], v[166:169], v[208:211], v[4:7]
	v_mfma_f32_16x16x32_bf16 v[4:7], v[170:173], v[212:215], v[4:7]
	v_mfma_f32_16x16x32_bf16 v[0:3], v[174:177], v[208:211], v[0:3]
	v_mfma_f32_16x16x32_bf16 v[0:3], v[178:181], v[212:215], v[0:3]
	s_setprio 0
	s_barrier
	s_add_i32 s61, 0, 0x18000
	s_add_i32 s62, 0, 0x1c000
	v_add_u32_e32 v162, s61, v149
	v_add_u32_e32 v178, s62, v149
	ds_read_b128 v[144:147], v162
	ds_read_b128 v[154:157], v162 offset:1024
	ds_read_b128 v[158:161], v162 offset:2048
	ds_read_b128 v[162:165], v162 offset:3072
	ds_read_b128 v[166:169], v178
	ds_read_b128 v[170:173], v178 offset:1024
	ds_read_b128 v[174:177], v178 offset:2048
	ds_read_b128 v[178:181], v178 offset:3072
	s_add_u32 s2, s2, 0x80000
	s_addc_u32 s3, s3, 0
	s_mov_b32 m0, s46
	v_lshl_add_u64 v[224:225], s[2:3], 0, v[128:129]
	ds_read_b128 v[182:185], v153 offset:32768
	ds_read_b128 v[186:189], v153 offset:33792
	ds_read_b128 v[190:193], v153 offset:34816
	ds_read_b128 v[194:197], v153 offset:35840
	ds_read_b128 v[200:203], v153 offset:36864
	ds_read_b128 v[204:207], v153 offset:37888
	ds_read_b128 v[208:211], v153 offset:38912
	ds_read_b128 v[212:215], v153 offset:39936
	global_load_lds_dwordx4 v[224:225], off
	v_lshl_add_u64 v[224:225], s[2:3], 0, v[132:133]
	s_mov_b32 m0, s48
	s_nop 0
	global_load_lds_dwordx4 v[224:225], off
	s_waitcnt vmcnt(8)
	s_waitcnt lgkmcnt(0)
	s_barrier
	s_setprio 1
	s_waitcnt lgkmcnt(0)
	v_mfma_f32_16x16x32_bf16 v[124:127], v[144:147], v[182:185], v[124:127]
	v_mfma_f32_16x16x32_bf16 v[124:127], v[154:157], v[186:189], v[124:127]
	v_mfma_f32_16x16x32_bf16 v[120:123], v[158:161], v[182:185], v[120:123]
	v_mfma_f32_16x16x32_bf16 v[120:123], v[162:165], v[186:189], v[120:123]
	v_mfma_f32_16x16x32_bf16 v[108:111], v[144:147], v[190:193], v[108:111]
	v_mfma_f32_16x16x32_bf16 v[108:111], v[154:157], v[194:197], v[108:111]
	v_mfma_f32_16x16x32_bf16 v[104:107], v[158:161], v[190:193], v[104:107]
	v_mfma_f32_16x16x32_bf16 v[104:107], v[162:165], v[194:197], v[104:107]
	v_mfma_f32_16x16x32_bf16 v[92:95], v[144:147], v[200:203], v[92:95]
	v_mfma_f32_16x16x32_bf16 v[92:95], v[154:157], v[204:207], v[92:95]
	v_mfma_f32_16x16x32_bf16 v[88:91], v[158:161], v[200:203], v[88:91]
	v_mfma_f32_16x16x32_bf16 v[88:91], v[162:165], v[204:207], v[88:91]
	v_mfma_f32_16x16x32_bf16 v[76:79], v[144:147], v[208:211], v[76:79]
	v_mfma_f32_16x16x32_bf16 v[76:79], v[154:157], v[212:215], v[76:79]
	v_mfma_f32_16x16x32_bf16 v[72:75], v[158:161], v[208:211], v[72:75]
	v_mfma_f32_16x16x32_bf16 v[72:75], v[162:165], v[212:215], v[72:75]
	s_setprio 0
	s_setprio 1
	v_mfma_f32_16x16x32_bf16 v[116:119], v[166:169], v[182:185], v[116:119]
	v_mfma_f32_16x16x32_bf16 v[116:119], v[170:173], v[186:189], v[116:119]
	v_mfma_f32_16x16x32_bf16 v[112:115], v[174:177], v[182:185], v[112:115]
	v_mfma_f32_16x16x32_bf16 v[112:115], v[178:181], v[186:189], v[112:115]
	v_mfma_f32_16x16x32_bf16 v[100:103], v[166:169], v[190:193], v[100:103]
	v_mfma_f32_16x16x32_bf16 v[100:103], v[170:173], v[194:197], v[100:103]
	v_mfma_f32_16x16x32_bf16 v[96:99], v[174:177], v[190:193], v[96:99]
	v_mfma_f32_16x16x32_bf16 v[96:99], v[178:181], v[194:197], v[96:99]
	v_mfma_f32_16x16x32_bf16 v[84:87], v[166:169], v[200:203], v[84:87]
	v_mfma_f32_16x16x32_bf16 v[84:87], v[170:173], v[204:207], v[84:87]
	v_mfma_f32_16x16x32_bf16 v[80:83], v[174:177], v[200:203], v[80:83]
	v_mfma_f32_16x16x32_bf16 v[80:83], v[178:181], v[204:207], v[80:83]
	v_mfma_f32_16x16x32_bf16 v[68:71], v[166:169], v[208:211], v[68:71]
	v_mfma_f32_16x16x32_bf16 v[68:71], v[170:173], v[212:215], v[68:71]
	v_mfma_f32_16x16x32_bf16 v[64:67], v[174:177], v[208:211], v[64:67]
	v_mfma_f32_16x16x32_bf16 v[64:67], v[178:181], v[212:215], v[64:67]
	s_setprio 0
	s_barrier
; __device__ __forceinline__ unsigned cvt_pk_bf16(float lo, float hi) { unsigned r; asm volatile("v_cvt_pk_bf16_f32 %0, %1, %2" : "=v"(r) : "v"(lo), "v"(hi)); return r; }
; #define PG8_STAGE(bufoff, gbase, voff) do { _Pragma("unroll") for (int _i = 0; _i < 2; ++_i) \
;         __builtin_amdgcn_global_load_lds((const unsigned*)((const char*)(gbase) + (voff)[_i]), (PG8_LAS unsigned*)(lds + (bufoff) + ldsw + _i * 8192), 16, 0, 0); } while (0)
; #define PG8_WAIT_V(n) asm volatile("s_waitcnt vmcnt(" #n ")" ::: "memory")
;     __device__ __forceinline__ void operator()(const f32x4 (&acc)[2][2][4][2], const Unit& u, int wr, int wc, int fr, int fq) const {
;         const int row0 = u.pm * BM + wr * 64 + fr; const int col0 = u.pn * BM + wc * 32 + 8 * fq;
; #pragma unroll
;         for (int ai = 0; ai < 2; ++ai)
; #pragma unroll
;             for (int m = 0; m < 4; ++m) { const int row = row0 + ai * HALF + m * 16; const size_t off = (size_t)row * ldc + col0; float sq = 0.f;
; #pragma unroll
;                 for (int bj = 0; bj < 2; ++bj) {
;                     const f32x4 o0 = *(const f32x4*)(base + off + bj * HALF) + acc[ai][bj][m][0], o1 = *(const f32x4*)(base + off + bj * HALF + 4) + acc[ai][bj][m][1];
;                     *(f32x4*)(out + off + bj * HALF) = o0; *(f32x4*)(out + off + bj * HALF + 4) = o1;
;                     u32x4 w; w.x = cvt_pk_bf16(o0[0], o0[1]); w.y = cvt_pk_bf16(o0[2], o0[3]); w.z = cvt_pk_bf16(o1[0], o1[1]); w.w = cvt_pk_bf16(o1[2], o1[3]);
;                     *(u32x4*)(xb + off + bj * HALF) = w;
;                     sq += (o0[0] * o0[0] + o0[1] * o0[1]) + (o0[2] * o0[2] + o0[3] * o0[3]) + (o1[0] * o1[0] + o1[1] * o1[1]) + (o1[2] * o1[2] + o1[3] * o1[3]); }
;                 sq += __shfl_xor(sq, 16); sq += __shfl_xor(sq, 32);
;                 if (fq == 0) ssq[(size_t)row * 32 + u.pn * 4 + wc] = sq;
;                 asm volatile("" ::: "memory"); }
; template <class Epi, class Sched, bool ALIGN_EPI = false, bool SP2 = false>
; __device__ __forceinline__ void gemm_phase(PG8_LAS unsigned char* lds, const Gemm g, const Sched& S, const Epi& E, const int tid) {
;     ...
;             PG8_LDA(At, 1, 1); PG8_STAGE(PG8_SB(1, 0), b3, voffB); PG8_STAGE(PG8_SB(1, 1), b3 + hstep, voffB); PG8_STAGE(PG8_SA(1, 0), a3, voffA);
;             PG8_WAIT_V(8); PG8_WAIT_L(0); PG8_BAR; PG8_MMA(1, 0, At, B0); PG8_MMA(1, 1, At, B1); PG8_BAR; PG8_SCHED;
	s_add_i32 s2, s61, s41
	v_lshl_add_u64 v[216:217], v[216:217], 0, s[24:25]
	s_mov_b32 m0, s2
	ds_read_b128 v[182:185], v153 offset:49152
	ds_read_b128 v[186:189], v153 offset:50176
	ds_read_b128 v[190:193], v153 offset:51200
	ds_read_b128 v[194:197], v153 offset:52224
	ds_read_b128 v[200:203], v153 offset:53248
	ds_read_b128 v[204:207], v153 offset:54272
	ds_read_b128 v[208:211], v153 offset:55296
	ds_read_b128 v[212:215], v153 offset:56320
	global_load_lds_dwordx4 v[216:217], off
	s_add_i32 m0, s2, 0x2000
	s_add_u32 s0, s0, 0x80080
	v_lshl_add_u64 v[216:217], v[218:219], 0, s[24:25]
	s_addc_u32 s1, s1, 0
	s_add_i32 s2, s62, s41
	global_load_lds_dwordx4 v[216:217], off
	v_lshl_add_u64 v[216:217], s[0:1], 0, v[130:131]
	s_mov_b32 m0, s2
	s_nop 0
	global_load_lds_dwordx4 v[216:217], off
	v_lshl_add_u64 v[216:217], s[0:1], 0, v[134:135]
	s_add_i32 m0, s2, 0x2000
	s_nop 0
	global_load_lds_dwordx4 v[216:217], off
	v_lshl_add_u64 v[216:217], v[220:221], 0, s[24:25]
	s_mov_b32 m0, s51
	s_nop 0
	global_load_lds_dwordx4 v[216:217], off
	v_lshl_add_u64 v[216:217], v[222:223], 0, s[24:25]
	s_mov_b32 m0, s52
	s_nop 0
	global_load_lds_dwordx4 v[216:217], off
	s_waitcnt vmcnt(8)
	s_waitcnt lgkmcnt(0)
	s_barrier
	s_setprio 1
	s_waitcnt lgkmcnt(0)
	v_mfma_f32_16x16x32_bf16 v[60:63], v[144:147], v[182:185], v[60:63]
	v_mfma_f32_16x16x32_bf16 v[60:63], v[154:157], v[186:189], v[60:63]
	v_mfma_f32_16x16x32_bf16 v[56:59], v[158:161], v[182:185], v[56:59]
	v_mfma_f32_16x16x32_bf16 v[56:59], v[162:165], v[186:189], v[56:59]
	v_mfma_f32_16x16x32_bf16 v[44:47], v[144:147], v[190:193], v[44:47]
	v_mfma_f32_16x16x32_bf16 v[44:47], v[154:157], v[194:197], v[44:47]
	v_mfma_f32_16x16x32_bf16 v[40:43], v[158:161], v[190:193], v[40:43]
	v_mfma_f32_16x16x32_bf16 v[40:43], v[162:165], v[194:197], v[40:43]
	v_mfma_f32_16x16x32_bf16 v[28:31], v[144:147], v[200:203], v[28:31]
	v_mfma_f32_16x16x32_bf16 v[28:31], v[154:157], v[204:207], v[28:31]
	v_mfma_f32_16x16x32_bf16 v[24:27], v[158:161], v[200:203], v[24:27]
	v_mfma_f32_16x16x32_bf16 v[24:27], v[162:165], v[204:207], v[24:27]
	v_mfma_f32_16x16x32_bf16 v[12:15], v[144:147], v[208:211], v[12:15]
	v_mfma_f32_16x16x32_bf16 v[12:15], v[154:157], v[212:215], v[12:15]
	v_mfma_f32_16x16x32_bf16 v[8:11], v[158:161], v[208:211], v[8:11]
	v_mfma_f32_16x16x32_bf16 v[8:11], v[162:165], v[212:215], v[8:11]
	s_setprio 0
	s_setprio 1
	v_mfma_f32_16x16x32_bf16 v[52:55], v[166:169], v[182:185], v[52:55]
	v_mfma_f32_16x16x32_bf16 v[52:55], v[170:173], v[186:189], v[52:55]
	v_mfma_f32_16x16x32_bf16 v[48:51], v[174:177], v[182:185], v[48:51]
	v_mfma_f32_16x16x32_bf16 v[48:51], v[178:181], v[186:189], v[48:51]
	v_mfma_f32_16x16x32_bf16 v[36:39], v[166:169], v[190:193], v[36:39]
	v_mfma_f32_16x16x32_bf16 v[36:39], v[170:173], v[194:197], v[36:39]
	v_mfma_f32_16x16x32_bf16 v[32:35], v[174:177], v[190:193], v[32:35]
	v_mfma_f32_16x16x32_bf16 v[32:35], v[178:181], v[194:197], v[32:35]
	v_mfma_f32_16x16x32_bf16 v[20:23], v[166:169], v[200:203], v[20:23]
	v_mfma_f32_16x16x32_bf16 v[20:23], v[170:173], v[204:207], v[20:23]
	v_mfma_f32_16x16x32_bf16 v[16:19], v[174:177], v[200:203], v[16:19]
	v_mfma_f32_16x16x32_bf16 v[16:19], v[178:181], v[204:207], v[16:19]
	v_mfma_f32_16x16x32_bf16 v[4:7], v[166:169], v[208:211], v[4:7]
	v_mfma_f32_16x16x32_bf16 v[4:7], v[170:173], v[212:215], v[4:7]
	v_mfma_f32_16x16x32_bf16 v[0:3], v[174:177], v[208:211], v[0:3]
	v_mfma_f32_16x16x32_bf16 v[0:3], v[178:181], v[212:215], v[0:3]
	s_setprio 0
	s_barrier
	s_add_i32 s60, s60, 2
	s_add_u32 s38, s38, 0x100
	s_addc_u32 s39, s39, 0
	s_add_u32 s37, s37, 0x100
	s_addc_u32 s59, s59, 0
	s_cmp_gt_u32 s60, 29
	s_cbranch_scc0 .LBB0_616
	v_lshl_add_u32 v146, s36, 8, v148
	v_lshl_or_b32 v144, s20, 8, v150
	v_ashrrev_i32_e32 v147, 31, v146
	v_ashrrev_i32_e32 v145, 31, v144
	v_lshlrev_b64 v[154:155], 11, v[146:147]
	v_lshl_add_u64 v[162:163], v[154:155], 0, v[144:145]
	v_lshlrev_b64 v[164:165], 2, v[162:163]
	v_lshl_add_u64 v[166:167], s[12:13], 0, v[164:165]
	global_load_dwordx4 v[154:157], v[166:167], off
	global_load_dwordx4 v[158:161], v[166:167], off offset:16
	v_lshl_add_u64 v[168:169], v[162:163], 1, s[18:19]
	v_lshl_add_u64 v[170:171], s[16:17], 0, v[164:165]
	s_lshl_b32 s36, s20, 2
	s_ashr_i32 s37, s36, 31
	s_waitcnt vmcnt(0)
	v_pk_add_f32 v[126:127], v[126:127], v[156:157]
	v_pk_add_f32 v[124:125], v[124:125], v[154:155]
	v_pk_add_f32 v[156:157], v[122:123], v[160:161]
	v_pk_add_f32 v[154:155], v[120:121], v[158:159]
	global_store_dwordx4 v[170:171], v[124:127], off
	global_store_dwordx4 v[170:171], v[154:157], off offset:16
	v_cvt_pk_bf16_f32 v120, v124, v125
	v_cvt_pk_bf16_f32 v121, v126, v127
	v_cvt_pk_bf16_f32 v122, v154, v155
	v_cvt_pk_bf16_f32 v123, v156, v157
	global_store_dwordx4 v[168:169], v[120:123], off
	global_load_dwordx4 v[158:161], v[166:167], off offset:512
	global_load_dwordx4 v[162:165], v[166:167], off offset:528
	v_mul_f32_e32 v122, v125, v125
	v_mul_f32_e32 v123, v127, v127
	v_mul_f32_e32 v125, v155, v155
	v_fmac_f32_e32 v122, v124, v124
	v_fmac_f32_e32 v123, v126, v126
	v_mul_f32_e32 v127, v157, v157
	v_fmac_f32_e32 v125, v154, v154
	v_add_f32_e32 v122, v122, v123
	v_fmac_f32_e32 v127, v156, v156
	v_add_f32_e32 v122, v122, v125
	v_add_f32_e32 v126, v127, v122
	v_and_b32_e32 v121, 64, v198
	v_xor_b32_e32 v120, 16, v198
	v_add_u32_e32 v121, 64, v121
	v_cmp_lt_i32_e32 vcc, v120, v121
	v_xor_b32_e32 v166, 32, v198
	s_waitcnt vmcnt(1)
	v_pk_add_f32 v[118:119], v[118:119], v[160:161]
	v_pk_add_f32 v[116:117], v[116:117], v[158:159]
	s_waitcnt vmcnt(0)
	v_pk_add_f32 v[122:123], v[112:113], v[162:163]
	v_mul_f32_e32 v112, v117, v117
	v_mul_f32_e32 v113, v119, v119
	v_pk_add_f32 v[124:125], v[114:115], v[164:165]
	v_mul_f32_e32 v114, v123, v123
	v_fmac_f32_e32 v112, v116, v116
	v_fmac_f32_e32 v113, v118, v118
	v_mul_f32_e32 v115, v125, v125
	v_fmac_f32_e32 v114, v122, v122
	v_add_f32_e32 v112, v112, v113
	v_fmac_f32_e32 v115, v124, v124
	v_add_f32_e32 v112, v112, v114
	v_cndmask_b32_e32 v120, v198, v120, vcc
	v_add_f32_e32 v112, v115, v112
	v_lshlrev_b32_e32 v120, 2, v120
	v_add_f32_e32 v112, v126, v112
	ds_bpermute_b32 v113, v120, v112
	v_cmp_lt_i32_e32 vcc, v166, v121
	global_store_dwordx4 v[170:171], v[116:119], off offset:512
	global_store_dwordx4 v[170:171], v[122:125], off offset:528
	v_cndmask_b32_e32 v114, v198, v166, vcc
	v_lshlrev_b32_e32 v114, 2, v114
	s_waitcnt lgkmcnt(0)
	v_add_f32_e32 v112, v112, v113
	ds_bpermute_b32 v113, v114, v112
	v_cvt_pk_bf16_f32 v116, v116, v117
	v_cvt_pk_bf16_f32 v117, v118, v119
	v_cvt_pk_bf16_f32 v118, v122, v123
	v_cvt_pk_bf16_f32 v119, v124, v125
	global_store_dwordx4 v[168:169], v[116:119], off offset:256
	s_and_saveexec_b64 s[0:1], s[8:9]
	s_cbranch_execz .LBB0_619
	v_lshlrev_b64 v[116:117], 7, v[146:147]
	v_lshl_add_u64 v[116:117], s[22:23], 0, v[116:117]
	v_lshl_add_u64 v[116:117], s[36:37], 2, v[116:117]
	s_lshl_b32 s20, s50, 2
	v_lshl_add_u64 v[116:117], v[116:117], 0, s[20:21]
	s_waitcnt lgkmcnt(0)
	v_add_f32_e32 v112, v112, v113
	global_store_dword v[116:117], v112, off

; #define PG8_STAGE(bufoff, gbase, voff) do { _Pragma("unroll") for (int _i = 0; _i < 2; ++_i) \
;         __builtin_amdgcn_global_load_lds((const unsigned*)((const char*)(gbase) + (voff)[_i]), (PG8_LAS unsigned*)(lds + (bufoff) + ldsw + _i * 8192), 16, 0, 0); } while (0)
; #define PG8_LDA(dst, b, h) do { _Pragma("unroll") for (int m = 0; m < 4; ++m) _Pragma("unroll") for (int k = 0; k < 2; ++k) dst[m][k] = *(const PG8_LAS bf16x8*)(lds + PG8_SA(b, h) + aoff + m * 2048 + k * 1024); } while (0)
; #define PG8_LDB(dst, b, h) do { _Pragma("unroll") for (int n = 0; n < 2; ++n) _Pragma("unroll") for (int k = 0; k < 2; ++k) dst[n][k] = *(const PG8_LAS bf16x8*)(lds + PG8_SB(b, h) + boff + n * 2048 + k * 1024); } while (0)
; #define PG8_MMA(ai, bj, At, Bt) do { __builtin_amdgcn_s_setprio(1); _Pragma("unroll") for (int m = 0; m < 4; ++m) _Pragma("unroll") for (int n = 0; n < 2; ++n) _Pragma("unroll") for (int k = 0; k < 2; ++k) \
;         acc[ai][bj][m][n] = __builtin_amdgcn_mfma_f32_16x16x32_bf16(Bt[n][k], At[m][k], acc[ai][bj][m][n], 0, 0, 0); __builtin_amdgcn_s_setprio(0); } while (0)
; #define PG8_WAIT_V(n) asm volatile("s_waitcnt vmcnt(" #n ")" ::: "memory")
; #define PG8_WAIT_L(n) asm volatile("s_waitcnt lgkmcnt(" #n ")" ::: "memory")
; #define PG8_BAR __builtin_amdgcn_s_barrier()
; #define PG8_SCHED __builtin_amdgcn_sched_barrier(0)
; template <class Epi, class Sched, bool ALIGN_EPI = false, bool SP2 = false>
; __device__ __forceinline__ void gemm_phase(PG8_LAS unsigned char* lds, const Gemm g, const Sched& S, const Epi& E, const int tid) {
;     ...
;             PG8_LDB(B0, 0, 0); PG8_LDB(B1, 0, 1); PG8_SCHED; PG8_LDA(At, 0, 0); PG8_STAGE(PG8_SA(1, 1), a1 + hstep, voffA);
;             PG8_WAIT_V(8); PG8_WAIT_L(0); PG8_BAR; PG8_MMA(0, 0, At, B0); PG8_MMA(0, 1, At, B1); PG8_BAR; PG8_SCHED;
;             PG8_LDA(At, 0, 1); PG8_STAGE(PG8_SB(0, 0), b2, voffB); PG8_STAGE(PG8_SB(0, 1), b2 + hstep, voffB); PG8_STAGE(PG8_SA(0, 0), a2, voffA);
;             PG8_WAIT_V(8); PG8_WAIT_L(0); PG8_BAR; PG8_MMA(1, 0, At, B0); PG8_MMA(1, 1, At, B1); PG8_BAR; PG8_SCHED;
.LBB0_759:
	ds_read_b128 v[144:147], v153
	ds_read_b128 v[158:161], v153 offset:1024
	ds_read_b128 v[162:165], v153 offset:2048
	ds_read_b128 v[166:169], v153 offset:3072
	ds_read_b128 v[170:173], v154
	ds_read_b128 v[174:177], v154 offset:1024
	ds_read_b128 v[178:181], v154 offset:2048
	ds_read_b128 v[182:185], v154 offset:3072
	s_add_u32 s0, s36, 0xfff80080
	s_addc_u32 s1, s37, -1
	s_cmp_eq_u32 s56, 28
	s_cselect_b32 s3, s4, s1
	s_cselect_b32 s2, s5, s0
	s_cselect_b32 s1, s13, s55
	s_cselect_b32 s0, s25, s27
	v_lshl_add_u64 v[220:221], s[36:37], 0, v[136:137]
	s_add_i32 m0, s35, 0xc000
	ds_read_b128 v[186:189], v155
	ds_read_b128 v[190:193], v155 offset:1024
	ds_read_b128 v[194:197], v155 offset:2048
	ds_read_b128 v[200:203], v155 offset:3072
	ds_read_b128 v[204:207], v155 offset:4096
	ds_read_b128 v[208:211], v155 offset:5120
	ds_read_b128 v[212:215], v155 offset:6144
	ds_read_b128 v[216:219], v155 offset:7168
	global_load_lds_dwordx4 v[220:221], off
	v_lshl_add_u64 v[220:221], s[36:37], 0, v[138:139]
	s_add_i32 m0, s35, 0xe000
	s_nop 0
	global_load_lds_dwordx4 v[220:221], off
	s_waitcnt vmcnt(8)
	s_waitcnt lgkmcnt(0)
	s_barrier
	s_setprio 1
	s_waitcnt lgkmcnt(0)
	v_mfma_f32_16x16x32_bf16 v[124:127], v[144:147], v[186:189], v[124:127]
	v_mfma_f32_16x16x32_bf16 v[124:127], v[158:161], v[190:193], v[124:127]
	v_mfma_f32_16x16x32_bf16 v[120:123], v[162:165], v[186:189], v[120:123]
	v_mfma_f32_16x16x32_bf16 v[120:123], v[166:169], v[190:193], v[120:123]
	v_mfma_f32_16x16x32_bf16 v[108:111], v[144:147], v[194:197], v[108:111]
	v_mfma_f32_16x16x32_bf16 v[108:111], v[158:161], v[200:203], v[108:111]
	v_mfma_f32_16x16x32_bf16 v[104:107], v[162:165], v[194:197], v[104:107]
	v_mfma_f32_16x16x32_bf16 v[104:107], v[166:169], v[200:203], v[104:107]
	v_mfma_f32_16x16x32_bf16 v[92:95], v[144:147], v[204:207], v[92:95]
	v_mfma_f32_16x16x32_bf16 v[92:95], v[158:161], v[208:211], v[92:95]
	v_mfma_f32_16x16x32_bf16 v[88:91], v[162:165], v[204:207], v[88:91]
	v_mfma_f32_16x16x32_bf16 v[88:91], v[166:169], v[208:211], v[88:91]
	v_mfma_f32_16x16x32_bf16 v[76:79], v[144:147], v[212:215], v[76:79]
	v_mfma_f32_16x16x32_bf16 v[76:79], v[158:161], v[216:219], v[76:79]
	v_mfma_f32_16x16x32_bf16 v[72:75], v[162:165], v[212:215], v[72:75]
	v_mfma_f32_16x16x32_bf16 v[72:75], v[166:169], v[216:219], v[72:75]
	s_setprio 0
	s_setprio 1
	v_mfma_f32_16x16x32_bf16 v[116:119], v[170:173], v[186:189], v[116:119]
	v_mfma_f32_16x16x32_bf16 v[116:119], v[174:177], v[190:193], v[116:119]
	v_mfma_f32_16x16x32_bf16 v[112:115], v[178:181], v[186:189], v[112:115]
	v_mfma_f32_16x16x32_bf16 v[112:115], v[182:185], v[190:193], v[112:115]
	v_mfma_f32_16x16x32_bf16 v[100:103], v[170:173], v[194:197], v[100:103]
	v_mfma_f32_16x16x32_bf16 v[100:103], v[174:177], v[200:203], v[100:103]
	v_mfma_f32_16x16x32_bf16 v[96:99], v[178:181], v[194:197], v[96:99]
	v_mfma_f32_16x16x32_bf16 v[96:99], v[182:185], v[200:203], v[96:99]
	v_mfma_f32_16x16x32_bf16 v[84:87], v[170:173], v[204:207], v[84:87]
	v_mfma_f32_16x16x32_bf16 v[84:87], v[174:177], v[208:211], v[84:87]
	v_mfma_f32_16x16x32_bf16 v[80:83], v[178:181], v[204:207], v[80:83]
	v_mfma_f32_16x16x32_bf16 v[80:83], v[182:185], v[208:211], v[80:83]
	v_mfma_f32_16x16x32_bf16 v[68:71], v[170:173], v[212:215], v[68:71]
	v_mfma_f32_16x16x32_bf16 v[68:71], v[174:177], v[216:219], v[68:71]
	v_mfma_f32_16x16x32_bf16 v[64:67], v[178:181], v[212:215], v[64:67]
	v_mfma_f32_16x16x32_bf16 v[64:67], v[182:185], v[216:219], v[64:67]
	s_setprio 0
	s_barrier
	s_add_i32 s57, s52, s38
	v_lshl_add_u64 v[220:221], s[0:1], 0, v[130:131]
	s_mov_b32 m0, s57
	ds_read_b128 v[186:189], v155 offset:16384
	ds_read_b128 v[190:193], v155 offset:17408
	ds_read_b128 v[194:197], v155 offset:18432
	ds_read_b128 v[200:203], v155 offset:19456
	ds_read_b128 v[204:207], v155 offset:20480
	ds_read_b128 v[208:211], v155 offset:21504
	ds_read_b128 v[212:215], v155 offset:22528
	ds_read_b128 v[216:219], v155 offset:23552
	global_load_lds_dwordx4 v[220:221], off
	s_add_i32 m0, s57, 0x2000
	s_add_u32 s58, s0, 0x80000
	v_lshl_add_u64 v[222:223], s[0:1], 0, v[134:135]
	s_addc_u32 s59, s1, 0
	s_add_i32 s57, s53, s38
	global_load_lds_dwordx4 v[222:223], off
	v_lshl_add_u64 v[224:225], s[58:59], 0, v[130:131]
	s_mov_b32 m0, s57
	v_lshl_add_u64 v[226:227], s[2:3], 0, v[132:133]
	global_load_lds_dwordx4 v[224:225], off
	v_lshl_add_u64 v[224:225], s[58:59], 0, v[134:135]
	s_add_i32 m0, s57, 0x2000
	s_nop 0
	global_load_lds_dwordx4 v[224:225], off
	v_lshl_add_u64 v[224:225], s[2:3], 0, v[128:129]
	s_mov_b32 m0, s35
	s_nop 0
	global_load_lds_dwordx4 v[224:225], off
	s_mov_b32 m0, s39
	s_nop 0
	global_load_lds_dwordx4 v[226:227], off
	s_waitcnt vmcnt(8)
	s_waitcnt lgkmcnt(0)
	s_barrier
; #define PG8_STAGE(bufoff, gbase, voff) do { _Pragma("unroll") for (int _i = 0; _i < 2; ++_i) \
;         __builtin_amdgcn_global_load_lds((const unsigned*)((const char*)(gbase) + (voff)[_i]), (PG8_LAS unsigned*)(lds + (bufoff) + ldsw + _i * 8192), 16, 0, 0); } while (0)
; #define PG8_LDA(dst, b, h) do { _Pragma("unroll") for (int m = 0; m < 4; ++m) _Pragma("unroll") for (int k = 0; k < 2; ++k) dst[m][k] = *(const PG8_LAS bf16x8*)(lds + PG8_SA(b, h) + aoff + m * 2048 + k * 1024); } while (0)
; #define PG8_LDB(dst, b, h) do { _Pragma("unroll") for (int n = 0; n < 2; ++n) _Pragma("unroll") for (int k = 0; k < 2; ++k) dst[n][k] = *(const PG8_LAS bf16x8*)(lds + PG8_SB(b, h) + boff + n * 2048 + k * 1024); } while (0)
; #define PG8_MMA(ai, bj, At, Bt) do { __builtin_amdgcn_s_setprio(1); _Pragma("unroll") for (int m = 0; m < 4; ++m) _Pragma("unroll") for (int n = 0; n < 2; ++n) _Pragma("unroll") for (int k = 0; k < 2; ++k) \
;         acc[ai][bj][m][n] = __builtin_amdgcn_mfma_f32_16x16x32_bf16(Bt[n][k], At[m][k], acc[ai][bj][m][n], 0, 0, 0); __builtin_amdgcn_s_setprio(0); } while (0)
; #define PG8_WAIT_V(n) asm volatile("s_waitcnt vmcnt(" #n ")" ::: "memory")
; #define PG8_WAIT_L(n) asm volatile("s_waitcnt lgkmcnt(" #n ")" ::: "memory")
; #define PG8_BAR __builtin_amdgcn_s_barrier()
; #define PG8_SCHED __builtin_amdgcn_sched_barrier(0)
; template <class Epi, class Sched, bool ALIGN_EPI = false, bool SP2 = false>
; __device__ __forceinline__ void gemm_phase(PG8_LAS unsigned char* lds, const Gemm g, const Sched& S, const Epi& E, const int tid) {
;     ...
;             PG8_WAIT_V(8); PG8_WAIT_L(0); PG8_BAR; PG8_MMA(1, 0, At, B0); PG8_MMA(1, 1, At, B1); PG8_BAR; PG8_SCHED;
;             PG8_LDB(B0, 1, 0); PG8_LDB(B1, 1, 1); PG8_SCHED; PG8_LDA(At, 1, 0); PG8_STAGE(PG8_SA(0, 1), a2 + hstep, voffA);
;             PG8_WAIT_V(8); PG8_WAIT_L(0); PG8_BAR; PG8_MMA(0, 0, At, B0); PG8_MMA(0, 1, At, B1); PG8_BAR; PG8_SCHED;
	s_setprio 1
	s_waitcnt lgkmcnt(0)
	v_mfma_f32_16x16x32_bf16 v[60:63], v[144:147], v[186:189], v[60:63]
	v_mfma_f32_16x16x32_bf16 v[60:63], v[158:161], v[190:193], v[60:63]
	v_mfma_f32_16x16x32_bf16 v[56:59], v[162:165], v[186:189], v[56:59]
	v_mfma_f32_16x16x32_bf16 v[56:59], v[166:169], v[190:193], v[56:59]
	v_mfma_f32_16x16x32_bf16 v[44:47], v[144:147], v[194:197], v[44:47]
	v_mfma_f32_16x16x32_bf16 v[44:47], v[158:161], v[200:203], v[44:47]
	v_mfma_f32_16x16x32_bf16 v[40:43], v[162:165], v[194:197], v[40:43]
	v_mfma_f32_16x16x32_bf16 v[40:43], v[166:169], v[200:203], v[40:43]
	v_mfma_f32_16x16x32_bf16 v[28:31], v[144:147], v[204:207], v[28:31]
	v_mfma_f32_16x16x32_bf16 v[28:31], v[158:161], v[208:211], v[28:31]
	v_mfma_f32_16x16x32_bf16 v[24:27], v[162:165], v[204:207], v[24:27]
	v_mfma_f32_16x16x32_bf16 v[24:27], v[166:169], v[208:211], v[24:27]
	v_mfma_f32_16x16x32_bf16 v[12:15], v[144:147], v[212:215], v[12:15]
	v_mfma_f32_16x16x32_bf16 v[12:15], v[158:161], v[216:219], v[12:15]
	v_mfma_f32_16x16x32_bf16 v[8:11], v[162:165], v[212:215], v[8:11]
	v_mfma_f32_16x16x32_bf16 v[8:11], v[166:169], v[216:219], v[8:11]
	s_setprio 0
	s_setprio 1
	v_mfma_f32_16x16x32_bf16 v[52:55], v[170:173], v[186:189], v[52:55]
	v_mfma_f32_16x16x32_bf16 v[52:55], v[174:177], v[190:193], v[52:55]
	v_mfma_f32_16x16x32_bf16 v[48:51], v[178:181], v[186:189], v[48:51]
	v_mfma_f32_16x16x32_bf16 v[48:51], v[182:185], v[190:193], v[48:51]
	v_mfma_f32_16x16x32_bf16 v[36:39], v[170:173], v[194:197], v[36:39]
	v_mfma_f32_16x16x32_bf16 v[36:39], v[174:177], v[200:203], v[36:39]
	v_mfma_f32_16x16x32_bf16 v[32:35], v[178:181], v[194:197], v[32:35]
	v_mfma_f32_16x16x32_bf16 v[32:35], v[182:185], v[200:203], v[32:35]
	v_mfma_f32_16x16x32_bf16 v[20:23], v[170:173], v[204:207], v[20:23]
	v_mfma_f32_16x16x32_bf16 v[20:23], v[174:177], v[208:211], v[20:23]
	v_mfma_f32_16x16x32_bf16 v[16:19], v[178:181], v[204:207], v[16:19]
	v_mfma_f32_16x16x32_bf16 v[16:19], v[182:185], v[208:211], v[16:19]
	v_mfma_f32_16x16x32_bf16 v[4:7], v[170:173], v[212:215], v[4:7]
	v_mfma_f32_16x16x32_bf16 v[4:7], v[174:177], v[216:219], v[4:7]
	v_mfma_f32_16x16x32_bf16 v[0:3], v[178:181], v[212:215], v[0:3]
	v_mfma_f32_16x16x32_bf16 v[0:3], v[182:185], v[216:219], v[0:3]
	s_setprio 0
	s_barrier
	s_add_i32 s57, 0, 0x18000
	v_add_u32_e32 v148, s57, v151
	s_add_i32 s58, 0, 0x1c000
	ds_read_b128 v[144:147], v148
	ds_read_b128 v[158:161], v148 offset:1024
	ds_read_b128 v[162:165], v148 offset:2048
	ds_read_b128 v[166:169], v148 offset:3072
	v_add_u32_e32 v148, s58, v151
	ds_read_b128 v[170:173], v148
	ds_read_b128 v[174:177], v148 offset:1024
	ds_read_b128 v[178:181], v148 offset:2048
	ds_read_b128 v[182:185], v148 offset:3072
	s_add_u32 s2, s2, 0x80000
	s_addc_u32 s3, s3, 0
	s_mov_b32 m0, s40
	v_lshl_add_u64 v[228:229], s[2:3], 0, v[128:129]
	ds_read_b128 v[186:189], v155 offset:32768
	ds_read_b128 v[190:193], v155 offset:33792
	ds_read_b128 v[194:197], v155 offset:34816
	ds_read_b128 v[200:203], v155 offset:35840
	ds_read_b128 v[204:207], v155 offset:36864
	ds_read_b128 v[208:211], v155 offset:37888
	ds_read_b128 v[212:215], v155 offset:38912
	ds_read_b128 v[216:219], v155 offset:39936
	global_load_lds_dwordx4 v[228:229], off
	v_lshl_add_u64 v[228:229], s[2:3], 0, v[132:133]
	s_mov_b32 m0, s41
	s_nop 0
	global_load_lds_dwordx4 v[228:229], off
	s_waitcnt vmcnt(8)
	s_waitcnt lgkmcnt(0)
	s_barrier
	s_setprio 1
	s_waitcnt lgkmcnt(0)
	v_mfma_f32_16x16x32_bf16 v[124:127], v[144:147], v[186:189], v[124:127]
	v_mfma_f32_16x16x32_bf16 v[124:127], v[158:161], v[190:193], v[124:127]
	v_mfma_f32_16x16x32_bf16 v[120:123], v[162:165], v[186:189], v[120:123]
	v_mfma_f32_16x16x32_bf16 v[120:123], v[166:169], v[190:193], v[120:123]
	v_mfma_f32_16x16x32_bf16 v[108:111], v[144:147], v[194:197], v[108:111]
	v_mfma_f32_16x16x32_bf16 v[108:111], v[158:161], v[200:203], v[108:111]
	v_mfma_f32_16x16x32_bf16 v[104:107], v[162:165], v[194:197], v[104:107]
	v_mfma_f32_16x16x32_bf16 v[104:107], v[166:169], v[200:203], v[104:107]
	v_mfma_f32_16x16x32_bf16 v[92:95], v[144:147], v[204:207], v[92:95]
	v_mfma_f32_16x16x32_bf16 v[92:95], v[158:161], v[208:211], v[92:95]
	v_mfma_f32_16x16x32_bf16 v[88:91], v[162:165], v[204:207], v[88:91]
	v_mfma_f32_16x16x32_bf16 v[88:91], v[166:169], v[208:211], v[88:91]
	v_mfma_f32_16x16x32_bf16 v[76:79], v[144:147], v[212:215], v[76:79]
	v_mfma_f32_16x16x32_bf16 v[76:79], v[158:161], v[216:219], v[76:79]
	v_mfma_f32_16x16x32_bf16 v[72:75], v[162:165], v[212:215], v[72:75]
	v_mfma_f32_16x16x32_bf16 v[72:75], v[166:169], v[216:219], v[72:75]
	s_setprio 0
	s_setprio 1
	v_mfma_f32_16x16x32_bf16 v[116:119], v[170:173], v[186:189], v[116:119]
	v_mfma_f32_16x16x32_bf16 v[116:119], v[174:177], v[190:193], v[116:119]
	v_mfma_f32_16x16x32_bf16 v[112:115], v[178:181], v[186:189], v[112:115]
	v_mfma_f32_16x16x32_bf16 v[112:115], v[182:185], v[190:193], v[112:115]
	v_mfma_f32_16x16x32_bf16 v[100:103], v[170:173], v[194:197], v[100:103]
	v_mfma_f32_16x16x32_bf16 v[100:103], v[174:177], v[200:203], v[100:103]
	v_mfma_f32_16x16x32_bf16 v[96:99], v[178:181], v[194:197], v[96:99]
	v_mfma_f32_16x16x32_bf16 v[96:99], v[182:185], v[200:203], v[96:99]
	v_mfma_f32_16x16x32_bf16 v[84:87], v[170:173], v[204:207], v[84:87]
	v_mfma_f32_16x16x32_bf16 v[84:87], v[174:177], v[208:211], v[84:87]
	v_mfma_f32_16x16x32_bf16 v[80:83], v[178:181], v[204:207], v[80:83]
	v_mfma_f32_16x16x32_bf16 v[80:83], v[182:185], v[208:211], v[80:83]
	v_mfma_f32_16x16x32_bf16 v[68:71], v[170:173], v[212:215], v[68:71]
	v_mfma_f32_16x16x32_bf16 v[68:71], v[174:177], v[216:219], v[68:71]
	v_mfma_f32_16x16x32_bf16 v[64:67], v[178:181], v[212:215], v[64:67]
	v_mfma_f32_16x16x32_bf16 v[64:67], v[182:185], v[216:219], v[64:67]
	s_setprio 0
	s_barrier
; #define PG8_STAGE(bufoff, gbase, voff) do { _Pragma("unroll") for (int _i = 0; _i < 2; ++_i) \
;         __builtin_amdgcn_global_load_lds((const unsigned*)((const char*)(gbase) + (voff)[_i]), (PG8_LAS unsigned*)(lds + (bufoff) + ldsw + _i * 8192), 16, 0, 0); } while (0)
; #define PG8_LDA(dst, b, h) do { _Pragma("unroll") for (int m = 0; m < 4; ++m) _Pragma("unroll") for (int k = 0; k < 2; ++k) dst[m][k] = *(const PG8_LAS bf16x8*)(lds + PG8_SA(b, h) + aoff + m * 2048 + k * 1024); } while (0)
; #define PG8_MMA(ai, bj, At, Bt) do { __builtin_amdgcn_s_setprio(1); _Pragma("unroll") for (int m = 0; m < 4; ++m) _Pragma("unroll") for (int n = 0; n < 2; ++n) _Pragma("unroll") for (int k = 0; k < 2; ++k) \
;         acc[ai][bj][m][n] = __builtin_amdgcn_mfma_f32_16x16x32_bf16(Bt[n][k], At[m][k], acc[ai][bj][m][n], 0, 0, 0); __builtin_amdgcn_s_setprio(0); } while (0)
; #define PG8_WAIT_V(n) asm volatile("s_waitcnt vmcnt(" #n ")" ::: "memory")
; #define PG8_WAIT_L(n) asm volatile("s_waitcnt lgkmcnt(" #n ")" ::: "memory")
; #define PG8_BAR __builtin_amdgcn_s_barrier()
; #define PG8_SCHED __builtin_amdgcn_sched_barrier(0)
; template <class Epi, class Sched, bool ALIGN_EPI = false, bool SP2 = false>
; __device__ __forceinline__ void gemm_phase(PG8_LAS unsigned char* lds, const Gemm g, const Sched& S, const Epi& E, const int tid) {
;     ...
;             PG8_LDA(At, 1, 1); PG8_STAGE(PG8_SB(1, 0), b3, voffB); PG8_STAGE(PG8_SB(1, 1), b3 + hstep, voffB); PG8_STAGE(PG8_SA(1, 0), a3, voffA);
;             PG8_WAIT_V(8); PG8_WAIT_L(0); PG8_BAR; PG8_MMA(1, 0, At, B0); PG8_MMA(1, 1, At, B1); PG8_BAR; PG8_SCHED;
;     ...
;         if constexpr (ALIGN_EPI) { if (wr == 0) PG8_BAR; }
	s_add_i32 s2, s57, s38
	v_lshl_add_u64 v[220:221], v[220:221], 0, s[16:17]
	s_mov_b32 m0, s2
	ds_read_b128 v[186:189], v155 offset:49152
	ds_read_b128 v[190:193], v155 offset:50176
	ds_read_b128 v[194:197], v155 offset:51200
	ds_read_b128 v[200:203], v155 offset:52224
	ds_read_b128 v[204:207], v155 offset:53248
	ds_read_b128 v[208:211], v155 offset:54272
	ds_read_b128 v[212:215], v155 offset:55296
	ds_read_b128 v[216:219], v155 offset:56320
	global_load_lds_dwordx4 v[220:221], off
	s_add_i32 m0, s2, 0x2000
	s_add_u32 s0, s0, 0x80080
	v_lshl_add_u64 v[220:221], v[222:223], 0, s[16:17]
	s_addc_u32 s1, s1, 0
	s_add_i32 s2, s58, s38
	global_load_lds_dwordx4 v[220:221], off
	v_lshl_add_u64 v[220:221], s[0:1], 0, v[130:131]
	s_mov_b32 m0, s2
	s_nop 0
	global_load_lds_dwordx4 v[220:221], off
	v_lshl_add_u64 v[220:221], s[0:1], 0, v[134:135]
	s_add_i32 m0, s2, 0x2000
	s_nop 0
	global_load_lds_dwordx4 v[220:221], off
	v_lshl_add_u64 v[220:221], v[224:225], 0, s[16:17]
	s_mov_b32 m0, s44
	s_nop 0
	global_load_lds_dwordx4 v[220:221], off
	v_lshl_add_u64 v[220:221], v[226:227], 0, s[16:17]
	s_mov_b32 m0, s46
	s_nop 0
	global_load_lds_dwordx4 v[220:221], off
	s_waitcnt vmcnt(8)
	s_waitcnt lgkmcnt(0)
	s_barrier
	s_setprio 1
	s_waitcnt lgkmcnt(0)
	v_mfma_f32_16x16x32_bf16 v[60:63], v[144:147], v[186:189], v[60:63]
	v_mfma_f32_16x16x32_bf16 v[60:63], v[158:161], v[190:193], v[60:63]
	v_mfma_f32_16x16x32_bf16 v[56:59], v[162:165], v[186:189], v[56:59]
	v_mfma_f32_16x16x32_bf16 v[56:59], v[166:169], v[190:193], v[56:59]
	v_mfma_f32_16x16x32_bf16 v[44:47], v[144:147], v[194:197], v[44:47]
	v_mfma_f32_16x16x32_bf16 v[44:47], v[158:161], v[200:203], v[44:47]
	v_mfma_f32_16x16x32_bf16 v[40:43], v[162:165], v[194:197], v[40:43]
	v_mfma_f32_16x16x32_bf16 v[40:43], v[166:169], v[200:203], v[40:43]
	v_mfma_f32_16x16x32_bf16 v[28:31], v[144:147], v[204:207], v[28:31]
	v_mfma_f32_16x16x32_bf16 v[28:31], v[158:161], v[208:211], v[28:31]
	v_mfma_f32_16x16x32_bf16 v[24:27], v[162:165], v[204:207], v[24:27]
	v_mfma_f32_16x16x32_bf16 v[24:27], v[166:169], v[208:211], v[24:27]
	v_mfma_f32_16x16x32_bf16 v[12:15], v[144:147], v[212:215], v[12:15]
	v_mfma_f32_16x16x32_bf16 v[12:15], v[158:161], v[216:219], v[12:15]
	v_mfma_f32_16x16x32_bf16 v[8:11], v[162:165], v[212:215], v[8:11]
	v_mfma_f32_16x16x32_bf16 v[8:11], v[166:169], v[216:219], v[8:11]
	s_setprio 0
	s_setprio 1
	v_mfma_f32_16x16x32_bf16 v[52:55], v[170:173], v[186:189], v[52:55]
	v_mfma_f32_16x16x32_bf16 v[52:55], v[174:177], v[190:193], v[52:55]
	v_mfma_f32_16x16x32_bf16 v[48:51], v[178:181], v[186:189], v[48:51]
	v_mfma_f32_16x16x32_bf16 v[48:51], v[182:185], v[190:193], v[48:51]
	v_mfma_f32_16x16x32_bf16 v[36:39], v[170:173], v[194:197], v[36:39]
	v_mfma_f32_16x16x32_bf16 v[36:39], v[174:177], v[200:203], v[36:39]
	v_mfma_f32_16x16x32_bf16 v[32:35], v[178:181], v[194:197], v[32:35]
	v_mfma_f32_16x16x32_bf16 v[32:35], v[182:185], v[200:203], v[32:35]
	v_mfma_f32_16x16x32_bf16 v[20:23], v[170:173], v[204:207], v[20:23]
	v_mfma_f32_16x16x32_bf16 v[20:23], v[174:177], v[208:211], v[20:23]
	v_mfma_f32_16x16x32_bf16 v[16:19], v[178:181], v[204:207], v[16:19]
	v_mfma_f32_16x16x32_bf16 v[16:19], v[182:185], v[208:211], v[16:19]
	v_mfma_f32_16x16x32_bf16 v[4:7], v[170:173], v[212:215], v[4:7]
	v_mfma_f32_16x16x32_bf16 v[4:7], v[174:177], v[216:219], v[4:7]
	v_mfma_f32_16x16x32_bf16 v[0:3], v[178:181], v[212:215], v[0:3]
	v_mfma_f32_16x16x32_bf16 v[0:3], v[182:185], v[216:219], v[0:3]
	s_setprio 0
	s_barrier
	s_add_i32 s56, s56, 2
	s_add_u32 s36, s36, 0x100
	s_addc_u32 s37, s37, 0
	s_add_u32 s27, s27, 0x100
	s_addc_u32 s55, s55, 0
	s_cmp_gt_u32 s56, 29
	s_cbranch_scc0 .LBB0_759
	s_and_b64 vcc, exec, s[20:21]
	s_cbranch_vccz .LBB0_762
	s_barrier

; #define PG8_STAGE(bufoff, gbase, voff) do { _Pragma("unroll") for (int _i = 0; _i < 2; ++_i) \
;         __builtin_amdgcn_global_load_lds((const unsigned*)((const char*)(gbase) + (voff)[_i]), (PG8_LAS unsigned*)(lds + (bufoff) + ldsw + _i * 8192), 16, 0, 0); } while (0)
; #define PG8_LDA(dst, b, h) do { _Pragma("unroll") for (int m = 0; m < 4; ++m) _Pragma("unroll") for (int k = 0; k < 2; ++k) dst[m][k] = *(const PG8_LAS bf16x8*)(lds + PG8_SA(b, h) + aoff + m * 2048 + k * 1024); } while (0)
; #define PG8_LDB(dst, b, h) do { _Pragma("unroll") for (int n = 0; n < 2; ++n) _Pragma("unroll") for (int k = 0; k < 2; ++k) dst[n][k] = *(const PG8_LAS bf16x8*)(lds + PG8_SB(b, h) + boff + n * 2048 + k * 1024); } while (0)
; #define PG8_MMA(ai, bj, At, Bt) do { __builtin_amdgcn_s_setprio(1); _Pragma("unroll") for (int m = 0; m < 4; ++m) _Pragma("unroll") for (int n = 0; n < 2; ++n) _Pragma("unroll") for (int k = 0; k < 2; ++k) \
;         acc[ai][bj][m][n] = __builtin_amdgcn_mfma_f32_16x16x32_bf16(Bt[n][k], At[m][k], acc[ai][bj][m][n], 0, 0, 0); __builtin_amdgcn_s_setprio(0); } while (0)
; #define PG8_WAIT_V(n) asm volatile("s_waitcnt vmcnt(" #n ")" ::: "memory")
; #define PG8_WAIT_L(n) asm volatile("s_waitcnt lgkmcnt(" #n ")" ::: "memory")
; #define PG8_BAR __builtin_amdgcn_s_barrier()
; #define PG8_SCHED __builtin_amdgcn_sched_barrier(0)
; template <class Epi, class Sched, bool ALIGN_EPI = false, bool SP2 = false>
; __device__ __forceinline__ void gemm_phase(PG8_LAS unsigned char* lds, const Gemm g, const Sched& S, const Epi& E, const int tid) {
;     ...
;             PG8_LDB(B0, 0, 0); PG8_LDB(B1, 0, 1); PG8_SCHED; PG8_LDA(At, 0, 0); PG8_STAGE(PG8_SA(1, 1), a1 + hstep, voffA);
;             PG8_WAIT_V(8); PG8_WAIT_L(0); PG8_BAR; PG8_MMA(0, 0, At, B0); PG8_MMA(0, 1, At, B1); PG8_BAR; PG8_SCHED;
;             PG8_LDA(At, 0, 1); PG8_STAGE(PG8_SB(0, 0), b2, voffB); PG8_STAGE(PG8_SB(0, 1), b2 + hstep, voffB); PG8_STAGE(PG8_SA(0, 0), a2, voffA);
;             PG8_WAIT_V(8); PG8_WAIT_L(0); PG8_BAR; PG8_MMA(1, 0, At, B0); PG8_MMA(1, 1, At, B1); PG8_BAR; PG8_SCHED;
.LBB0_850:
	ds_read_b128 v[88:91], v207
	ds_read_b128 v[92:95], v207 offset:1024
	ds_read_b128 v[96:99], v207 offset:2048
	ds_read_b128 v[100:103], v207 offset:3072
	ds_read_b128 v[104:107], v208
	ds_read_b128 v[108:111], v208 offset:1024
	ds_read_b128 v[112:115], v208 offset:2048
	ds_read_b128 v[116:119], v208 offset:3072
	s_add_u32 s0, s14, 0xfff80080
	s_addc_u32 s1, s15, -1
	s_cmp_eq_u32 s55, 28
	s_cselect_b32 s3, s4, s1
	s_cselect_b32 s2, s5, s0
	s_cselect_b32 s1, s11, s17
	s_cselect_b32 s0, s13, s16
	v_lshl_add_u64 v[216:217], s[14:15], 0, v[180:181]
	s_add_i32 m0, s44, 0xc000
	ds_read_b128 v[160:163], v209
	ds_read_b128 v[164:167], v209 offset:1024
	ds_read_b128 v[168:171], v209 offset:2048
	ds_read_b128 v[188:191], v209 offset:3072
	ds_read_b128 v[192:195], v209 offset:4096
	ds_read_b128 v[196:199], v209 offset:5120
	ds_read_b128 v[200:203], v209 offset:6144
	ds_read_b128 v[212:215], v209 offset:7168
	global_load_lds_dwordx4 v[216:217], off
	v_lshl_add_u64 v[216:217], s[14:15], 0, v[182:183]
	s_add_i32 m0, s44, 0xe000
	s_nop 0
	global_load_lds_dwordx4 v[216:217], off
	s_waitcnt vmcnt(8)
	s_waitcnt lgkmcnt(0)
	s_barrier
	s_setprio 1
	s_waitcnt lgkmcnt(0)
	v_mfma_f32_16x16x32_bf16 v[156:159], v[88:91], v[160:163], v[156:159]
	v_mfma_f32_16x16x32_bf16 v[156:159], v[92:95], v[164:167], v[156:159]
	v_mfma_f32_16x16x32_bf16 v[152:155], v[96:99], v[160:163], v[152:155]
	v_mfma_f32_16x16x32_bf16 v[152:155], v[100:103], v[164:167], v[152:155]
	v_mfma_f32_16x16x32_bf16 v[148:151], v[88:91], v[168:171], v[148:151]
	v_mfma_f32_16x16x32_bf16 v[148:151], v[92:95], v[188:191], v[148:151]
	v_mfma_f32_16x16x32_bf16 v[144:147], v[96:99], v[168:171], v[144:147]
	v_mfma_f32_16x16x32_bf16 v[144:147], v[100:103], v[188:191], v[144:147]
	v_mfma_f32_16x16x32_bf16 v[140:143], v[88:91], v[192:195], v[140:143]
	v_mfma_f32_16x16x32_bf16 v[140:143], v[92:95], v[196:199], v[140:143]
	v_mfma_f32_16x16x32_bf16 v[136:139], v[96:99], v[192:195], v[136:139]
	v_mfma_f32_16x16x32_bf16 v[136:139], v[100:103], v[196:199], v[136:139]
	v_mfma_f32_16x16x32_bf16 v[132:135], v[88:91], v[200:203], v[132:135]
	v_mfma_f32_16x16x32_bf16 v[132:135], v[92:95], v[212:215], v[132:135]
	v_mfma_f32_16x16x32_bf16 v[128:131], v[96:99], v[200:203], v[128:131]
	v_mfma_f32_16x16x32_bf16 v[128:131], v[100:103], v[212:215], v[128:131]
	s_setprio 0
	s_setprio 1
	v_mfma_f32_16x16x32_bf16 v[60:63], v[104:107], v[160:163], v[60:63]
	v_mfma_f32_16x16x32_bf16 v[60:63], v[108:111], v[164:167], v[60:63]
	v_mfma_f32_16x16x32_bf16 v[56:59], v[112:115], v[160:163], v[56:59]
	v_mfma_f32_16x16x32_bf16 v[56:59], v[116:119], v[164:167], v[56:59]
	v_mfma_f32_16x16x32_bf16 v[52:55], v[104:107], v[168:171], v[52:55]
	v_mfma_f32_16x16x32_bf16 v[52:55], v[108:111], v[188:191], v[52:55]
	v_mfma_f32_16x16x32_bf16 v[48:51], v[112:115], v[168:171], v[48:51]
	v_mfma_f32_16x16x32_bf16 v[48:51], v[116:119], v[188:191], v[48:51]
	v_mfma_f32_16x16x32_bf16 v[44:47], v[104:107], v[192:195], v[44:47]
	v_mfma_f32_16x16x32_bf16 v[44:47], v[108:111], v[196:199], v[44:47]
	v_mfma_f32_16x16x32_bf16 v[40:43], v[112:115], v[192:195], v[40:43]
	v_mfma_f32_16x16x32_bf16 v[40:43], v[116:119], v[196:199], v[40:43]
	v_mfma_f32_16x16x32_bf16 v[36:39], v[104:107], v[200:203], v[36:39]
	v_mfma_f32_16x16x32_bf16 v[36:39], v[108:111], v[212:215], v[36:39]
	v_mfma_f32_16x16x32_bf16 v[32:35], v[112:115], v[200:203], v[32:35]
	v_mfma_f32_16x16x32_bf16 v[32:35], v[116:119], v[212:215], v[32:35]
	s_setprio 0
	s_barrier
	s_add_i32 s57, s68, s42
	v_lshl_add_u64 v[216:217], s[0:1], 0, v[174:175]
	s_mov_b32 m0, s57
	ds_read_b128 v[160:163], v209 offset:16384
	ds_read_b128 v[164:167], v209 offset:17408
	ds_read_b128 v[168:171], v209 offset:18432
	ds_read_b128 v[188:191], v209 offset:19456
	ds_read_b128 v[192:195], v209 offset:20480
	ds_read_b128 v[196:199], v209 offset:21504
	ds_read_b128 v[200:203], v209 offset:22528
	ds_read_b128 v[212:215], v209 offset:23552
	global_load_lds_dwordx4 v[216:217], off
	s_add_i32 m0, s57, 0x2000
	s_add_u32 s62, s0, 0x80000
	v_lshl_add_u64 v[218:219], s[0:1], 0, v[178:179]
	s_addc_u32 s63, s1, 0
	s_add_i32 s57, s69, s42
	global_load_lds_dwordx4 v[218:219], off
	v_lshl_add_u64 v[220:221], s[62:63], 0, v[174:175]
	s_mov_b32 m0, s57
	v_lshl_add_u64 v[222:223], s[2:3], 0, v[176:177]
	global_load_lds_dwordx4 v[220:221], off
	v_lshl_add_u64 v[220:221], s[62:63], 0, v[178:179]
	s_add_i32 m0, s57, 0x2000
	s_nop 0
	global_load_lds_dwordx4 v[220:221], off
	v_lshl_add_u64 v[220:221], s[2:3], 0, v[172:173]
	s_mov_b32 m0, s44
	s_nop 0
	global_load_lds_dwordx4 v[220:221], off
	s_mov_b32 m0, s46
	s_nop 0
	global_load_lds_dwordx4 v[222:223], off
	s_waitcnt vmcnt(8)
	s_waitcnt lgkmcnt(0)
	s_barrier
; #define PG8_STAGE(bufoff, gbase, voff) do { _Pragma("unroll") for (int _i = 0; _i < 2; ++_i) \
;         __builtin_amdgcn_global_load_lds((const unsigned*)((const char*)(gbase) + (voff)[_i]), (PG8_LAS unsigned*)(lds + (bufoff) + ldsw + _i * 8192), 16, 0, 0); } while (0)
; #define PG8_LDA(dst, b, h) do { _Pragma("unroll") for (int m = 0; m < 4; ++m) _Pragma("unroll") for (int k = 0; k < 2; ++k) dst[m][k] = *(const PG8_LAS bf16x8*)(lds + PG8_SA(b, h) + aoff + m * 2048 + k * 1024); } while (0)
; #define PG8_LDB(dst, b, h) do { _Pragma("unroll") for (int n = 0; n < 2; ++n) _Pragma("unroll") for (int k = 0; k < 2; ++k) dst[n][k] = *(const PG8_LAS bf16x8*)(lds + PG8_SB(b, h) + boff + n * 2048 + k * 1024); } while (0)
; #define PG8_MMA(ai, bj, At, Bt) do { __builtin_amdgcn_s_setprio(1); _Pragma("unroll") for (int m = 0; m < 4; ++m) _Pragma("unroll") for (int n = 0; n < 2; ++n) _Pragma("unroll") for (int k = 0; k < 2; ++k) \
;         acc[ai][bj][m][n] = __builtin_amdgcn_mfma_f32_16x16x32_bf16(Bt[n][k], At[m][k], acc[ai][bj][m][n], 0, 0, 0); __builtin_amdgcn_s_setprio(0); } while (0)
; #define PG8_WAIT_V(n) asm volatile("s_waitcnt vmcnt(" #n ")" ::: "memory")
; #define PG8_WAIT_L(n) asm volatile("s_waitcnt lgkmcnt(" #n ")" ::: "memory")
; #define PG8_BAR __builtin_amdgcn_s_barrier()
; #define PG8_SCHED __builtin_amdgcn_sched_barrier(0)
; template <class Epi, class Sched, bool ALIGN_EPI = false, bool SP2 = false>
; __device__ __forceinline__ void gemm_phase(PG8_LAS unsigned char* lds, const Gemm g, const Sched& S, const Epi& E, const int tid) {
;     ...
;             PG8_WAIT_V(8); PG8_WAIT_L(0); PG8_BAR; PG8_MMA(1, 0, At, B0); PG8_MMA(1, 1, At, B1); PG8_BAR; PG8_SCHED;
;             PG8_LDB(B0, 1, 0); PG8_LDB(B1, 1, 1); PG8_SCHED; PG8_LDA(At, 1, 0); PG8_STAGE(PG8_SA(0, 1), a2 + hstep, voffA);
;             PG8_WAIT_V(8); PG8_WAIT_L(0); PG8_BAR; PG8_MMA(0, 0, At, B0); PG8_MMA(0, 1, At, B1); PG8_BAR; PG8_SCHED;
	s_setprio 1
	s_waitcnt lgkmcnt(0)
	v_mfma_f32_16x16x32_bf16 v[124:127], v[88:91], v[160:163], v[124:127]
	v_mfma_f32_16x16x32_bf16 v[124:127], v[92:95], v[164:167], v[124:127]
	v_mfma_f32_16x16x32_bf16 v[120:123], v[96:99], v[160:163], v[120:123]
	v_mfma_f32_16x16x32_bf16 v[120:123], v[100:103], v[164:167], v[120:123]
	v_mfma_f32_16x16x32_bf16 v[84:87], v[88:91], v[168:171], v[84:87]
	v_mfma_f32_16x16x32_bf16 v[84:87], v[92:95], v[188:191], v[84:87]
	v_mfma_f32_16x16x32_bf16 v[80:83], v[96:99], v[168:171], v[80:83]
	v_mfma_f32_16x16x32_bf16 v[80:83], v[100:103], v[188:191], v[80:83]
	v_mfma_f32_16x16x32_bf16 v[76:79], v[88:91], v[192:195], v[76:79]
	v_mfma_f32_16x16x32_bf16 v[76:79], v[92:95], v[196:199], v[76:79]
	v_mfma_f32_16x16x32_bf16 v[72:75], v[96:99], v[192:195], v[72:75]
	v_mfma_f32_16x16x32_bf16 v[72:75], v[100:103], v[196:199], v[72:75]
	v_mfma_f32_16x16x32_bf16 v[68:71], v[88:91], v[200:203], v[68:71]
	v_mfma_f32_16x16x32_bf16 v[68:71], v[92:95], v[212:215], v[68:71]
	v_mfma_f32_16x16x32_bf16 v[64:67], v[96:99], v[200:203], v[64:67]
	v_mfma_f32_16x16x32_bf16 v[64:67], v[100:103], v[212:215], v[64:67]
	s_setprio 0
	s_setprio 1
	v_mfma_f32_16x16x32_bf16 v[28:31], v[104:107], v[160:163], v[28:31]
	v_mfma_f32_16x16x32_bf16 v[28:31], v[108:111], v[164:167], v[28:31]
	v_mfma_f32_16x16x32_bf16 v[24:27], v[112:115], v[160:163], v[24:27]
	v_mfma_f32_16x16x32_bf16 v[24:27], v[116:119], v[164:167], v[24:27]
	v_mfma_f32_16x16x32_bf16 v[20:23], v[104:107], v[168:171], v[20:23]
	v_mfma_f32_16x16x32_bf16 v[20:23], v[108:111], v[188:191], v[20:23]
	v_mfma_f32_16x16x32_bf16 v[16:19], v[112:115], v[168:171], v[16:19]
	v_mfma_f32_16x16x32_bf16 v[16:19], v[116:119], v[188:191], v[16:19]
	v_mfma_f32_16x16x32_bf16 v[12:15], v[104:107], v[192:195], v[12:15]
	v_mfma_f32_16x16x32_bf16 v[12:15], v[108:111], v[196:199], v[12:15]
	v_mfma_f32_16x16x32_bf16 v[8:11], v[112:115], v[192:195], v[8:11]
	v_mfma_f32_16x16x32_bf16 v[8:11], v[116:119], v[196:199], v[8:11]
	v_mfma_f32_16x16x32_bf16 v[4:7], v[104:107], v[200:203], v[4:7]
	v_mfma_f32_16x16x32_bf16 v[4:7], v[108:111], v[212:215], v[4:7]
	v_mfma_f32_16x16x32_bf16 v[0:3], v[112:115], v[200:203], v[0:3]
	v_mfma_f32_16x16x32_bf16 v[0:3], v[116:119], v[212:215], v[0:3]
	s_setprio 0
	s_barrier
	s_add_i32 s57, 0, 0x18000
	s_add_i32 s62, 0, 0x1c000
	v_add_u32_e32 v100, s57, v205
	v_add_u32_e32 v116, s62, v205
	ds_read_b128 v[88:91], v100
	ds_read_b128 v[92:95], v100 offset:1024
	ds_read_b128 v[96:99], v100 offset:2048
	ds_read_b128 v[100:103], v100 offset:3072
	ds_read_b128 v[104:107], v116
	ds_read_b128 v[108:111], v116 offset:1024
	ds_read_b128 v[112:115], v116 offset:2048
	ds_read_b128 v[116:119], v116 offset:3072
	s_add_u32 s2, s2, 0x80000
	s_addc_u32 s3, s3, 0
	s_mov_b32 m0, s47
	v_lshl_add_u64 v[224:225], s[2:3], 0, v[172:173]
	ds_read_b128 v[160:163], v209 offset:32768
	ds_read_b128 v[164:167], v209 offset:33792
	ds_read_b128 v[168:171], v209 offset:34816
	ds_read_b128 v[188:191], v209 offset:35840
	ds_read_b128 v[192:195], v209 offset:36864
	ds_read_b128 v[196:199], v209 offset:37888
	ds_read_b128 v[200:203], v209 offset:38912
	ds_read_b128 v[212:215], v209 offset:39936
	global_load_lds_dwordx4 v[224:225], off
	v_lshl_add_u64 v[224:225], s[2:3], 0, v[176:177]
	s_mov_b32 m0, s48
	s_nop 0
	global_load_lds_dwordx4 v[224:225], off
	s_waitcnt vmcnt(8)
	s_waitcnt lgkmcnt(0)
	s_barrier
	s_setprio 1
	s_waitcnt lgkmcnt(0)
	v_mfma_f32_16x16x32_bf16 v[156:159], v[88:91], v[160:163], v[156:159]
	v_mfma_f32_16x16x32_bf16 v[156:159], v[92:95], v[164:167], v[156:159]
	v_mfma_f32_16x16x32_bf16 v[152:155], v[96:99], v[160:163], v[152:155]
	v_mfma_f32_16x16x32_bf16 v[152:155], v[100:103], v[164:167], v[152:155]
	v_mfma_f32_16x16x32_bf16 v[148:151], v[88:91], v[168:171], v[148:151]
	v_mfma_f32_16x16x32_bf16 v[148:151], v[92:95], v[188:191], v[148:151]
	v_mfma_f32_16x16x32_bf16 v[144:147], v[96:99], v[168:171], v[144:147]
	v_mfma_f32_16x16x32_bf16 v[144:147], v[100:103], v[188:191], v[144:147]
	v_mfma_f32_16x16x32_bf16 v[140:143], v[88:91], v[192:195], v[140:143]
	v_mfma_f32_16x16x32_bf16 v[140:143], v[92:95], v[196:199], v[140:143]
	v_mfma_f32_16x16x32_bf16 v[136:139], v[96:99], v[192:195], v[136:139]
	v_mfma_f32_16x16x32_bf16 v[136:139], v[100:103], v[196:199], v[136:139]
	v_mfma_f32_16x16x32_bf16 v[132:135], v[88:91], v[200:203], v[132:135]
	v_mfma_f32_16x16x32_bf16 v[132:135], v[92:95], v[212:215], v[132:135]
	v_mfma_f32_16x16x32_bf16 v[128:131], v[96:99], v[200:203], v[128:131]
	v_mfma_f32_16x16x32_bf16 v[128:131], v[100:103], v[212:215], v[128:131]
	s_setprio 0
	s_setprio 1
	v_mfma_f32_16x16x32_bf16 v[60:63], v[104:107], v[160:163], v[60:63]
	v_mfma_f32_16x16x32_bf16 v[60:63], v[108:111], v[164:167], v[60:63]
	v_mfma_f32_16x16x32_bf16 v[56:59], v[112:115], v[160:163], v[56:59]
	v_mfma_f32_16x16x32_bf16 v[56:59], v[116:119], v[164:167], v[56:59]
	v_mfma_f32_16x16x32_bf16 v[52:55], v[104:107], v[168:171], v[52:55]
	v_mfma_f32_16x16x32_bf16 v[52:55], v[108:111], v[188:191], v[52:55]
	v_mfma_f32_16x16x32_bf16 v[48:51], v[112:115], v[168:171], v[48:51]
	v_mfma_f32_16x16x32_bf16 v[48:51], v[116:119], v[188:191], v[48:51]
	v_mfma_f32_16x16x32_bf16 v[44:47], v[104:107], v[192:195], v[44:47]
	v_mfma_f32_16x16x32_bf16 v[44:47], v[108:111], v[196:199], v[44:47]
	v_mfma_f32_16x16x32_bf16 v[40:43], v[112:115], v[192:195], v[40:43]
	v_mfma_f32_16x16x32_bf16 v[40:43], v[116:119], v[196:199], v[40:43]
	v_mfma_f32_16x16x32_bf16 v[36:39], v[104:107], v[200:203], v[36:39]
	v_mfma_f32_16x16x32_bf16 v[36:39], v[108:111], v[212:215], v[36:39]
	v_mfma_f32_16x16x32_bf16 v[32:35], v[112:115], v[200:203], v[32:35]
	v_mfma_f32_16x16x32_bf16 v[32:35], v[116:119], v[212:215], v[32:35]
	s_setprio 0
	s_barrier
; #define PG8_STAGE(bufoff, gbase, voff) do { _Pragma("unroll") for (int _i = 0; _i < 2; ++_i) \
;         __builtin_amdgcn_global_load_lds((const unsigned*)((const char*)(gbase) + (voff)[_i]), (PG8_LAS unsigned*)(lds + (bufoff) + ldsw + _i * 8192), 16, 0, 0); } while (0)
; #define PG8_LDA(dst, b, h) do { _Pragma("unroll") for (int m = 0; m < 4; ++m) _Pragma("unroll") for (int k = 0; k < 2; ++k) dst[m][k] = *(const PG8_LAS bf16x8*)(lds + PG8_SA(b, h) + aoff + m * 2048 + k * 1024); } while (0)
; #define PG8_MMA(ai, bj, At, Bt) do { __builtin_amdgcn_s_setprio(1); _Pragma("unroll") for (int m = 0; m < 4; ++m) _Pragma("unroll") for (int n = 0; n < 2; ++n) _Pragma("unroll") for (int k = 0; k < 2; ++k) \
;         acc[ai][bj][m][n] = __builtin_amdgcn_mfma_f32_16x16x32_bf16(Bt[n][k], At[m][k], acc[ai][bj][m][n], 0, 0, 0); __builtin_amdgcn_s_setprio(0); } while (0)
; #define PG8_WAIT_V(n) asm volatile("s_waitcnt vmcnt(" #n ")" ::: "memory")
; #define PG8_WAIT_L(n) asm volatile("s_waitcnt lgkmcnt(" #n ")" ::: "memory")
; #define PG8_BAR __builtin_amdgcn_s_barrier()
; #define PG8_SCHED __builtin_amdgcn_sched_barrier(0)
; template <class Epi, class Sched, bool ALIGN_EPI = false, bool SP2 = false>
; __device__ __forceinline__ void gemm_phase(PG8_LAS unsigned char* lds, const Gemm g, const Sched& S, const Epi& E, const int tid) {
;     ...
;             PG8_LDA(At, 1, 1); PG8_STAGE(PG8_SB(1, 0), b3, voffB); PG8_STAGE(PG8_SB(1, 1), b3 + hstep, voffB); PG8_STAGE(PG8_SA(1, 0), a3, voffA);
;             PG8_WAIT_V(8); PG8_WAIT_L(0); PG8_BAR; PG8_MMA(1, 0, At, B0); PG8_MMA(1, 1, At, B1); PG8_BAR; PG8_SCHED;
;     ...
;         if constexpr (ALIGN_EPI) { if (wr == 0) PG8_BAR; }
	s_add_i32 s2, s57, s42
	v_lshl_add_u64 v[216:217], v[216:217], 0, s[30:31]
	s_mov_b32 m0, s2
	ds_read_b128 v[160:163], v209 offset:49152
	ds_read_b128 v[164:167], v209 offset:50176
	ds_read_b128 v[168:171], v209 offset:51200
	ds_read_b128 v[188:191], v209 offset:52224
	ds_read_b128 v[192:195], v209 offset:53248
	ds_read_b128 v[196:199], v209 offset:54272
	ds_read_b128 v[200:203], v209 offset:55296
	ds_read_b128 v[212:215], v209 offset:56320
	global_load_lds_dwordx4 v[216:217], off
	s_add_i32 m0, s2, 0x2000
	s_add_u32 s0, s0, 0x80080
	v_lshl_add_u64 v[216:217], v[218:219], 0, s[30:31]
	s_addc_u32 s1, s1, 0
	s_add_i32 s2, s62, s42
	global_load_lds_dwordx4 v[216:217], off
	v_lshl_add_u64 v[216:217], s[0:1], 0, v[174:175]
	s_mov_b32 m0, s2
	s_nop 0
	global_load_lds_dwordx4 v[216:217], off
	v_lshl_add_u64 v[216:217], s[0:1], 0, v[178:179]
	s_add_i32 m0, s2, 0x2000
	s_nop 0
	global_load_lds_dwordx4 v[216:217], off
	v_lshl_add_u64 v[216:217], v[220:221], 0, s[30:31]
	s_mov_b32 m0, s52
	s_nop 0
	global_load_lds_dwordx4 v[216:217], off
	v_lshl_add_u64 v[216:217], v[222:223], 0, s[30:31]
	s_mov_b32 m0, s53
	s_nop 0
	global_load_lds_dwordx4 v[216:217], off
	s_waitcnt vmcnt(8)
	s_waitcnt lgkmcnt(0)
	s_barrier
	s_setprio 1
	s_waitcnt lgkmcnt(0)
	v_mfma_f32_16x16x32_bf16 v[124:127], v[88:91], v[160:163], v[124:127]
	v_mfma_f32_16x16x32_bf16 v[124:127], v[92:95], v[164:167], v[124:127]
	v_mfma_f32_16x16x32_bf16 v[120:123], v[96:99], v[160:163], v[120:123]
	v_mfma_f32_16x16x32_bf16 v[120:123], v[100:103], v[164:167], v[120:123]
	v_mfma_f32_16x16x32_bf16 v[84:87], v[88:91], v[168:171], v[84:87]
	v_mfma_f32_16x16x32_bf16 v[84:87], v[92:95], v[188:191], v[84:87]
	v_mfma_f32_16x16x32_bf16 v[80:83], v[96:99], v[168:171], v[80:83]
	v_mfma_f32_16x16x32_bf16 v[80:83], v[100:103], v[188:191], v[80:83]
	v_mfma_f32_16x16x32_bf16 v[76:79], v[88:91], v[192:195], v[76:79]
	v_mfma_f32_16x16x32_bf16 v[76:79], v[92:95], v[196:199], v[76:79]
	v_mfma_f32_16x16x32_bf16 v[72:75], v[96:99], v[192:195], v[72:75]
	v_mfma_f32_16x16x32_bf16 v[72:75], v[100:103], v[196:199], v[72:75]
	v_mfma_f32_16x16x32_bf16 v[68:71], v[88:91], v[200:203], v[68:71]
	v_mfma_f32_16x16x32_bf16 v[68:71], v[92:95], v[212:215], v[68:71]
	v_mfma_f32_16x16x32_bf16 v[64:67], v[96:99], v[200:203], v[64:67]
	v_mfma_f32_16x16x32_bf16 v[64:67], v[100:103], v[212:215], v[64:67]
	s_setprio 0
	s_setprio 1
	v_mfma_f32_16x16x32_bf16 v[28:31], v[104:107], v[160:163], v[28:31]
	v_mfma_f32_16x16x32_bf16 v[28:31], v[108:111], v[164:167], v[28:31]
	v_mfma_f32_16x16x32_bf16 v[24:27], v[112:115], v[160:163], v[24:27]
	v_mfma_f32_16x16x32_bf16 v[24:27], v[116:119], v[164:167], v[24:27]
	v_mfma_f32_16x16x32_bf16 v[20:23], v[104:107], v[168:171], v[20:23]
	v_mfma_f32_16x16x32_bf16 v[20:23], v[108:111], v[188:191], v[20:23]
	v_mfma_f32_16x16x32_bf16 v[16:19], v[112:115], v[168:171], v[16:19]
	v_mfma_f32_16x16x32_bf16 v[16:19], v[116:119], v[188:191], v[16:19]
	v_mfma_f32_16x16x32_bf16 v[12:15], v[104:107], v[192:195], v[12:15]
	v_mfma_f32_16x16x32_bf16 v[12:15], v[108:111], v[196:199], v[12:15]
	v_mfma_f32_16x16x32_bf16 v[8:11], v[112:115], v[192:195], v[8:11]
	v_mfma_f32_16x16x32_bf16 v[8:11], v[116:119], v[196:199], v[8:11]
	v_mfma_f32_16x16x32_bf16 v[4:7], v[104:107], v[200:203], v[4:7]
	v_mfma_f32_16x16x32_bf16 v[4:7], v[108:111], v[212:215], v[4:7]
	v_mfma_f32_16x16x32_bf16 v[0:3], v[112:115], v[200:203], v[0:3]
	v_mfma_f32_16x16x32_bf16 v[0:3], v[116:119], v[212:215], v[0:3]
	s_setprio 0
	s_barrier
	s_add_i32 s55, s55, 2
	s_add_u32 s14, s14, 0x100
	s_addc_u32 s15, s15, 0
	s_add_u32 s16, s16, 0x100
	s_addc_u32 s17, s17, 0
	s_cmp_gt_u32 s55, 29
	s_cbranch_scc0 .LBB0_850
	s_and_b64 vcc, exec, s[34:35]
	s_cbranch_vccz .LBB0_853
	s_barrier

; #define PG8_STAGE(bufoff, gbase, voff) do { _Pragma("unroll") for (int _i = 0; _i < 2; ++_i) \
;         __builtin_amdgcn_global_load_lds((const unsigned*)((const char*)(gbase) + (voff)[_i]), (PG8_LAS unsigned*)(lds + (bufoff) + ldsw + _i * 8192), 16, 0, 0); } while (0)
; #define PG8_LDA(dst, b, h) do { _Pragma("unroll") for (int m = 0; m < 4; ++m) _Pragma("unroll") for (int k = 0; k < 2; ++k) dst[m][k] = *(const PG8_LAS bf16x8*)(lds + PG8_SA(b, h) + aoff + m * 2048 + k * 1024); } while (0)
; #define PG8_LDB(dst, b, h) do { _Pragma("unroll") for (int n = 0; n < 2; ++n) _Pragma("unroll") for (int k = 0; k < 2; ++k) dst[n][k] = *(const PG8_LAS bf16x8*)(lds + PG8_SB(b, h) + boff + n * 2048 + k * 1024); } while (0)
; #define PG8_MMA(ai, bj, At, Bt) do { __builtin_amdgcn_s_setprio(1); _Pragma("unroll") for (int m = 0; m < 4; ++m) _Pragma("unroll") for (int n = 0; n < 2; ++n) _Pragma("unroll") for (int k = 0; k < 2; ++k) \
;         acc[ai][bj][m][n] = __builtin_amdgcn_mfma_f32_16x16x32_bf16(Bt[n][k], At[m][k], acc[ai][bj][m][n], 0, 0, 0); __builtin_amdgcn_s_setprio(0); } while (0)
; #define PG8_WAIT_V(n) asm volatile("s_waitcnt vmcnt(" #n ")" ::: "memory")
; #define PG8_WAIT_L(n) asm volatile("s_waitcnt lgkmcnt(" #n ")" ::: "memory")
; #define PG8_BAR __builtin_amdgcn_s_barrier()
; #define PG8_SCHED __builtin_amdgcn_sched_barrier(0)
; template <class Epi, class Sched, bool ALIGN_EPI = false, bool SP2 = false>
; __device__ __forceinline__ void gemm_phase(PG8_LAS unsigned char* lds, const Gemm g, const Sched& S, const Epi& E, const int tid) {
;     ...
;             PG8_LDB(B0, 0, 0); PG8_LDB(B1, 0, 1); PG8_SCHED; PG8_LDA(At, 0, 0); PG8_STAGE(PG8_SA(1, 1), a1 + hstep, voffA);
;             PG8_WAIT_V(8); PG8_WAIT_L(0); PG8_BAR; PG8_MMA(0, 0, At, B0); PG8_MMA(0, 1, At, B1); PG8_BAR; PG8_SCHED;
;             PG8_LDA(At, 0, 1); PG8_STAGE(PG8_SB(0, 0), b2, voffB); PG8_STAGE(PG8_SB(0, 1), b2 + hstep, voffB); PG8_STAGE(PG8_SA(0, 0), a2, voffA);
;             PG8_WAIT_V(8); PG8_WAIT_L(0); PG8_BAR; PG8_MMA(1, 0, At, B0); PG8_MMA(1, 1, At, B1); PG8_BAR; PG8_SCHED;
.LBB0_954:
	ds_read_b128 v[152:155], v149
	ds_read_b128 v[156:159], v149 offset:1024
	ds_read_b128 v[160:163], v149 offset:2048
	ds_read_b128 v[164:167], v149 offset:3072
	ds_read_b128 v[168:171], v150
	ds_read_b128 v[172:175], v150 offset:1024
	ds_read_b128 v[176:179], v150 offset:2048
	ds_read_b128 v[180:183], v150 offset:3072
	s_add_u32 s28, s26, 0x100
	s_addc_u32 s29, s27, 0
	s_cmpk_eq_i32 s55, 0x54
	s_cselect_b32 s31, s5, s29
	s_cselect_b32 s30, s4, s28
	s_cselect_b32 s3, s23, s54
	s_cselect_b32 s2, s22, s53
	v_lshl_add_u64 v[144:145], s[26:27], 0, v[136:137]
	s_add_i32 m0, s35, 0xc000
	ds_read_b128 v[184:187], v151
	ds_read_b128 v[188:191], v151 offset:1024
	ds_read_b128 v[192:195], v151 offset:2048
	ds_read_b128 v[196:199], v151 offset:3072
	ds_read_b128 v[200:203], v151 offset:4096
	ds_read_b128 v[204:207], v151 offset:5120
	ds_read_b128 v[208:211], v151 offset:6144
	ds_read_b128 v[212:215], v151 offset:7168
	global_load_lds_dwordx4 v[144:145], off
	v_lshl_add_u64 v[144:145], s[26:27], 0, v[138:139]
	s_add_i32 m0, s35, 0xe000
	s_nop 0
	global_load_lds_dwordx4 v[144:145], off
	s_waitcnt vmcnt(8)
	s_waitcnt lgkmcnt(0)
	s_barrier
	s_setprio 1
	s_waitcnt lgkmcnt(0)
	v_mfma_f32_16x16x32_bf16 v[124:127], v[152:155], v[184:187], v[124:127]
	v_mfma_f32_16x16x32_bf16 v[124:127], v[156:159], v[188:191], v[124:127]
	v_mfma_f32_16x16x32_bf16 v[120:123], v[160:163], v[184:187], v[120:123]
	v_mfma_f32_16x16x32_bf16 v[120:123], v[164:167], v[188:191], v[120:123]
	v_mfma_f32_16x16x32_bf16 v[108:111], v[152:155], v[192:195], v[108:111]
	v_mfma_f32_16x16x32_bf16 v[108:111], v[156:159], v[196:199], v[108:111]
	v_mfma_f32_16x16x32_bf16 v[104:107], v[160:163], v[192:195], v[104:107]
	v_mfma_f32_16x16x32_bf16 v[104:107], v[164:167], v[196:199], v[104:107]
	v_mfma_f32_16x16x32_bf16 v[92:95], v[152:155], v[200:203], v[92:95]
	v_mfma_f32_16x16x32_bf16 v[92:95], v[156:159], v[204:207], v[92:95]
	v_mfma_f32_16x16x32_bf16 v[88:91], v[160:163], v[200:203], v[88:91]
	v_mfma_f32_16x16x32_bf16 v[88:91], v[164:167], v[204:207], v[88:91]
	v_mfma_f32_16x16x32_bf16 v[76:79], v[152:155], v[208:211], v[76:79]
	v_mfma_f32_16x16x32_bf16 v[76:79], v[156:159], v[212:215], v[76:79]
	v_mfma_f32_16x16x32_bf16 v[72:75], v[160:163], v[208:211], v[72:75]
	v_mfma_f32_16x16x32_bf16 v[72:75], v[164:167], v[212:215], v[72:75]
	s_setprio 0
	s_setprio 1
	v_mfma_f32_16x16x32_bf16 v[116:119], v[168:171], v[184:187], v[116:119]
	v_mfma_f32_16x16x32_bf16 v[116:119], v[172:175], v[188:191], v[116:119]
	v_mfma_f32_16x16x32_bf16 v[112:115], v[176:179], v[184:187], v[112:115]
	v_mfma_f32_16x16x32_bf16 v[112:115], v[180:183], v[188:191], v[112:115]
	v_mfma_f32_16x16x32_bf16 v[100:103], v[168:171], v[192:195], v[100:103]
	v_mfma_f32_16x16x32_bf16 v[100:103], v[172:175], v[196:199], v[100:103]
	v_mfma_f32_16x16x32_bf16 v[96:99], v[176:179], v[192:195], v[96:99]
	v_mfma_f32_16x16x32_bf16 v[96:99], v[180:183], v[196:199], v[96:99]
	v_mfma_f32_16x16x32_bf16 v[84:87], v[168:171], v[200:203], v[84:87]
	v_mfma_f32_16x16x32_bf16 v[84:87], v[172:175], v[204:207], v[84:87]
	v_mfma_f32_16x16x32_bf16 v[80:83], v[176:179], v[200:203], v[80:83]
	v_mfma_f32_16x16x32_bf16 v[80:83], v[180:183], v[204:207], v[80:83]
	v_mfma_f32_16x16x32_bf16 v[68:71], v[168:171], v[208:211], v[68:71]
	v_mfma_f32_16x16x32_bf16 v[68:71], v[172:175], v[212:215], v[68:71]
	v_mfma_f32_16x16x32_bf16 v[64:67], v[176:179], v[208:211], v[64:67]
	v_mfma_f32_16x16x32_bf16 v[64:67], v[180:183], v[212:215], v[64:67]
	s_setprio 0
	s_barrier
	s_add_i32 s26, s43, s34
	v_lshl_add_u64 v[144:145], s[2:3], 0, v[130:131]
	s_mov_b32 m0, s26
	ds_read_b128 v[184:187], v151 offset:16384
	ds_read_b128 v[188:191], v151 offset:17408
	ds_read_b128 v[192:195], v151 offset:18432
	ds_read_b128 v[196:199], v151 offset:19456
	ds_read_b128 v[200:203], v151 offset:20480
	ds_read_b128 v[204:207], v151 offset:21504
	ds_read_b128 v[208:211], v151 offset:22528
	ds_read_b128 v[212:215], v151 offset:23552
	global_load_lds_dwordx4 v[144:145], off
	s_add_i32 m0, s26, 0x2000
	s_add_u32 s26, s2, 0x160000
	v_lshl_add_u64 v[216:217], s[2:3], 0, v[134:135]
	s_addc_u32 s27, s3, 0
	s_add_i32 s56, s44, s34
	global_load_lds_dwordx4 v[216:217], off
	v_lshl_add_u64 v[218:219], s[26:27], 0, v[130:131]
	s_mov_b32 m0, s56
	v_lshl_add_u64 v[220:221], s[30:31], 0, v[132:133]
	global_load_lds_dwordx4 v[218:219], off
	v_lshl_add_u64 v[218:219], s[26:27], 0, v[134:135]
	s_add_i32 m0, s56, 0x2000
	s_nop 0
	global_load_lds_dwordx4 v[218:219], off
	v_lshl_add_u64 v[218:219], s[30:31], 0, v[128:129]
	s_mov_b32 m0, s35
	s_nop 0
	global_load_lds_dwordx4 v[218:219], off
	s_mov_b32 m0, s36
	s_nop 0
	global_load_lds_dwordx4 v[220:221], off
	s_waitcnt vmcnt(8)
	s_waitcnt lgkmcnt(0)
	s_barrier
; #define PG8_STAGE(bufoff, gbase, voff) do { _Pragma("unroll") for (int _i = 0; _i < 2; ++_i) \
;         __builtin_amdgcn_global_load_lds((const unsigned*)((const char*)(gbase) + (voff)[_i]), (PG8_LAS unsigned*)(lds + (bufoff) + ldsw + _i * 8192), 16, 0, 0); } while (0)
; #define PG8_LDA(dst, b, h) do { _Pragma("unroll") for (int m = 0; m < 4; ++m) _Pragma("unroll") for (int k = 0; k < 2; ++k) dst[m][k] = *(const PG8_LAS bf16x8*)(lds + PG8_SA(b, h) + aoff + m * 2048 + k * 1024); } while (0)
; #define PG8_LDB(dst, b, h) do { _Pragma("unroll") for (int n = 0; n < 2; ++n) _Pragma("unroll") for (int k = 0; k < 2; ++k) dst[n][k] = *(const PG8_LAS bf16x8*)(lds + PG8_SB(b, h) + boff + n * 2048 + k * 1024); } while (0)
; #define PG8_MMA(ai, bj, At, Bt) do { __builtin_amdgcn_s_setprio(1); _Pragma("unroll") for (int m = 0; m < 4; ++m) _Pragma("unroll") for (int n = 0; n < 2; ++n) _Pragma("unroll") for (int k = 0; k < 2; ++k) \
;         acc[ai][bj][m][n] = __builtin_amdgcn_mfma_f32_16x16x32_bf16(Bt[n][k], At[m][k], acc[ai][bj][m][n], 0, 0, 0); __builtin_amdgcn_s_setprio(0); } while (0)
; #define PG8_WAIT_V(n) asm volatile("s_waitcnt vmcnt(" #n ")" ::: "memory")
; #define PG8_WAIT_L(n) asm volatile("s_waitcnt lgkmcnt(" #n ")" ::: "memory")
; #define PG8_BAR __builtin_amdgcn_s_barrier()
; #define PG8_SCHED __builtin_amdgcn_sched_barrier(0)
; template <class Epi, class Sched, bool ALIGN_EPI = false, bool SP2 = false>
; __device__ __forceinline__ void gemm_phase(PG8_LAS unsigned char* lds, const Gemm g, const Sched& S, const Epi& E, const int tid) {
;     ...
;             PG8_WAIT_V(8); PG8_WAIT_L(0); PG8_BAR; PG8_MMA(1, 0, At, B0); PG8_MMA(1, 1, At, B1); PG8_BAR; PG8_SCHED;
;             PG8_LDB(B0, 1, 0); PG8_LDB(B1, 1, 1); PG8_SCHED; PG8_LDA(At, 1, 0); PG8_STAGE(PG8_SA(0, 1), a2 + hstep, voffA);
;             PG8_WAIT_V(8); PG8_WAIT_L(0); PG8_BAR; PG8_MMA(0, 0, At, B0); PG8_MMA(0, 1, At, B1); PG8_BAR; PG8_SCHED;
	s_setprio 1
	s_waitcnt lgkmcnt(0)
	v_mfma_f32_16x16x32_bf16 v[60:63], v[152:155], v[184:187], v[60:63]
	v_mfma_f32_16x16x32_bf16 v[60:63], v[156:159], v[188:191], v[60:63]
	v_mfma_f32_16x16x32_bf16 v[56:59], v[160:163], v[184:187], v[56:59]
	v_mfma_f32_16x16x32_bf16 v[56:59], v[164:167], v[188:191], v[56:59]
	v_mfma_f32_16x16x32_bf16 v[44:47], v[152:155], v[192:195], v[44:47]
	v_mfma_f32_16x16x32_bf16 v[44:47], v[156:159], v[196:199], v[44:47]
	v_mfma_f32_16x16x32_bf16 v[40:43], v[160:163], v[192:195], v[40:43]
	v_mfma_f32_16x16x32_bf16 v[40:43], v[164:167], v[196:199], v[40:43]
	v_mfma_f32_16x16x32_bf16 v[28:31], v[152:155], v[200:203], v[28:31]
	v_mfma_f32_16x16x32_bf16 v[28:31], v[156:159], v[204:207], v[28:31]
	v_mfma_f32_16x16x32_bf16 v[24:27], v[160:163], v[200:203], v[24:27]
	v_mfma_f32_16x16x32_bf16 v[24:27], v[164:167], v[204:207], v[24:27]
	v_mfma_f32_16x16x32_bf16 v[12:15], v[152:155], v[208:211], v[12:15]
	v_mfma_f32_16x16x32_bf16 v[12:15], v[156:159], v[212:215], v[12:15]
	v_mfma_f32_16x16x32_bf16 v[8:11], v[160:163], v[208:211], v[8:11]
	v_mfma_f32_16x16x32_bf16 v[8:11], v[164:167], v[212:215], v[8:11]
	s_setprio 0
	s_setprio 1
	v_mfma_f32_16x16x32_bf16 v[52:55], v[168:171], v[184:187], v[52:55]
	v_mfma_f32_16x16x32_bf16 v[52:55], v[172:175], v[188:191], v[52:55]
	v_mfma_f32_16x16x32_bf16 v[48:51], v[176:179], v[184:187], v[48:51]
	v_mfma_f32_16x16x32_bf16 v[48:51], v[180:183], v[188:191], v[48:51]
	v_mfma_f32_16x16x32_bf16 v[36:39], v[168:171], v[192:195], v[36:39]
	v_mfma_f32_16x16x32_bf16 v[36:39], v[172:175], v[196:199], v[36:39]
	v_mfma_f32_16x16x32_bf16 v[32:35], v[176:179], v[192:195], v[32:35]
	v_mfma_f32_16x16x32_bf16 v[32:35], v[180:183], v[196:199], v[32:35]
	v_mfma_f32_16x16x32_bf16 v[20:23], v[168:171], v[200:203], v[20:23]
	v_mfma_f32_16x16x32_bf16 v[20:23], v[172:175], v[204:207], v[20:23]
	v_mfma_f32_16x16x32_bf16 v[16:19], v[176:179], v[200:203], v[16:19]
	v_mfma_f32_16x16x32_bf16 v[16:19], v[180:183], v[204:207], v[16:19]
	v_mfma_f32_16x16x32_bf16 v[4:7], v[168:171], v[208:211], v[4:7]
	v_mfma_f32_16x16x32_bf16 v[4:7], v[172:175], v[212:215], v[4:7]
	v_mfma_f32_16x16x32_bf16 v[0:3], v[176:179], v[208:211], v[0:3]
	v_mfma_f32_16x16x32_bf16 v[0:3], v[180:183], v[212:215], v[0:3]
	s_setprio 0
	s_barrier
	s_add_i32 s56, 0, 0x18000
	s_add_i32 s57, 0, 0x1c000
	v_add_u32_e32 v164, s56, v147
	v_add_u32_e32 v180, s57, v147
	ds_read_b128 v[152:155], v164
	ds_read_b128 v[156:159], v164 offset:1024
	ds_read_b128 v[160:163], v164 offset:2048
	ds_read_b128 v[164:167], v164 offset:3072
	ds_read_b128 v[168:171], v180
	ds_read_b128 v[172:175], v180 offset:1024
	ds_read_b128 v[176:179], v180 offset:2048
	ds_read_b128 v[180:183], v180 offset:3072
	s_add_u32 s26, s30, 0x160000
	s_addc_u32 s27, s31, 0
	s_mov_b32 m0, s37
	v_lshl_add_u64 v[222:223], s[26:27], 0, v[128:129]
	ds_read_b128 v[184:187], v151 offset:32768
	ds_read_b128 v[188:191], v151 offset:33792
	ds_read_b128 v[192:195], v151 offset:34816
	ds_read_b128 v[196:199], v151 offset:35840
	ds_read_b128 v[200:203], v151 offset:36864
	ds_read_b128 v[204:207], v151 offset:37888
	ds_read_b128 v[208:211], v151 offset:38912
	ds_read_b128 v[212:215], v151 offset:39936
	global_load_lds_dwordx4 v[222:223], off
	v_lshl_add_u64 v[222:223], s[26:27], 0, v[132:133]
	s_mov_b32 m0, s38
	s_nop 0
	global_load_lds_dwordx4 v[222:223], off
	s_waitcnt vmcnt(8)
	s_waitcnt lgkmcnt(0)
	s_barrier
	s_setprio 1
	s_waitcnt lgkmcnt(0)
	v_mfma_f32_16x16x32_bf16 v[124:127], v[152:155], v[184:187], v[124:127]
	v_mfma_f32_16x16x32_bf16 v[124:127], v[156:159], v[188:191], v[124:127]
	v_mfma_f32_16x16x32_bf16 v[120:123], v[160:163], v[184:187], v[120:123]
	v_mfma_f32_16x16x32_bf16 v[120:123], v[164:167], v[188:191], v[120:123]
	v_mfma_f32_16x16x32_bf16 v[108:111], v[152:155], v[192:195], v[108:111]
	v_mfma_f32_16x16x32_bf16 v[108:111], v[156:159], v[196:199], v[108:111]
	v_mfma_f32_16x16x32_bf16 v[104:107], v[160:163], v[192:195], v[104:107]
	v_mfma_f32_16x16x32_bf16 v[104:107], v[164:167], v[196:199], v[104:107]
	v_mfma_f32_16x16x32_bf16 v[92:95], v[152:155], v[200:203], v[92:95]
	v_mfma_f32_16x16x32_bf16 v[92:95], v[156:159], v[204:207], v[92:95]
	v_mfma_f32_16x16x32_bf16 v[88:91], v[160:163], v[200:203], v[88:91]
	v_mfma_f32_16x16x32_bf16 v[88:91], v[164:167], v[204:207], v[88:91]
	v_mfma_f32_16x16x32_bf16 v[76:79], v[152:155], v[208:211], v[76:79]
	v_mfma_f32_16x16x32_bf16 v[76:79], v[156:159], v[212:215], v[76:79]
	v_mfma_f32_16x16x32_bf16 v[72:75], v[160:163], v[208:211], v[72:75]
	v_mfma_f32_16x16x32_bf16 v[72:75], v[164:167], v[212:215], v[72:75]
	s_setprio 0
	s_setprio 1
	v_mfma_f32_16x16x32_bf16 v[116:119], v[168:171], v[184:187], v[116:119]
	v_mfma_f32_16x16x32_bf16 v[116:119], v[172:175], v[188:191], v[116:119]
	v_mfma_f32_16x16x32_bf16 v[112:115], v[176:179], v[184:187], v[112:115]
	v_mfma_f32_16x16x32_bf16 v[112:115], v[180:183], v[188:191], v[112:115]
	v_mfma_f32_16x16x32_bf16 v[100:103], v[168:171], v[192:195], v[100:103]
	v_mfma_f32_16x16x32_bf16 v[100:103], v[172:175], v[196:199], v[100:103]
	v_mfma_f32_16x16x32_bf16 v[96:99], v[176:179], v[192:195], v[96:99]
	v_mfma_f32_16x16x32_bf16 v[96:99], v[180:183], v[196:199], v[96:99]
	v_mfma_f32_16x16x32_bf16 v[84:87], v[168:171], v[200:203], v[84:87]
	v_mfma_f32_16x16x32_bf16 v[84:87], v[172:175], v[204:207], v[84:87]
	v_mfma_f32_16x16x32_bf16 v[80:83], v[176:179], v[200:203], v[80:83]
	v_mfma_f32_16x16x32_bf16 v[80:83], v[180:183], v[204:207], v[80:83]
	v_mfma_f32_16x16x32_bf16 v[68:71], v[168:171], v[208:211], v[68:71]
	v_mfma_f32_16x16x32_bf16 v[68:71], v[172:175], v[212:215], v[68:71]
	v_mfma_f32_16x16x32_bf16 v[64:67], v[176:179], v[208:211], v[64:67]
	v_mfma_f32_16x16x32_bf16 v[64:67], v[180:183], v[212:215], v[64:67]
	s_setprio 0
	s_barrier
; #define PG8_STAGE(bufoff, gbase, voff) do { _Pragma("unroll") for (int _i = 0; _i < 2; ++_i) \
;         __builtin_amdgcn_global_load_lds((const unsigned*)((const char*)(gbase) + (voff)[_i]), (PG8_LAS unsigned*)(lds + (bufoff) + ldsw + _i * 8192), 16, 0, 0); } while (0)
; #define PG8_LDA(dst, b, h) do { _Pragma("unroll") for (int m = 0; m < 4; ++m) _Pragma("unroll") for (int k = 0; k < 2; ++k) dst[m][k] = *(const PG8_LAS bf16x8*)(lds + PG8_SA(b, h) + aoff + m * 2048 + k * 1024); } while (0)
; #define PG8_MMA(ai, bj, At, Bt) do { __builtin_amdgcn_s_setprio(1); _Pragma("unroll") for (int m = 0; m < 4; ++m) _Pragma("unroll") for (int n = 0; n < 2; ++n) _Pragma("unroll") for (int k = 0; k < 2; ++k) \
;         acc[ai][bj][m][n] = __builtin_amdgcn_mfma_f32_16x16x32_bf16(Bt[n][k], At[m][k], acc[ai][bj][m][n], 0, 0, 0); __builtin_amdgcn_s_setprio(0); } while (0)
; #define PG8_WAIT_V(n) asm volatile("s_waitcnt vmcnt(" #n ")" ::: "memory")
; #define PG8_WAIT_L(n) asm volatile("s_waitcnt lgkmcnt(" #n ")" ::: "memory")
; #define PG8_BAR __builtin_amdgcn_s_barrier()
; #define PG8_SCHED __builtin_amdgcn_sched_barrier(0)
; template <class Epi, class Sched, bool ALIGN_EPI = false, bool SP2 = false>
; __device__ __forceinline__ void gemm_phase(PG8_LAS unsigned char* lds, const Gemm g, const Sched& S, const Epi& E, const int tid) {
;     ...
;             PG8_LDA(At, 1, 1); PG8_STAGE(PG8_SB(1, 0), b3, voffB); PG8_STAGE(PG8_SB(1, 1), b3 + hstep, voffB); PG8_STAGE(PG8_SA(1, 0), a3, voffA);
;             PG8_WAIT_V(8); PG8_WAIT_L(0); PG8_BAR; PG8_MMA(1, 0, At, B0); PG8_MMA(1, 1, At, B1); PG8_BAR; PG8_SCHED;
;     ...
;         if constexpr (ALIGN_EPI) { if (wr == 0) PG8_BAR; }
	s_add_i32 s26, s56, s34
	v_lshl_add_u64 v[144:145], v[144:145], 0, s[12:13]
	s_mov_b32 m0, s26
	ds_read_b128 v[184:187], v151 offset:49152
	ds_read_b128 v[188:191], v151 offset:50176
	ds_read_b128 v[192:195], v151 offset:51200
	ds_read_b128 v[196:199], v151 offset:52224
	ds_read_b128 v[200:203], v151 offset:53248
	ds_read_b128 v[204:207], v151 offset:54272
	ds_read_b128 v[208:211], v151 offset:55296
	ds_read_b128 v[212:215], v151 offset:56320
	global_load_lds_dwordx4 v[144:145], off
	s_add_i32 m0, s26, 0x2000
	s_add_u32 s2, s2, 0x160080
	v_lshl_add_u64 v[144:145], v[216:217], 0, s[12:13]
	s_addc_u32 s3, s3, 0
	s_add_i32 s26, s57, s34
	global_load_lds_dwordx4 v[144:145], off
	v_lshl_add_u64 v[144:145], s[2:3], 0, v[130:131]
	s_mov_b32 m0, s26
	s_nop 0
	global_load_lds_dwordx4 v[144:145], off
	v_lshl_add_u64 v[144:145], s[2:3], 0, v[134:135]
	s_add_i32 m0, s26, 0x2000
	s_nop 0
	global_load_lds_dwordx4 v[144:145], off
	v_lshl_add_u64 v[144:145], v[218:219], 0, s[12:13]
	s_mov_b32 m0, s40
	s_nop 0
	global_load_lds_dwordx4 v[144:145], off
	v_lshl_add_u64 v[144:145], v[220:221], 0, s[12:13]
	s_mov_b32 m0, s41
	s_nop 0
	global_load_lds_dwordx4 v[144:145], off
	s_waitcnt vmcnt(8)
	s_waitcnt lgkmcnt(0)
	s_barrier
	s_setprio 1
	s_waitcnt lgkmcnt(0)
	v_mfma_f32_16x16x32_bf16 v[60:63], v[152:155], v[184:187], v[60:63]
	v_mfma_f32_16x16x32_bf16 v[60:63], v[156:159], v[188:191], v[60:63]
	v_mfma_f32_16x16x32_bf16 v[56:59], v[160:163], v[184:187], v[56:59]
	v_mfma_f32_16x16x32_bf16 v[56:59], v[164:167], v[188:191], v[56:59]
	v_mfma_f32_16x16x32_bf16 v[44:47], v[152:155], v[192:195], v[44:47]
	v_mfma_f32_16x16x32_bf16 v[44:47], v[156:159], v[196:199], v[44:47]
	v_mfma_f32_16x16x32_bf16 v[40:43], v[160:163], v[192:195], v[40:43]
	v_mfma_f32_16x16x32_bf16 v[40:43], v[164:167], v[196:199], v[40:43]
	v_mfma_f32_16x16x32_bf16 v[28:31], v[152:155], v[200:203], v[28:31]
	v_mfma_f32_16x16x32_bf16 v[28:31], v[156:159], v[204:207], v[28:31]
	v_mfma_f32_16x16x32_bf16 v[24:27], v[160:163], v[200:203], v[24:27]
	v_mfma_f32_16x16x32_bf16 v[24:27], v[164:167], v[204:207], v[24:27]
	v_mfma_f32_16x16x32_bf16 v[12:15], v[152:155], v[208:211], v[12:15]
	v_mfma_f32_16x16x32_bf16 v[12:15], v[156:159], v[212:215], v[12:15]
	v_mfma_f32_16x16x32_bf16 v[8:11], v[160:163], v[208:211], v[8:11]
	v_mfma_f32_16x16x32_bf16 v[8:11], v[164:167], v[212:215], v[8:11]
	s_setprio 0
	s_setprio 1
	v_mfma_f32_16x16x32_bf16 v[52:55], v[168:171], v[184:187], v[52:55]
	v_mfma_f32_16x16x32_bf16 v[52:55], v[172:175], v[188:191], v[52:55]
	v_mfma_f32_16x16x32_bf16 v[48:51], v[176:179], v[184:187], v[48:51]
	v_mfma_f32_16x16x32_bf16 v[48:51], v[180:183], v[188:191], v[48:51]
	v_mfma_f32_16x16x32_bf16 v[36:39], v[168:171], v[192:195], v[36:39]
	v_mfma_f32_16x16x32_bf16 v[36:39], v[172:175], v[196:199], v[36:39]
	v_mfma_f32_16x16x32_bf16 v[32:35], v[176:179], v[192:195], v[32:35]
	v_mfma_f32_16x16x32_bf16 v[32:35], v[180:183], v[196:199], v[32:35]
	v_mfma_f32_16x16x32_bf16 v[20:23], v[168:171], v[200:203], v[20:23]
	v_mfma_f32_16x16x32_bf16 v[20:23], v[172:175], v[204:207], v[20:23]
	v_mfma_f32_16x16x32_bf16 v[16:19], v[176:179], v[200:203], v[16:19]
	v_mfma_f32_16x16x32_bf16 v[16:19], v[180:183], v[204:207], v[16:19]
	v_mfma_f32_16x16x32_bf16 v[4:7], v[168:171], v[208:211], v[4:7]
	v_mfma_f32_16x16x32_bf16 v[4:7], v[172:175], v[212:215], v[4:7]
	v_mfma_f32_16x16x32_bf16 v[0:3], v[176:179], v[208:211], v[0:3]
	v_mfma_f32_16x16x32_bf16 v[0:3], v[180:183], v[212:215], v[0:3]
	s_setprio 0
	s_barrier
	s_add_i32 s55, s55, 2
	s_add_u32 s53, s53, 0x100
	s_addc_u32 s54, s54, 0
	s_cmpk_gt_u32 s55, 0x55
	s_mov_b64 s[26:27], s[28:29]
	s_cbranch_scc0 .LBB0_954
	s_and_b64 vcc, exec, s[14:15]
	s_cbranch_vccz .LBB0_957
	s_barrier
